# v086 + GEMM K-loops: counter/pointer/exit-test block moved in front of the loop-back barrier (back-edge rotation, 16 sites)
# speedup vs baseline: 1.0022x; 1.0007x over previous
; #define PG8_STAGE(bufoff, gbase, voff) do { _Pragma("unroll") for (int _i = 0; _i < 2; ++_i) \
;         __builtin_amdgcn_global_load_lds((const unsigned*)((const char*)(gbase) + (voff)[_i]), (PG8_LAS unsigned*)(lds + (bufoff) + ldsw + _i * 8192), 16, 0, 0); } while (0)
; #define PG8_LDA(dst, b, h) do { _Pragma("unroll") for (int m = 0; m < 4; ++m) _Pragma("unroll") for (int k = 0; k < 2; ++k) dst[m][k] = *(const PG8_LAS bf16x8*)(lds + PG8_SA(b, h) + aoff + m * 2048 + k * 1024); } while (0)
; #define PG8_LDB(dst, b, h) do { _Pragma("unroll") for (int n = 0; n < 2; ++n) _Pragma("unroll") for (int k = 0; k < 2; ++k) dst[n][k] = *(const PG8_LAS bf16x8*)(lds + PG8_SB(b, h) + boff + n * 2048 + k * 1024); } while (0)
; #define PG8_WAIT_V(n) asm volatile("s_waitcnt vmcnt(" #n ")" ::: "memory")
; #define PG8_WAIT_L(n) asm volatile("s_waitcnt lgkmcnt(" #n ")" ::: "memory")
; #define PG8_BAR __builtin_amdgcn_s_barrier()
; #define PG8_SCHED __builtin_amdgcn_sched_barrier(0)
; template <class Epi, class Sched, bool ALIGN_EPI = false, bool SP2 = false>
; __device__ __forceinline__ void gemm_phase(PG8_LAS unsigned char* lds, const Gemm g, const Sched& S, const Epi& E) {
;     ...
;         const bool has_next = S.next(ui + 1, nxt);
;         const char* nA = has_next ? (const char*)g.A + (size_t)nxt.pm * tstep : cA; const char* nB = has_next ? (const char*)g.Bt + (size_t)nxt.pn * tstep : cB;
;         for (int t = 0; t < nt; t += 2) {
;             const bool last = (t == nt - 2);
;             const char* a1 = cA + (size_t)(t + 1) * kstep;
;             const char* a2 = last ? nA : cA + (size_t)(t + 2) * kstep; const char* b2 = last ? nB : cB + (size_t)(t + 2) * kstep;
;             const char* a3 = a2 + kstep; const char* b3 = b2 + kstep;
;             if (last && has_next) S.a_ready(nxt);
;             if constexpr (SP2) {
;             PG8_LDB(B0, 0, 0); PG8_LDB(B1, 0, 1); PG8_SCHED; PG8_LDA(At, 0, 0); PG8_STAGE(PG8_SA(1, 1), a1 + hstep, voffA);
;             PG8_WAIT_V(8); PG8_WAIT_L(0); PG8_BAR; PG8_MMA(0, 0, At, B0); PG8_MMA(0, 1, At, B1); PG8_BAR; PG8_SCHED;
;             PG8_LDA(At, 0, 1); PG8_STAGE(PG8_SB(0, 0), b2, voffB); PG8_STAGE(PG8_SB(0, 1), b2 + hstep, voffB); PG8_STAGE(PG8_SA(0, 0), a2, voffA);
;             PG8_WAIT_V(8); PG8_WAIT_L(0); PG8_BAR; PG8_MMA(1, 0, At, B0); PG8_MMA(1, 1, At, B1); PG8_BAR; PG8_SCHED;
.LBB0_90:
	s_ashr_i32 s55, s54, 31
	s_lshl_b64 s[24:25], s[54:55], 19
	s_add_u32 s60, s70, s24
	s_addc_u32 s61, s71, s25
	s_and_b64 s[24:25], s[58:59], exec
	s_cselect_b32 s23, s61, s77
	s_cselect_b32 s24, s60, s76
	s_ashr_i32 s53, s52, 31
	s_lshl_b64 s[26:27], s[52:53], 19
	s_add_u32 s62, s83, s26
	s_addc_u32 s63, s84, s27
	s_and_b64 s[26:27], s[58:59], exec
	s_cselect_b32 s25, s63, s79
	s_cselect_b32 s26, s62, s78
	s_add_u32 s76, s76, 0x40080
	s_addc_u32 s77, s77, 0
	s_add_u32 s27, s78, 0x100
	s_addc_u32 s28, s79, 0
	s_mov_b32 s29, -2
	ds_read_b128 v[128:131], v183
	ds_read_b128 v[132:135], v183 offset:1024
	ds_read_b128 v[136:139], v183 offset:2048
	ds_read_b128 v[140:143], v183 offset:3072
	ds_read_b128 v[192:195], v185
	ds_read_b128 v[196:199], v185 offset:1024
	ds_read_b128 v[200:203], v185 offset:2048
	ds_read_b128 v[204:207], v185 offset:3072
	s_add_u32 s30, s76, 0xfffc0080
	s_addc_u32 s31, s77, -1
	s_cmp_eq_u32 s29, 12
	s_cselect_b32 s81, s23, s31
	s_cselect_b32 s80, s24, s30
	s_cselect_b32 s79, s25, s28
	s_cselect_b32 s78, s26, s27
	s_add_i32 m0, s87, 0xc000
	ds_read_b128 v[208:211], v186
	ds_read_b128 v[212:215], v186 offset:1024
	ds_read_b128 v[216:219], v186 offset:2048
	ds_read_b128 v[220:223], v186 offset:3072
	ds_read_b128 v[224:227], v186 offset:4096
	ds_read_b128 v[232:235], v186 offset:5120
	ds_read_b128 v[236:239], v186 offset:6144
	ds_read_b128 v[240:243], v186 offset:7168
	global_load_lds_dwordx4 v158, s[76:77]
	s_add_i32 m0, s87, 0xe000
	s_nop 0
	global_load_lds_dwordx4 v160, s[76:77]
	s_waitcnt vmcnt(8)
	s_waitcnt lgkmcnt(0)
	s_barrier
	s_setprio 1
	s_waitcnt lgkmcnt(0)
	v_mfma_f32_16x16x32_bf16 v[124:127], v[128:131], v[208:211], 0
	v_mfma_f32_16x16x32_bf16 v[120:123], v[136:139], v[208:211], 0
	v_mfma_f32_16x16x32_bf16 v[112:115], v[128:131], v[216:219], 0
	v_mfma_f32_16x16x32_bf16 v[108:111], v[136:139], v[216:219], 0
	v_mfma_f32_16x16x32_bf16 v[96:99], v[128:131], v[224:227], 0
	v_mfma_f32_16x16x32_bf16 v[88:91], v[136:139], v[224:227], 0
	v_mfma_f32_16x16x32_bf16 v[80:83], v[128:131], v[236:239], 0
	v_mfma_f32_16x16x32_bf16 v[72:75], v[136:139], v[236:239], 0
	v_mfma_f32_16x16x32_bf16 v[124:127], v[132:135], v[212:215], v[124:127]
	v_mfma_f32_16x16x32_bf16 v[120:123], v[140:143], v[212:215], v[120:123]
	v_mfma_f32_16x16x32_bf16 v[112:115], v[132:135], v[220:223], v[112:115]
	v_mfma_f32_16x16x32_bf16 v[108:111], v[140:143], v[220:223], v[108:111]
	v_mfma_f32_16x16x32_bf16 v[96:99], v[132:135], v[232:235], v[96:99]
	v_mfma_f32_16x16x32_bf16 v[88:91], v[140:143], v[232:235], v[88:91]
	v_mfma_f32_16x16x32_bf16 v[80:83], v[132:135], v[240:243], v[80:83]
	v_mfma_f32_16x16x32_bf16 v[72:75], v[140:143], v[240:243], v[72:75]
	s_setprio 0
	s_setprio 1
	v_mfma_f32_16x16x32_bf16 v[116:119], v[192:195], v[208:211], 0
	v_mfma_f32_16x16x32_bf16 v[104:107], v[200:203], v[208:211], 0
	v_mfma_f32_16x16x32_bf16 v[100:103], v[192:195], v[216:219], 0
	v_mfma_f32_16x16x32_bf16 v[92:95], v[200:203], v[216:219], 0
	v_mfma_f32_16x16x32_bf16 v[84:87], v[192:195], v[224:227], 0
	v_mfma_f32_16x16x32_bf16 v[76:79], v[200:203], v[224:227], 0
	v_mfma_f32_16x16x32_bf16 v[68:71], v[192:195], v[236:239], 0
	v_mfma_f32_16x16x32_bf16 v[64:67], v[200:203], v[236:239], 0
	v_mfma_f32_16x16x32_bf16 v[116:119], v[196:199], v[212:215], v[116:119]
	v_mfma_f32_16x16x32_bf16 v[104:107], v[204:207], v[212:215], v[104:107]
	v_mfma_f32_16x16x32_bf16 v[100:103], v[196:199], v[220:223], v[100:103]
	v_mfma_f32_16x16x32_bf16 v[92:95], v[204:207], v[220:223], v[92:95]
	v_mfma_f32_16x16x32_bf16 v[84:87], v[196:199], v[232:235], v[84:87]
	v_mfma_f32_16x16x32_bf16 v[76:79], v[204:207], v[232:235], v[76:79]
	v_mfma_f32_16x16x32_bf16 v[68:71], v[196:199], v[240:243], v[68:71]
	v_mfma_f32_16x16x32_bf16 v[64:67], v[204:207], v[240:243], v[64:67]
	s_setprio 0
	s_barrier
	s_add_i32 s30, s33, s86
	v_lshl_add_u64 v[172:173], s[78:79], 0, v[146:147]
	s_mov_b32 m0, s30
	ds_read_b128 v[208:211], v186 offset:16384
	ds_read_b128 v[212:215], v186 offset:17408
	ds_read_b128 v[216:219], v186 offset:18432
	ds_read_b128 v[220:223], v186 offset:19456
	ds_read_b128 v[224:227], v186 offset:20480
	ds_read_b128 v[232:235], v186 offset:21504
	ds_read_b128 v[236:239], v186 offset:22528
	ds_read_b128 v[240:243], v186 offset:23552
	global_load_lds_dwordx4 v[172:173], off
	s_add_i32 m0, s30, 0x2000
	s_add_u32 s30, s78, 0x40000
	v_lshl_add_u64 v[228:229], s[78:79], 0, v[150:151]
	s_addc_u32 s31, s79, 0
	s_add_i32 s53, s16, s86
	global_load_lds_dwordx4 v[228:229], off
	s_mov_b32 m0, s53
	v_lshl_add_u64 v[246:247], s[80:81], 0, v[148:149]
	global_load_lds_dwordx4 v146, s[30:31]
	s_add_i32 m0, s53, 0x2000
	s_nop 0
	global_load_lds_dwordx4 v150, s[30:31]
	v_lshl_add_u64 v[244:245], s[80:81], 0, v[144:145]
	s_mov_b32 m0, s87
	s_nop 0
	global_load_lds_dwordx4 v[244:245], off
	s_mov_b32 m0, s88
	s_nop 0
	global_load_lds_dwordx4 v[246:247], off
	s_waitcnt vmcnt(8)
	s_waitcnt lgkmcnt(0)
	s_barrier
; #define PG8_STAGE(bufoff, gbase, voff) do { _Pragma("unroll") for (int _i = 0; _i < 2; ++_i) \
;         __builtin_amdgcn_global_load_lds((const unsigned*)((const char*)(gbase) + (voff)[_i]), (PG8_LAS unsigned*)(lds + (bufoff) + ldsw + _i * 8192), 16, 0, 0); } while (0)
; #define PG8_LDA(dst, b, h) do { _Pragma("unroll") for (int m = 0; m < 4; ++m) _Pragma("unroll") for (int k = 0; k < 2; ++k) dst[m][k] = *(const PG8_LAS bf16x8*)(lds + PG8_SA(b, h) + aoff + m * 2048 + k * 1024); } while (0)
; #define PG8_LDB(dst, b, h) do { _Pragma("unroll") for (int n = 0; n < 2; ++n) _Pragma("unroll") for (int k = 0; k < 2; ++k) dst[n][k] = *(const PG8_LAS bf16x8*)(lds + PG8_SB(b, h) + boff + n * 2048 + k * 1024); } while (0)
; #define PG8_MMA(ai, bj, At, Bt) do { __builtin_amdgcn_s_setprio(1); _Pragma("unroll") for (int m = 0; m < 4; ++m) _Pragma("unroll") for (int n = 0; n < 2; ++n) _Pragma("unroll") for (int k = 0; k < 2; ++k) \
;         acc[ai][bj][m][n] = __builtin_amdgcn_mfma_f32_16x16x32_bf16(Bt[n][k], At[m][k], acc[ai][bj][m][n], 0, 0, 0); __builtin_amdgcn_s_setprio(0); } while (0)
; #define PG8_WAIT_V(n) asm volatile("s_waitcnt vmcnt(" #n ")" ::: "memory")
; #define PG8_WAIT_L(n) asm volatile("s_waitcnt lgkmcnt(" #n ")" ::: "memory")
; #define PG8_BAR __builtin_amdgcn_s_barrier()
; #define PG8_SCHED __builtin_amdgcn_sched_barrier(0)
; template <class Epi, class Sched, bool ALIGN_EPI = false, bool SP2 = false>
; __device__ __forceinline__ void gemm_phase(PG8_LAS unsigned char* lds, const Gemm g, const Sched& S, const Epi& E) {
;     ...
;             PG8_WAIT_V(8); PG8_WAIT_L(0); PG8_BAR; PG8_MMA(1, 0, At, B0); PG8_MMA(1, 1, At, B1); PG8_BAR; PG8_SCHED;
;             PG8_LDB(B0, 1, 0); PG8_LDB(B1, 1, 1); PG8_SCHED; PG8_LDA(At, 1, 0); PG8_STAGE(PG8_SA(0, 1), a2 + hstep, voffA);
;             PG8_WAIT_V(8); PG8_WAIT_L(0); PG8_BAR; PG8_MMA(0, 0, At, B0); PG8_MMA(0, 1, At, B1); PG8_BAR; PG8_SCHED;
	s_setprio 1
	s_waitcnt lgkmcnt(0)
	v_mfma_f32_16x16x32_bf16 v[60:63], v[128:131], v[208:211], 0
	v_mfma_f32_16x16x32_bf16 v[56:59], v[136:139], v[208:211], 0
	v_mfma_f32_16x16x32_bf16 v[48:51], v[128:131], v[216:219], 0
	v_mfma_f32_16x16x32_bf16 v[44:47], v[136:139], v[216:219], 0
	v_mfma_f32_16x16x32_bf16 v[32:35], v[128:131], v[224:227], 0
	v_mfma_f32_16x16x32_bf16 v[28:31], v[136:139], v[224:227], 0
	v_mfma_f32_16x16x32_bf16 v[16:19], v[128:131], v[236:239], 0
	v_mfma_f32_16x16x32_bf16 v[12:15], v[136:139], v[236:239], 0
	v_mfma_f32_16x16x32_bf16 v[60:63], v[132:135], v[212:215], v[60:63]
	v_mfma_f32_16x16x32_bf16 v[56:59], v[140:143], v[212:215], v[56:59]
	v_mfma_f32_16x16x32_bf16 v[48:51], v[132:135], v[220:223], v[48:51]
	v_mfma_f32_16x16x32_bf16 v[44:47], v[140:143], v[220:223], v[44:47]
	v_mfma_f32_16x16x32_bf16 v[32:35], v[132:135], v[232:235], v[32:35]
	v_mfma_f32_16x16x32_bf16 v[28:31], v[140:143], v[232:235], v[28:31]
	v_mfma_f32_16x16x32_bf16 v[16:19], v[132:135], v[240:243], v[16:19]
	v_mfma_f32_16x16x32_bf16 v[12:15], v[140:143], v[240:243], v[12:15]
	s_setprio 0
	s_setprio 1
	v_mfma_f32_16x16x32_bf16 v[52:55], v[192:195], v[208:211], 0
	v_mfma_f32_16x16x32_bf16 v[40:43], v[200:203], v[208:211], 0
	v_mfma_f32_16x16x32_bf16 v[36:39], v[192:195], v[216:219], 0
	v_mfma_f32_16x16x32_bf16 v[24:27], v[200:203], v[216:219], 0
	v_mfma_f32_16x16x32_bf16 v[20:23], v[192:195], v[224:227], 0
	v_mfma_f32_16x16x32_bf16 v[8:11], v[200:203], v[224:227], 0
	v_mfma_f32_16x16x32_bf16 v[4:7], v[192:195], v[236:239], 0
	v_mfma_f32_16x16x32_bf16 v[0:3], v[200:203], v[236:239], 0
	v_mfma_f32_16x16x32_bf16 v[52:55], v[196:199], v[212:215], v[52:55]
	v_mfma_f32_16x16x32_bf16 v[40:43], v[204:207], v[212:215], v[40:43]
	v_mfma_f32_16x16x32_bf16 v[36:39], v[196:199], v[220:223], v[36:39]
	v_mfma_f32_16x16x32_bf16 v[24:27], v[204:207], v[220:223], v[24:27]
	v_mfma_f32_16x16x32_bf16 v[20:23], v[196:199], v[232:235], v[20:23]
	v_mfma_f32_16x16x32_bf16 v[8:11], v[204:207], v[232:235], v[8:11]
	v_mfma_f32_16x16x32_bf16 v[4:7], v[196:199], v[240:243], v[4:7]
	v_mfma_f32_16x16x32_bf16 v[0:3], v[204:207], v[240:243], v[0:3]
	s_setprio 0
	s_barrier
	s_add_i32 s53, 0, 0x18000
	s_add_i32 s55, 0, 0x1c000
	v_add_u32_e32 v140, s53, v177
	v_add_u32_e32 v163, s55, v177
	ds_read_b128 v[128:131], v140
	ds_read_b128 v[132:135], v140 offset:1024
	ds_read_b128 v[136:139], v140 offset:2048
	ds_read_b128 v[140:143], v140 offset:3072
	ds_read_b128 v[192:195], v163
	ds_read_b128 v[196:199], v163 offset:1024
	ds_read_b128 v[200:203], v163 offset:2048
	ds_read_b128 v[204:207], v163 offset:3072
	s_add_u32 s30, s80, 0x40000
	s_addc_u32 s31, s81, 0
	s_mov_b32 m0, s89
	ds_read_b128 v[208:211], v186 offset:32768
	ds_read_b128 v[212:215], v186 offset:33792
	ds_read_b128 v[216:219], v186 offset:34816
	ds_read_b128 v[220:223], v186 offset:35840
	ds_read_b128 v[224:227], v186 offset:36864
	ds_read_b128 v[232:235], v186 offset:37888
	ds_read_b128 v[236:239], v186 offset:38912
	ds_read_b128 v[240:243], v186 offset:39936
	global_load_lds_dwordx4 v144, s[30:31]
	v_lshl_add_u64 v[248:249], s[30:31], 0, v[148:149]
	s_mov_b32 m0, s90
	s_nop 0
	global_load_lds_dwordx4 v[248:249], off
	s_waitcnt vmcnt(8)
	s_waitcnt lgkmcnt(0)
	s_barrier
	s_setprio 1
	s_waitcnt lgkmcnt(0)
	v_mfma_f32_16x16x32_bf16 v[124:127], v[128:131], v[208:211], v[124:127]
	v_mfma_f32_16x16x32_bf16 v[120:123], v[136:139], v[208:211], v[120:123]
	v_mfma_f32_16x16x32_bf16 v[112:115], v[128:131], v[216:219], v[112:115]
	v_mfma_f32_16x16x32_bf16 v[108:111], v[136:139], v[216:219], v[108:111]
	v_mfma_f32_16x16x32_bf16 v[96:99], v[128:131], v[224:227], v[96:99]
	v_mfma_f32_16x16x32_bf16 v[88:91], v[136:139], v[224:227], v[88:91]
	v_mfma_f32_16x16x32_bf16 v[80:83], v[128:131], v[236:239], v[80:83]
	v_mfma_f32_16x16x32_bf16 v[72:75], v[136:139], v[236:239], v[72:75]
	v_mfma_f32_16x16x32_bf16 v[124:127], v[132:135], v[212:215], v[124:127]
	v_mfma_f32_16x16x32_bf16 v[120:123], v[140:143], v[212:215], v[120:123]
	v_mfma_f32_16x16x32_bf16 v[112:115], v[132:135], v[220:223], v[112:115]
	v_mfma_f32_16x16x32_bf16 v[108:111], v[140:143], v[220:223], v[108:111]
	v_mfma_f32_16x16x32_bf16 v[96:99], v[132:135], v[232:235], v[96:99]
	v_mfma_f32_16x16x32_bf16 v[88:91], v[140:143], v[232:235], v[88:91]
	v_mfma_f32_16x16x32_bf16 v[80:83], v[132:135], v[240:243], v[80:83]
	v_mfma_f32_16x16x32_bf16 v[72:75], v[140:143], v[240:243], v[72:75]
	s_setprio 0
	s_setprio 1
	v_mfma_f32_16x16x32_bf16 v[116:119], v[192:195], v[208:211], v[116:119]
	v_mfma_f32_16x16x32_bf16 v[104:107], v[200:203], v[208:211], v[104:107]
	v_mfma_f32_16x16x32_bf16 v[100:103], v[192:195], v[216:219], v[100:103]
	v_mfma_f32_16x16x32_bf16 v[92:95], v[200:203], v[216:219], v[92:95]
	v_mfma_f32_16x16x32_bf16 v[84:87], v[192:195], v[224:227], v[84:87]
	v_mfma_f32_16x16x32_bf16 v[76:79], v[200:203], v[224:227], v[76:79]
	v_mfma_f32_16x16x32_bf16 v[68:71], v[192:195], v[236:239], v[68:71]
	v_mfma_f32_16x16x32_bf16 v[64:67], v[200:203], v[236:239], v[64:67]
	v_mfma_f32_16x16x32_bf16 v[116:119], v[196:199], v[212:215], v[116:119]
	v_mfma_f32_16x16x32_bf16 v[104:107], v[204:207], v[212:215], v[104:107]
	v_mfma_f32_16x16x32_bf16 v[100:103], v[196:199], v[220:223], v[100:103]
	v_mfma_f32_16x16x32_bf16 v[92:95], v[204:207], v[220:223], v[92:95]
	v_mfma_f32_16x16x32_bf16 v[84:87], v[196:199], v[232:235], v[84:87]
	v_mfma_f32_16x16x32_bf16 v[76:79], v[204:207], v[232:235], v[76:79]
	v_mfma_f32_16x16x32_bf16 v[68:71], v[196:199], v[240:243], v[68:71]
	v_mfma_f32_16x16x32_bf16 v[64:67], v[204:207], v[240:243], v[64:67]
	s_setprio 0
	s_barrier
; #define PG8_STAGE(bufoff, gbase, voff) do { _Pragma("unroll") for (int _i = 0; _i < 2; ++_i) \
;         __builtin_amdgcn_global_load_lds((const unsigned*)((const char*)(gbase) + (voff)[_i]), (PG8_LAS unsigned*)(lds + (bufoff) + ldsw + _i * 8192), 16, 0, 0); } while (0)
; #define PG8_LDA(dst, b, h) do { _Pragma("unroll") for (int m = 0; m < 4; ++m) _Pragma("unroll") for (int k = 0; k < 2; ++k) dst[m][k] = *(const PG8_LAS bf16x8*)(lds + PG8_SA(b, h) + aoff + m * 2048 + k * 1024); } while (0)
; #define PG8_LDB(dst, b, h) do { _Pragma("unroll") for (int n = 0; n < 2; ++n) _Pragma("unroll") for (int k = 0; k < 2; ++k) dst[n][k] = *(const PG8_LAS bf16x8*)(lds + PG8_SB(b, h) + boff + n * 2048 + k * 1024); } while (0)
; #define PG8_MMA(ai, bj, At, Bt) do { __builtin_amdgcn_s_setprio(1); _Pragma("unroll") for (int m = 0; m < 4; ++m) _Pragma("unroll") for (int n = 0; n < 2; ++n) _Pragma("unroll") for (int k = 0; k < 2; ++k) \
;         acc[ai][bj][m][n] = __builtin_amdgcn_mfma_f32_16x16x32_bf16(Bt[n][k], At[m][k], acc[ai][bj][m][n], 0, 0, 0); __builtin_amdgcn_s_setprio(0); } while (0)
; #define PG8_WAIT_V(n) asm volatile("s_waitcnt vmcnt(" #n ")" ::: "memory")
; #define PG8_WAIT_L(n) asm volatile("s_waitcnt lgkmcnt(" #n ")" ::: "memory")
; #define PG8_BAR __builtin_amdgcn_s_barrier()
; #define PG8_SCHED __builtin_amdgcn_sched_barrier(0)
; template <class Epi, class Sched, bool ALIGN_EPI = false, bool SP2 = false>
; __device__ __forceinline__ void gemm_phase(PG8_LAS unsigned char* lds, const Gemm g, const Sched& S, const Epi& E) {
;     ...
;             PG8_LDB(B0, 0, 0); PG8_LDB(B1, 0, 1); PG8_SCHED; PG8_LDA(At, 0, 0); PG8_STAGE(PG8_SA(1, 1), a1 + hstep, voffA);
;             PG8_WAIT_V(8); PG8_WAIT_L(0); PG8_BAR; PG8_MMA(0, 0, At, B0); PG8_MMA(0, 1, At, B1); PG8_BAR; PG8_SCHED;
;     ...
;             PG8_LDA(At, 1, 1); PG8_STAGE(PG8_SB(1, 0), b3, voffB); PG8_STAGE(PG8_SB(1, 1), b3 + hstep, voffB); PG8_STAGE(PG8_SA(1, 0), a3, voffA);
;             PG8_WAIT_V(8); PG8_WAIT_L(0); PG8_BAR; PG8_MMA(1, 0, At, B0); PG8_MMA(1, 1, At, B1); PG8_BAR; PG8_SCHED;
	s_add_i32 s30, s53, s86
	v_lshl_add_u64 v[172:173], v[172:173], 0, s[18:19]
	s_mov_b32 m0, s30
	ds_read_b128 v[208:211], v186 offset:49152
	ds_read_b128 v[212:215], v186 offset:50176
	ds_read_b128 v[216:219], v186 offset:51200
	ds_read_b128 v[220:223], v186 offset:52224
	ds_read_b128 v[224:227], v186 offset:53248
	ds_read_b128 v[232:235], v186 offset:54272
	ds_read_b128 v[236:239], v186 offset:55296
	ds_read_b128 v[240:243], v186 offset:56320
	global_load_lds_dwordx4 v[172:173], off
	s_add_i32 m0, s30, 0x2000
	s_add_u32 s30, s78, 0x40080
	v_lshl_add_u64 v[172:173], v[228:229], 0, s[18:19]
	s_addc_u32 s31, s79, 0
	s_add_i32 s53, s55, s86
	global_load_lds_dwordx4 v[172:173], off
	s_mov_b32 m0, s53
	s_nop 0
	global_load_lds_dwordx4 v146, s[30:31]
	s_add_i32 m0, s53, 0x2000
	s_nop 0
	global_load_lds_dwordx4 v150, s[30:31]
	v_lshl_add_u64 v[172:173], v[244:245], 0, s[18:19]
	s_mov_b32 m0, s93
	s_nop 0
	global_load_lds_dwordx4 v[172:173], off
	v_lshl_add_u64 v[172:173], v[246:247], 0, s[18:19]
	s_mov_b32 m0, s94
	s_nop 0
	global_load_lds_dwordx4 v[172:173], off
	s_waitcnt vmcnt(8)
	s_waitcnt lgkmcnt(0)
	s_barrier
	s_setprio 1
	s_waitcnt lgkmcnt(0)
	v_mfma_f32_16x16x32_bf16 v[60:63], v[128:131], v[208:211], v[60:63]
	v_mfma_f32_16x16x32_bf16 v[56:59], v[136:139], v[208:211], v[56:59]
	v_mfma_f32_16x16x32_bf16 v[48:51], v[128:131], v[216:219], v[48:51]
	v_mfma_f32_16x16x32_bf16 v[44:47], v[136:139], v[216:219], v[44:47]
	v_mfma_f32_16x16x32_bf16 v[32:35], v[128:131], v[224:227], v[32:35]
	v_mfma_f32_16x16x32_bf16 v[28:31], v[136:139], v[224:227], v[28:31]
	v_mfma_f32_16x16x32_bf16 v[16:19], v[128:131], v[236:239], v[16:19]
	v_mfma_f32_16x16x32_bf16 v[12:15], v[136:139], v[236:239], v[12:15]
	v_mfma_f32_16x16x32_bf16 v[60:63], v[132:135], v[212:215], v[60:63]
	v_mfma_f32_16x16x32_bf16 v[56:59], v[140:143], v[212:215], v[56:59]
	v_mfma_f32_16x16x32_bf16 v[48:51], v[132:135], v[220:223], v[48:51]
	v_mfma_f32_16x16x32_bf16 v[44:47], v[140:143], v[220:223], v[44:47]
	v_mfma_f32_16x16x32_bf16 v[32:35], v[132:135], v[232:235], v[32:35]
	v_mfma_f32_16x16x32_bf16 v[28:31], v[140:143], v[232:235], v[28:31]
	v_mfma_f32_16x16x32_bf16 v[16:19], v[132:135], v[240:243], v[16:19]
	v_mfma_f32_16x16x32_bf16 v[12:15], v[140:143], v[240:243], v[12:15]
	s_setprio 0
	s_setprio 1
	v_mfma_f32_16x16x32_bf16 v[52:55], v[192:195], v[208:211], v[52:55]
	v_mfma_f32_16x16x32_bf16 v[40:43], v[200:203], v[208:211], v[40:43]
	v_mfma_f32_16x16x32_bf16 v[36:39], v[192:195], v[216:219], v[36:39]
	v_mfma_f32_16x16x32_bf16 v[24:27], v[200:203], v[216:219], v[24:27]
	v_mfma_f32_16x16x32_bf16 v[20:23], v[192:195], v[224:227], v[20:23]
	v_mfma_f32_16x16x32_bf16 v[8:11], v[200:203], v[224:227], v[8:11]
	v_mfma_f32_16x16x32_bf16 v[4:7], v[192:195], v[236:239], v[4:7]
	v_mfma_f32_16x16x32_bf16 v[0:3], v[200:203], v[236:239], v[0:3]
	v_mfma_f32_16x16x32_bf16 v[52:55], v[196:199], v[212:215], v[52:55]
	v_mfma_f32_16x16x32_bf16 v[40:43], v[204:207], v[212:215], v[40:43]
	v_mfma_f32_16x16x32_bf16 v[36:39], v[196:199], v[220:223], v[36:39]
	v_mfma_f32_16x16x32_bf16 v[24:27], v[204:207], v[220:223], v[24:27]
	v_mfma_f32_16x16x32_bf16 v[20:23], v[196:199], v[232:235], v[20:23]
	v_mfma_f32_16x16x32_bf16 v[8:11], v[204:207], v[232:235], v[8:11]
	v_mfma_f32_16x16x32_bf16 v[4:7], v[196:199], v[240:243], v[4:7]
	v_mfma_f32_16x16x32_bf16 v[0:3], v[204:207], v[240:243], v[0:3]
	s_setprio 0
	s_add_i32 s29, s29, 2
	s_add_u32 s76, s76, 0x100
	s_addc_u32 s77, s77, 0
	s_add_u32 s27, s27, 0x100
	s_addc_u32 s28, s28, 0
	s_cmp_gt_u32 s29, 13
	s_barrier
.LBB0_91:
	ds_read_b128 v[128:131], v183
	ds_read_b128 v[132:135], v183 offset:1024
	ds_read_b128 v[136:139], v183 offset:2048
	ds_read_b128 v[140:143], v183 offset:3072
	ds_read_b128 v[192:195], v185
	ds_read_b128 v[196:199], v185 offset:1024
	ds_read_b128 v[200:203], v185 offset:2048
	ds_read_b128 v[204:207], v185 offset:3072
	s_add_u32 s30, s76, 0xfffc0080
	s_addc_u32 s31, s77, -1
	s_cmp_eq_u32 s29, 12
	s_cselect_b32 s81, s23, s31
	s_cselect_b32 s80, s24, s30
	s_cselect_b32 s79, s25, s28
	s_cselect_b32 s78, s26, s27
	s_add_i32 m0, s87, 0xc000
	ds_read_b128 v[208:211], v186
	ds_read_b128 v[212:215], v186 offset:1024
	ds_read_b128 v[216:219], v186 offset:2048
	ds_read_b128 v[220:223], v186 offset:3072
	ds_read_b128 v[224:227], v186 offset:4096
	ds_read_b128 v[232:235], v186 offset:5120
	ds_read_b128 v[236:239], v186 offset:6144
	ds_read_b128 v[240:243], v186 offset:7168
	global_load_lds_dwordx4 v158, s[76:77]
	s_add_i32 m0, s87, 0xe000
	s_nop 0
	global_load_lds_dwordx4 v160, s[76:77]
	s_waitcnt vmcnt(8)
	s_waitcnt lgkmcnt(0)
	s_barrier
; #define PG8_STAGE(bufoff, gbase, voff) do { _Pragma("unroll") for (int _i = 0; _i < 2; ++_i) \
;         __builtin_amdgcn_global_load_lds((const unsigned*)((const char*)(gbase) + (voff)[_i]), (PG8_LAS unsigned*)(lds + (bufoff) + ldsw + _i * 8192), 16, 0, 0); } while (0)
; #define PG8_LDA(dst, b, h) do { _Pragma("unroll") for (int m = 0; m < 4; ++m) _Pragma("unroll") for (int k = 0; k < 2; ++k) dst[m][k] = *(const PG8_LAS bf16x8*)(lds + PG8_SA(b, h) + aoff + m * 2048 + k * 1024); } while (0)
; #define PG8_LDB(dst, b, h) do { _Pragma("unroll") for (int n = 0; n < 2; ++n) _Pragma("unroll") for (int k = 0; k < 2; ++k) dst[n][k] = *(const PG8_LAS bf16x8*)(lds + PG8_SB(b, h) + boff + n * 2048 + k * 1024); } while (0)
; #define PG8_MMA(ai, bj, At, Bt) do { __builtin_amdgcn_s_setprio(1); _Pragma("unroll") for (int m = 0; m < 4; ++m) _Pragma("unroll") for (int n = 0; n < 2; ++n) _Pragma("unroll") for (int k = 0; k < 2; ++k) \
;         acc[ai][bj][m][n] = __builtin_amdgcn_mfma_f32_16x16x32_bf16(Bt[n][k], At[m][k], acc[ai][bj][m][n], 0, 0, 0); __builtin_amdgcn_s_setprio(0); } while (0)
; #define PG8_WAIT_V(n) asm volatile("s_waitcnt vmcnt(" #n ")" ::: "memory")
; #define PG8_WAIT_L(n) asm volatile("s_waitcnt lgkmcnt(" #n ")" ::: "memory")
; #define PG8_BAR __builtin_amdgcn_s_barrier()
; #define PG8_SCHED __builtin_amdgcn_sched_barrier(0)
; template <class Epi, class Sched, bool ALIGN_EPI = false, bool SP2 = false>
; __device__ __forceinline__ void gemm_phase(PG8_LAS unsigned char* lds, const Gemm g, const Sched& S, const Epi& E) {
;     ...
;             PG8_LDB(B0, 0, 0); PG8_LDB(B1, 0, 1); PG8_SCHED; PG8_LDA(At, 0, 0); PG8_STAGE(PG8_SA(1, 1), a1 + hstep, voffA);
;             PG8_WAIT_V(8); PG8_WAIT_L(0); PG8_BAR; PG8_MMA(0, 0, At, B0); PG8_MMA(0, 1, At, B1); PG8_BAR; PG8_SCHED;
;             PG8_LDA(At, 0, 1); PG8_STAGE(PG8_SB(0, 0), b2, voffB); PG8_STAGE(PG8_SB(0, 1), b2 + hstep, voffB); PG8_STAGE(PG8_SA(0, 0), a2, voffA);
;             PG8_WAIT_V(8); PG8_WAIT_L(0); PG8_BAR; PG8_MMA(1, 0, At, B0); PG8_MMA(1, 1, At, B1); PG8_BAR; PG8_SCHED;
	s_setprio 1
	s_waitcnt lgkmcnt(0)
	v_mfma_f32_16x16x32_bf16 v[124:127], v[128:131], v[208:211], v[124:127]
	v_mfma_f32_16x16x32_bf16 v[120:123], v[136:139], v[208:211], v[120:123]
	v_mfma_f32_16x16x32_bf16 v[112:115], v[128:131], v[216:219], v[112:115]
	v_mfma_f32_16x16x32_bf16 v[108:111], v[136:139], v[216:219], v[108:111]
	v_mfma_f32_16x16x32_bf16 v[96:99], v[128:131], v[224:227], v[96:99]
	v_mfma_f32_16x16x32_bf16 v[88:91], v[136:139], v[224:227], v[88:91]
	v_mfma_f32_16x16x32_bf16 v[80:83], v[128:131], v[236:239], v[80:83]
	v_mfma_f32_16x16x32_bf16 v[72:75], v[136:139], v[236:239], v[72:75]
	v_mfma_f32_16x16x32_bf16 v[124:127], v[132:135], v[212:215], v[124:127]
	v_mfma_f32_16x16x32_bf16 v[120:123], v[140:143], v[212:215], v[120:123]
	v_mfma_f32_16x16x32_bf16 v[112:115], v[132:135], v[220:223], v[112:115]
	v_mfma_f32_16x16x32_bf16 v[108:111], v[140:143], v[220:223], v[108:111]
	v_mfma_f32_16x16x32_bf16 v[96:99], v[132:135], v[232:235], v[96:99]
	v_mfma_f32_16x16x32_bf16 v[88:91], v[140:143], v[232:235], v[88:91]
	v_mfma_f32_16x16x32_bf16 v[80:83], v[132:135], v[240:243], v[80:83]
	v_mfma_f32_16x16x32_bf16 v[72:75], v[140:143], v[240:243], v[72:75]
	s_setprio 0
	s_setprio 1
	v_mfma_f32_16x16x32_bf16 v[116:119], v[192:195], v[208:211], v[116:119]
	v_mfma_f32_16x16x32_bf16 v[104:107], v[200:203], v[208:211], v[104:107]
	v_mfma_f32_16x16x32_bf16 v[100:103], v[192:195], v[216:219], v[100:103]
	v_mfma_f32_16x16x32_bf16 v[92:95], v[200:203], v[216:219], v[92:95]
	v_mfma_f32_16x16x32_bf16 v[84:87], v[192:195], v[224:227], v[84:87]
	v_mfma_f32_16x16x32_bf16 v[76:79], v[200:203], v[224:227], v[76:79]
	v_mfma_f32_16x16x32_bf16 v[68:71], v[192:195], v[236:239], v[68:71]
	v_mfma_f32_16x16x32_bf16 v[64:67], v[200:203], v[236:239], v[64:67]
	v_mfma_f32_16x16x32_bf16 v[116:119], v[196:199], v[212:215], v[116:119]
	v_mfma_f32_16x16x32_bf16 v[104:107], v[204:207], v[212:215], v[104:107]
	v_mfma_f32_16x16x32_bf16 v[100:103], v[196:199], v[220:223], v[100:103]
	v_mfma_f32_16x16x32_bf16 v[92:95], v[204:207], v[220:223], v[92:95]
	v_mfma_f32_16x16x32_bf16 v[84:87], v[196:199], v[232:235], v[84:87]
	v_mfma_f32_16x16x32_bf16 v[76:79], v[204:207], v[232:235], v[76:79]
	v_mfma_f32_16x16x32_bf16 v[68:71], v[196:199], v[240:243], v[68:71]
	v_mfma_f32_16x16x32_bf16 v[64:67], v[204:207], v[240:243], v[64:67]
	s_setprio 0
	s_barrier
	s_add_i32 s30, s33, s86
	v_lshl_add_u64 v[172:173], s[78:79], 0, v[146:147]
	s_mov_b32 m0, s30
	ds_read_b128 v[208:211], v186 offset:16384
	ds_read_b128 v[212:215], v186 offset:17408
	ds_read_b128 v[216:219], v186 offset:18432
	ds_read_b128 v[220:223], v186 offset:19456
	ds_read_b128 v[224:227], v186 offset:20480
	ds_read_b128 v[232:235], v186 offset:21504
	ds_read_b128 v[236:239], v186 offset:22528
	ds_read_b128 v[240:243], v186 offset:23552
	global_load_lds_dwordx4 v[172:173], off
	s_add_i32 m0, s30, 0x2000
	s_add_u32 s30, s78, 0x40000
	v_lshl_add_u64 v[228:229], s[78:79], 0, v[150:151]
	s_addc_u32 s31, s79, 0
	s_add_i32 s53, s16, s86
	global_load_lds_dwordx4 v[228:229], off
	s_mov_b32 m0, s53
	v_lshl_add_u64 v[246:247], s[80:81], 0, v[148:149]
	global_load_lds_dwordx4 v146, s[30:31]
	s_add_i32 m0, s53, 0x2000
	s_nop 0
	global_load_lds_dwordx4 v150, s[30:31]
	v_lshl_add_u64 v[244:245], s[80:81], 0, v[144:145]
	s_mov_b32 m0, s87
	s_nop 0
	global_load_lds_dwordx4 v[244:245], off
	s_mov_b32 m0, s88
	s_nop 0
	global_load_lds_dwordx4 v[246:247], off
	s_waitcnt vmcnt(8)
	s_waitcnt lgkmcnt(0)
	s_barrier
	s_setprio 1
	s_waitcnt lgkmcnt(0)
	v_mfma_f32_16x16x32_bf16 v[60:63], v[128:131], v[208:211], v[60:63]
	v_mfma_f32_16x16x32_bf16 v[56:59], v[136:139], v[208:211], v[56:59]
	v_mfma_f32_16x16x32_bf16 v[48:51], v[128:131], v[216:219], v[48:51]
	v_mfma_f32_16x16x32_bf16 v[44:47], v[136:139], v[216:219], v[44:47]
	v_mfma_f32_16x16x32_bf16 v[32:35], v[128:131], v[224:227], v[32:35]
	v_mfma_f32_16x16x32_bf16 v[28:31], v[136:139], v[224:227], v[28:31]
	v_mfma_f32_16x16x32_bf16 v[16:19], v[128:131], v[236:239], v[16:19]
	v_mfma_f32_16x16x32_bf16 v[12:15], v[136:139], v[236:239], v[12:15]
	v_mfma_f32_16x16x32_bf16 v[60:63], v[132:135], v[212:215], v[60:63]
	v_mfma_f32_16x16x32_bf16 v[56:59], v[140:143], v[212:215], v[56:59]
	v_mfma_f32_16x16x32_bf16 v[48:51], v[132:135], v[220:223], v[48:51]
	v_mfma_f32_16x16x32_bf16 v[44:47], v[140:143], v[220:223], v[44:47]
	v_mfma_f32_16x16x32_bf16 v[32:35], v[132:135], v[232:235], v[32:35]
	v_mfma_f32_16x16x32_bf16 v[28:31], v[140:143], v[232:235], v[28:31]
	v_mfma_f32_16x16x32_bf16 v[16:19], v[132:135], v[240:243], v[16:19]
	v_mfma_f32_16x16x32_bf16 v[12:15], v[140:143], v[240:243], v[12:15]
	s_setprio 0
	s_setprio 1
	v_mfma_f32_16x16x32_bf16 v[52:55], v[192:195], v[208:211], v[52:55]
	v_mfma_f32_16x16x32_bf16 v[40:43], v[200:203], v[208:211], v[40:43]
	v_mfma_f32_16x16x32_bf16 v[36:39], v[192:195], v[216:219], v[36:39]
	v_mfma_f32_16x16x32_bf16 v[24:27], v[200:203], v[216:219], v[24:27]
	v_mfma_f32_16x16x32_bf16 v[20:23], v[192:195], v[224:227], v[20:23]
	v_mfma_f32_16x16x32_bf16 v[8:11], v[200:203], v[224:227], v[8:11]
	v_mfma_f32_16x16x32_bf16 v[4:7], v[192:195], v[236:239], v[4:7]
	v_mfma_f32_16x16x32_bf16 v[0:3], v[200:203], v[236:239], v[0:3]
	v_mfma_f32_16x16x32_bf16 v[52:55], v[196:199], v[212:215], v[52:55]
	v_mfma_f32_16x16x32_bf16 v[40:43], v[204:207], v[212:215], v[40:43]
	v_mfma_f32_16x16x32_bf16 v[36:39], v[196:199], v[220:223], v[36:39]
	v_mfma_f32_16x16x32_bf16 v[24:27], v[204:207], v[220:223], v[24:27]
	v_mfma_f32_16x16x32_bf16 v[20:23], v[196:199], v[232:235], v[20:23]
	v_mfma_f32_16x16x32_bf16 v[8:11], v[204:207], v[232:235], v[8:11]
	v_mfma_f32_16x16x32_bf16 v[4:7], v[196:199], v[240:243], v[4:7]
	v_mfma_f32_16x16x32_bf16 v[0:3], v[204:207], v[240:243], v[0:3]
	s_setprio 0
	s_barrier
; #define PG8_STAGE(bufoff, gbase, voff) do { _Pragma("unroll") for (int _i = 0; _i < 2; ++_i) \
;         __builtin_amdgcn_global_load_lds((const unsigned*)((const char*)(gbase) + (voff)[_i]), (PG8_LAS unsigned*)(lds + (bufoff) + ldsw + _i * 8192), 16, 0, 0); } while (0)
; #define PG8_LDA(dst, b, h) do { _Pragma("unroll") for (int m = 0; m < 4; ++m) _Pragma("unroll") for (int k = 0; k < 2; ++k) dst[m][k] = *(const PG8_LAS bf16x8*)(lds + PG8_SA(b, h) + aoff + m * 2048 + k * 1024); } while (0)
; #define PG8_LDB(dst, b, h) do { _Pragma("unroll") for (int n = 0; n < 2; ++n) _Pragma("unroll") for (int k = 0; k < 2; ++k) dst[n][k] = *(const PG8_LAS bf16x8*)(lds + PG8_SB(b, h) + boff + n * 2048 + k * 1024); } while (0)
; #define PG8_MMA(ai, bj, At, Bt) do { __builtin_amdgcn_s_setprio(1); _Pragma("unroll") for (int m = 0; m < 4; ++m) _Pragma("unroll") for (int n = 0; n < 2; ++n) _Pragma("unroll") for (int k = 0; k < 2; ++k) \
;         acc[ai][bj][m][n] = __builtin_amdgcn_mfma_f32_16x16x32_bf16(Bt[n][k], At[m][k], acc[ai][bj][m][n], 0, 0, 0); __builtin_amdgcn_s_setprio(0); } while (0)
; #define PG8_WAIT_V(n) asm volatile("s_waitcnt vmcnt(" #n ")" ::: "memory")
; #define PG8_WAIT_L(n) asm volatile("s_waitcnt lgkmcnt(" #n ")" ::: "memory")
; #define PG8_BAR __builtin_amdgcn_s_barrier()
; #define PG8_SCHED __builtin_amdgcn_sched_barrier(0)
; template <class Epi, class Sched, bool ALIGN_EPI = false, bool SP2 = false>
; __device__ __forceinline__ void gemm_phase(PG8_LAS unsigned char* lds, const Gemm g, const Sched& S, const Epi& E) {
;     ...
;             PG8_LDB(B0, 1, 0); PG8_LDB(B1, 1, 1); PG8_SCHED; PG8_LDA(At, 1, 0); PG8_STAGE(PG8_SA(0, 1), a2 + hstep, voffA);
;             PG8_WAIT_V(8); PG8_WAIT_L(0); PG8_BAR; PG8_MMA(0, 0, At, B0); PG8_MMA(0, 1, At, B1); PG8_BAR; PG8_SCHED;
	s_add_i32 s53, 0, 0x18000
	s_add_i32 s55, 0, 0x1c000
	v_add_u32_e32 v140, s53, v177
	v_add_u32_e32 v163, s55, v177
	ds_read_b128 v[128:131], v140
	ds_read_b128 v[132:135], v140 offset:1024
	ds_read_b128 v[136:139], v140 offset:2048
	ds_read_b128 v[140:143], v140 offset:3072
	ds_read_b128 v[192:195], v163
	ds_read_b128 v[196:199], v163 offset:1024
	ds_read_b128 v[200:203], v163 offset:2048
	ds_read_b128 v[204:207], v163 offset:3072
	s_add_u32 s30, s80, 0x40000
	s_addc_u32 s31, s81, 0
	s_mov_b32 m0, s89
	ds_read_b128 v[208:211], v186 offset:32768
	ds_read_b128 v[212:215], v186 offset:33792
	ds_read_b128 v[216:219], v186 offset:34816
	ds_read_b128 v[220:223], v186 offset:35840
	ds_read_b128 v[224:227], v186 offset:36864
	ds_read_b128 v[232:235], v186 offset:37888
	ds_read_b128 v[236:239], v186 offset:38912
	ds_read_b128 v[240:243], v186 offset:39936
	global_load_lds_dwordx4 v144, s[30:31]
	v_lshl_add_u64 v[248:249], s[30:31], 0, v[148:149]
	s_mov_b32 m0, s90
	s_nop 0
	global_load_lds_dwordx4 v[248:249], off
	s_waitcnt vmcnt(8)
	s_waitcnt lgkmcnt(0)
	s_barrier
	s_setprio 1
	s_waitcnt lgkmcnt(0)
	v_mfma_f32_16x16x32_bf16 v[124:127], v[128:131], v[208:211], v[124:127]
	v_mfma_f32_16x16x32_bf16 v[120:123], v[136:139], v[208:211], v[120:123]
	v_mfma_f32_16x16x32_bf16 v[112:115], v[128:131], v[216:219], v[112:115]
	v_mfma_f32_16x16x32_bf16 v[108:111], v[136:139], v[216:219], v[108:111]
	v_mfma_f32_16x16x32_bf16 v[96:99], v[128:131], v[224:227], v[96:99]
	v_mfma_f32_16x16x32_bf16 v[88:91], v[136:139], v[224:227], v[88:91]
	v_mfma_f32_16x16x32_bf16 v[80:83], v[128:131], v[236:239], v[80:83]
	v_mfma_f32_16x16x32_bf16 v[72:75], v[136:139], v[236:239], v[72:75]
	v_mfma_f32_16x16x32_bf16 v[124:127], v[132:135], v[212:215], v[124:127]
	v_mfma_f32_16x16x32_bf16 v[120:123], v[140:143], v[212:215], v[120:123]
	v_mfma_f32_16x16x32_bf16 v[112:115], v[132:135], v[220:223], v[112:115]
	v_mfma_f32_16x16x32_bf16 v[108:111], v[140:143], v[220:223], v[108:111]
	v_mfma_f32_16x16x32_bf16 v[96:99], v[132:135], v[232:235], v[96:99]
	v_mfma_f32_16x16x32_bf16 v[88:91], v[140:143], v[232:235], v[88:91]
	v_mfma_f32_16x16x32_bf16 v[80:83], v[132:135], v[240:243], v[80:83]
	v_mfma_f32_16x16x32_bf16 v[72:75], v[140:143], v[240:243], v[72:75]
	s_setprio 0
	s_setprio 1
	v_mfma_f32_16x16x32_bf16 v[116:119], v[192:195], v[208:211], v[116:119]
	v_mfma_f32_16x16x32_bf16 v[104:107], v[200:203], v[208:211], v[104:107]
	v_mfma_f32_16x16x32_bf16 v[100:103], v[192:195], v[216:219], v[100:103]
	v_mfma_f32_16x16x32_bf16 v[92:95], v[200:203], v[216:219], v[92:95]
	v_mfma_f32_16x16x32_bf16 v[84:87], v[192:195], v[224:227], v[84:87]
	v_mfma_f32_16x16x32_bf16 v[76:79], v[200:203], v[224:227], v[76:79]
	v_mfma_f32_16x16x32_bf16 v[68:71], v[192:195], v[236:239], v[68:71]
	v_mfma_f32_16x16x32_bf16 v[64:67], v[200:203], v[236:239], v[64:67]
	v_mfma_f32_16x16x32_bf16 v[116:119], v[196:199], v[212:215], v[116:119]
	v_mfma_f32_16x16x32_bf16 v[104:107], v[204:207], v[212:215], v[104:107]
	v_mfma_f32_16x16x32_bf16 v[100:103], v[196:199], v[220:223], v[100:103]
	v_mfma_f32_16x16x32_bf16 v[92:95], v[204:207], v[220:223], v[92:95]
	v_mfma_f32_16x16x32_bf16 v[84:87], v[196:199], v[232:235], v[84:87]
	v_mfma_f32_16x16x32_bf16 v[76:79], v[204:207], v[232:235], v[76:79]
	v_mfma_f32_16x16x32_bf16 v[68:71], v[196:199], v[240:243], v[68:71]
	v_mfma_f32_16x16x32_bf16 v[64:67], v[204:207], v[240:243], v[64:67]
	s_setprio 0
	s_barrier
; #define PG8_STAGE(bufoff, gbase, voff) do { _Pragma("unroll") for (int _i = 0; _i < 2; ++_i) \
;         __builtin_amdgcn_global_load_lds((const unsigned*)((const char*)(gbase) + (voff)[_i]), (PG8_LAS unsigned*)(lds + (bufoff) + ldsw + _i * 8192), 16, 0, 0); } while (0)
; #define PG8_LDA(dst, b, h) do { _Pragma("unroll") for (int m = 0; m < 4; ++m) _Pragma("unroll") for (int k = 0; k < 2; ++k) dst[m][k] = *(const PG8_LAS bf16x8*)(lds + PG8_SA(b, h) + aoff + m * 2048 + k * 1024); } while (0)
; #define PG8_MMA(ai, bj, At, Bt) do { __builtin_amdgcn_s_setprio(1); _Pragma("unroll") for (int m = 0; m < 4; ++m) _Pragma("unroll") for (int n = 0; n < 2; ++n) _Pragma("unroll") for (int k = 0; k < 2; ++k) \
;         acc[ai][bj][m][n] = __builtin_amdgcn_mfma_f32_16x16x32_bf16(Bt[n][k], At[m][k], acc[ai][bj][m][n], 0, 0, 0); __builtin_amdgcn_s_setprio(0); } while (0)
; #define PG8_WAIT_V(n) asm volatile("s_waitcnt vmcnt(" #n ")" ::: "memory")
; #define PG8_WAIT_L(n) asm volatile("s_waitcnt lgkmcnt(" #n ")" ::: "memory")
; #define PG8_BAR __builtin_amdgcn_s_barrier()
; #define PG8_SCHED __builtin_amdgcn_sched_barrier(0)
; template <class Epi, class Sched, bool ALIGN_EPI = false, bool SP2 = false>
; __device__ __forceinline__ void gemm_phase(PG8_LAS unsigned char* lds, const Gemm g, const Sched& S, const Epi& E) {
;     ...
;             PG8_LDA(At, 1, 1); PG8_STAGE(PG8_SB(1, 0), b3, voffB); PG8_STAGE(PG8_SB(1, 1), b3 + hstep, voffB); PG8_STAGE(PG8_SA(1, 0), a3, voffA);
;             PG8_WAIT_V(8); PG8_WAIT_L(0); PG8_BAR; PG8_MMA(1, 0, At, B0); PG8_MMA(1, 1, At, B1); PG8_BAR; PG8_SCHED;
;     ...
;         if constexpr (ALIGN_EPI) { if (wr == 0) PG8_BAR; }
	s_add_i32 s30, s53, s86
	v_lshl_add_u64 v[172:173], v[172:173], 0, s[18:19]
	s_mov_b32 m0, s30
	ds_read_b128 v[208:211], v186 offset:49152
	ds_read_b128 v[212:215], v186 offset:50176
	ds_read_b128 v[216:219], v186 offset:51200
	ds_read_b128 v[220:223], v186 offset:52224
	ds_read_b128 v[224:227], v186 offset:53248
	ds_read_b128 v[232:235], v186 offset:54272
	ds_read_b128 v[236:239], v186 offset:55296
	ds_read_b128 v[240:243], v186 offset:56320
	global_load_lds_dwordx4 v[172:173], off
	s_add_i32 m0, s30, 0x2000
	s_add_u32 s30, s78, 0x40080
	v_lshl_add_u64 v[172:173], v[228:229], 0, s[18:19]
	s_addc_u32 s31, s79, 0
	s_add_i32 s53, s55, s86
	global_load_lds_dwordx4 v[172:173], off
	s_mov_b32 m0, s53
	s_nop 0
	global_load_lds_dwordx4 v146, s[30:31]
	s_add_i32 m0, s53, 0x2000
	s_nop 0
	global_load_lds_dwordx4 v150, s[30:31]
	v_lshl_add_u64 v[172:173], v[244:245], 0, s[18:19]
	s_mov_b32 m0, s93
	s_nop 0
	global_load_lds_dwordx4 v[172:173], off
	v_lshl_add_u64 v[172:173], v[246:247], 0, s[18:19]
	s_mov_b32 m0, s94
	s_nop 0
	global_load_lds_dwordx4 v[172:173], off
	s_waitcnt vmcnt(8)
	s_waitcnt lgkmcnt(0)
	s_barrier
	s_setprio 1
	s_waitcnt lgkmcnt(0)
	v_mfma_f32_16x16x32_bf16 v[60:63], v[128:131], v[208:211], v[60:63]
	v_mfma_f32_16x16x32_bf16 v[56:59], v[136:139], v[208:211], v[56:59]
	v_mfma_f32_16x16x32_bf16 v[48:51], v[128:131], v[216:219], v[48:51]
	v_mfma_f32_16x16x32_bf16 v[44:47], v[136:139], v[216:219], v[44:47]
	v_mfma_f32_16x16x32_bf16 v[32:35], v[128:131], v[224:227], v[32:35]
	v_mfma_f32_16x16x32_bf16 v[28:31], v[136:139], v[224:227], v[28:31]
	v_mfma_f32_16x16x32_bf16 v[16:19], v[128:131], v[236:239], v[16:19]
	v_mfma_f32_16x16x32_bf16 v[12:15], v[136:139], v[236:239], v[12:15]
	v_mfma_f32_16x16x32_bf16 v[60:63], v[132:135], v[212:215], v[60:63]
	v_mfma_f32_16x16x32_bf16 v[56:59], v[140:143], v[212:215], v[56:59]
	v_mfma_f32_16x16x32_bf16 v[48:51], v[132:135], v[220:223], v[48:51]
	v_mfma_f32_16x16x32_bf16 v[44:47], v[140:143], v[220:223], v[44:47]
	v_mfma_f32_16x16x32_bf16 v[32:35], v[132:135], v[232:235], v[32:35]
	v_mfma_f32_16x16x32_bf16 v[28:31], v[140:143], v[232:235], v[28:31]
	v_mfma_f32_16x16x32_bf16 v[16:19], v[132:135], v[240:243], v[16:19]
	v_mfma_f32_16x16x32_bf16 v[12:15], v[140:143], v[240:243], v[12:15]
	s_setprio 0
	s_setprio 1
	v_mfma_f32_16x16x32_bf16 v[52:55], v[192:195], v[208:211], v[52:55]
	v_mfma_f32_16x16x32_bf16 v[40:43], v[200:203], v[208:211], v[40:43]
	v_mfma_f32_16x16x32_bf16 v[36:39], v[192:195], v[216:219], v[36:39]
	v_mfma_f32_16x16x32_bf16 v[24:27], v[200:203], v[216:219], v[24:27]
	v_mfma_f32_16x16x32_bf16 v[20:23], v[192:195], v[224:227], v[20:23]
	v_mfma_f32_16x16x32_bf16 v[8:11], v[200:203], v[224:227], v[8:11]
	v_mfma_f32_16x16x32_bf16 v[4:7], v[192:195], v[236:239], v[4:7]
	v_mfma_f32_16x16x32_bf16 v[0:3], v[200:203], v[236:239], v[0:3]
	v_mfma_f32_16x16x32_bf16 v[52:55], v[196:199], v[212:215], v[52:55]
	v_mfma_f32_16x16x32_bf16 v[40:43], v[204:207], v[212:215], v[40:43]
	v_mfma_f32_16x16x32_bf16 v[36:39], v[196:199], v[220:223], v[36:39]
	v_mfma_f32_16x16x32_bf16 v[24:27], v[204:207], v[220:223], v[24:27]
	v_mfma_f32_16x16x32_bf16 v[20:23], v[196:199], v[232:235], v[20:23]
	v_mfma_f32_16x16x32_bf16 v[8:11], v[204:207], v[232:235], v[8:11]
	v_mfma_f32_16x16x32_bf16 v[4:7], v[196:199], v[240:243], v[4:7]
	v_mfma_f32_16x16x32_bf16 v[0:3], v[204:207], v[240:243], v[0:3]
	s_setprio 0
	s_add_i32 s29, s29, 2
	s_add_u32 s76, s76, 0x100
	s_addc_u32 s77, s77, 0
	s_add_u32 s27, s27, 0x100
	s_addc_u32 s28, s28, 0
	s_cmp_gt_u32 s29, 13
	s_barrier
	s_cbranch_scc0 .LBB0_91
	s_and_b64 vcc, exec, s[20:21]
	s_cbranch_vccz .LBB0_94
	s_barrier

; #define PG8_STAGE(bufoff, gbase, voff) do { _Pragma("unroll") for (int _i = 0; _i < 2; ++_i) \
;         __builtin_amdgcn_global_load_lds((const unsigned*)((const char*)(gbase) + (voff)[_i]), (PG8_LAS unsigned*)(lds + (bufoff) + ldsw + _i * 8192), 16, 0, 0); } while (0)
; #define PG8_LDA(dst, b, h) do { _Pragma("unroll") for (int m = 0; m < 4; ++m) _Pragma("unroll") for (int k = 0; k < 2; ++k) dst[m][k] = *(const PG8_LAS bf16x8*)(lds + PG8_SA(b, h) + aoff + m * 2048 + k * 1024); } while (0)
; #define PG8_LDB(dst, b, h) do { _Pragma("unroll") for (int n = 0; n < 2; ++n) _Pragma("unroll") for (int k = 0; k < 2; ++k) dst[n][k] = *(const PG8_LAS bf16x8*)(lds + PG8_SB(b, h) + boff + n * 2048 + k * 1024); } while (0)
; #define PG8_WAIT_V(n) asm volatile("s_waitcnt vmcnt(" #n ")" ::: "memory")
; #define PG8_WAIT_L(n) asm volatile("s_waitcnt lgkmcnt(" #n ")" ::: "memory")
; #define PG8_BAR __builtin_amdgcn_s_barrier()
; #define PG8_SCHED __builtin_amdgcn_sched_barrier(0)
; template <class Epi, class Sched, bool ALIGN_EPI = false, bool SP2 = false>
; __device__ __forceinline__ void gemm_phase(PG8_LAS unsigned char* lds, const Gemm g, const Sched& S, const Epi& E) {
;     ...
;         const bool has_next = S.next(ui + 1, nxt);
;         const char* nA = has_next ? (const char*)g.A + (size_t)nxt.pm * tstep : cA; const char* nB = has_next ? (const char*)g.Bt + (size_t)nxt.pn * tstep : cB;
;         for (int t = 0; t < nt; t += 2) {
;             const bool last = (t == nt - 2);
;             const char* a1 = cA + (size_t)(t + 1) * kstep;
;             const char* a2 = last ? nA : cA + (size_t)(t + 2) * kstep; const char* b2 = last ? nB : cB + (size_t)(t + 2) * kstep;
;             const char* a3 = a2 + kstep; const char* b3 = b2 + kstep;
;             if (last && has_next) S.a_ready(nxt);
;             if constexpr (SP2) {
;             PG8_LDB(B0, 0, 0); PG8_LDB(B1, 0, 1); PG8_SCHED; PG8_LDA(At, 0, 0); PG8_STAGE(PG8_SA(1, 1), a1 + hstep, voffA);
;             PG8_WAIT_V(8); PG8_WAIT_L(0); PG8_BAR; PG8_MMA(0, 0, At, B0); PG8_MMA(0, 1, At, B1); PG8_BAR; PG8_SCHED;
;             PG8_LDA(At, 0, 1); PG8_STAGE(PG8_SB(0, 0), b2, voffB); PG8_STAGE(PG8_SB(0, 1), b2 + hstep, voffB); PG8_STAGE(PG8_SA(0, 0), a2, voffA);
;             PG8_WAIT_V(8); PG8_WAIT_L(0); PG8_BAR; PG8_MMA(1, 0, At, B0); PG8_MMA(1, 1, At, B1); PG8_BAR; PG8_SCHED;
.LBB0_392:
	s_ashr_i32 s39, s38, 31
	s_lshl_b64 s[42:43], s[38:39], 19
	s_add_u32 s42, s68, s42
	s_addc_u32 s43, s69, s43
	s_and_b64 s[44:45], s[40:41], exec
	s_cselect_b32 s39, s43, s49
	s_cselect_b32 s47, s42, s48
	s_ashr_i32 s37, s36, 31
	s_lshl_b64 s[44:45], s[36:37], 19
	s_add_u32 s44, s23, s44
	s_addc_u32 s45, s24, s45
	s_and_b64 s[52:53], s[40:41], exec
	s_cselect_b32 s37, s45, s51
	s_cselect_b32 s59, s44, s50
	s_add_u32 s48, s48, 0x40080
	s_addc_u32 s49, s49, 0
	s_add_u32 s60, s50, 0x100
	s_addc_u32 s61, s51, 0
	s_mov_b32 s62, -2
	s_waitcnt lgkmcnt(0)
	ds_read_b128 v[124:127], v234
	ds_read_b128 v[132:135], v234 offset:1024
	ds_read_b128 v[136:139], v234 offset:2048
	ds_read_b128 v[140:143], v234 offset:3072
	ds_read_b128 v[144:147], v235
	ds_read_b128 v[148:151], v235 offset:1024
	ds_read_b128 v[152:155], v235 offset:2048
	ds_read_b128 v[156:159], v235 offset:3072
	s_add_u32 s50, s48, 0xfffc0080
	s_addc_u32 s51, s49, -1
	s_cmp_eq_u32 s62, 12
	s_cselect_b32 s53, s39, s51
	s_cselect_b32 s52, s47, s50
	s_cselect_b32 s51, s37, s61
	s_cselect_b32 s50, s59, s60
	s_add_i32 m0, s26, 0xc000
	ds_read_b128 v[160:163], v236
	ds_read_b128 v[164:167], v236 offset:1024
	ds_read_b128 v[168:171], v236 offset:2048
	ds_read_b128 v[172:175], v236 offset:3072
	ds_read_b128 v[176:179], v236 offset:4096
	ds_read_b128 v[180:183], v236 offset:5120
	ds_read_b128 v[198:201], v236 offset:6144
	ds_read_b128 v[202:205], v236 offset:7168
	global_load_lds_dwordx4 v192, s[48:49]
	s_add_i32 m0, s26, 0xe000
	s_nop 0
	global_load_lds_dwordx4 v194, s[48:49]
	s_waitcnt vmcnt(8)
	s_waitcnt lgkmcnt(0)
	s_barrier
	s_setprio 1
	s_waitcnt lgkmcnt(0)
	v_mfma_f32_16x16x32_bf16 v[128:131], v[124:127], v[160:163], 0
	v_mfma_f32_16x16x32_bf16 v[120:123], v[136:139], v[160:163], 0
	v_mfma_f32_16x16x32_bf16 v[108:111], v[124:127], v[168:171], 0
	v_mfma_f32_16x16x32_bf16 v[104:107], v[136:139], v[168:171], 0
	v_mfma_f32_16x16x32_bf16 v[92:95], v[124:127], v[176:179], 0
	v_mfma_f32_16x16x32_bf16 v[88:91], v[136:139], v[176:179], 0
	v_mfma_f32_16x16x32_bf16 v[76:79], v[124:127], v[198:201], 0
	v_mfma_f32_16x16x32_bf16 v[72:75], v[136:139], v[198:201], 0
	v_mfma_f32_16x16x32_bf16 v[128:131], v[132:135], v[164:167], v[128:131]
	v_mfma_f32_16x16x32_bf16 v[120:123], v[140:143], v[164:167], v[120:123]
	v_mfma_f32_16x16x32_bf16 v[108:111], v[132:135], v[172:175], v[108:111]
	v_mfma_f32_16x16x32_bf16 v[104:107], v[140:143], v[172:175], v[104:107]
	v_mfma_f32_16x16x32_bf16 v[92:95], v[132:135], v[180:183], v[92:95]
	v_mfma_f32_16x16x32_bf16 v[88:91], v[140:143], v[180:183], v[88:91]
	v_mfma_f32_16x16x32_bf16 v[76:79], v[132:135], v[202:205], v[76:79]
	v_mfma_f32_16x16x32_bf16 v[72:75], v[140:143], v[202:205], v[72:75]
	s_setprio 0
	s_setprio 1
	v_mfma_f32_16x16x32_bf16 v[116:119], v[144:147], v[160:163], 0
	v_mfma_f32_16x16x32_bf16 v[112:115], v[152:155], v[160:163], 0
	v_mfma_f32_16x16x32_bf16 v[100:103], v[144:147], v[168:171], 0
	v_mfma_f32_16x16x32_bf16 v[96:99], v[152:155], v[168:171], 0
	v_mfma_f32_16x16x32_bf16 v[84:87], v[144:147], v[176:179], 0
	v_mfma_f32_16x16x32_bf16 v[80:83], v[152:155], v[176:179], 0
	v_mfma_f32_16x16x32_bf16 v[68:71], v[144:147], v[198:201], 0
	v_mfma_f32_16x16x32_bf16 v[64:67], v[152:155], v[198:201], 0
	v_mfma_f32_16x16x32_bf16 v[116:119], v[148:151], v[164:167], v[116:119]
	v_mfma_f32_16x16x32_bf16 v[112:115], v[156:159], v[164:167], v[112:115]
	v_mfma_f32_16x16x32_bf16 v[100:103], v[148:151], v[172:175], v[100:103]
	v_mfma_f32_16x16x32_bf16 v[96:99], v[156:159], v[172:175], v[96:99]
	v_mfma_f32_16x16x32_bf16 v[84:87], v[148:151], v[180:183], v[84:87]
	v_mfma_f32_16x16x32_bf16 v[80:83], v[156:159], v[180:183], v[80:83]
	v_mfma_f32_16x16x32_bf16 v[68:71], v[148:151], v[202:205], v[68:71]
	v_mfma_f32_16x16x32_bf16 v[64:67], v[156:159], v[202:205], v[64:67]
	s_setprio 0
	s_barrier
	s_add_i32 s63, s56, s25
	v_lshl_add_u64 v[206:207], s[50:51], 0, v[186:187]
	s_mov_b32 m0, s63
	ds_read_b128 v[160:163], v236 offset:16384
	ds_read_b128 v[164:167], v236 offset:17408
	ds_read_b128 v[168:171], v236 offset:18432
	ds_read_b128 v[172:175], v236 offset:19456
	ds_read_b128 v[176:179], v236 offset:20480
	ds_read_b128 v[180:183], v236 offset:21504
	ds_read_b128 v[198:201], v236 offset:22528
	ds_read_b128 v[202:205], v236 offset:23552
	global_load_lds_dwordx4 v[206:207], off
	s_add_i32 m0, s63, 0x2000
	s_add_u32 s64, s50, 0x40000
	v_lshl_add_u64 v[208:209], s[50:51], 0, v[190:191]
	s_addc_u32 s65, s51, 0
	s_add_i32 s63, s57, s25
	global_load_lds_dwordx4 v[208:209], off
	s_mov_b32 m0, s63
	v_lshl_add_u64 v[212:213], s[52:53], 0, v[188:189]
	global_load_lds_dwordx4 v186, s[64:65]
	s_add_i32 m0, s63, 0x2000
	s_nop 0
	global_load_lds_dwordx4 v190, s[64:65]
	v_lshl_add_u64 v[210:211], s[52:53], 0, v[184:185]
	s_mov_b32 m0, s26
	s_nop 0
	global_load_lds_dwordx4 v[210:211], off
	s_mov_b32 m0, s27
	s_nop 0
	global_load_lds_dwordx4 v[212:213], off
	s_waitcnt vmcnt(8)
	s_waitcnt lgkmcnt(0)
	s_barrier
; #define PG8_STAGE(bufoff, gbase, voff) do { _Pragma("unroll") for (int _i = 0; _i < 2; ++_i) \
;         __builtin_amdgcn_global_load_lds((const unsigned*)((const char*)(gbase) + (voff)[_i]), (PG8_LAS unsigned*)(lds + (bufoff) + ldsw + _i * 8192), 16, 0, 0); } while (0)
; #define PG8_LDA(dst, b, h) do { _Pragma("unroll") for (int m = 0; m < 4; ++m) _Pragma("unroll") for (int k = 0; k < 2; ++k) dst[m][k] = *(const PG8_LAS bf16x8*)(lds + PG8_SA(b, h) + aoff + m * 2048 + k * 1024); } while (0)
; #define PG8_LDB(dst, b, h) do { _Pragma("unroll") for (int n = 0; n < 2; ++n) _Pragma("unroll") for (int k = 0; k < 2; ++k) dst[n][k] = *(const PG8_LAS bf16x8*)(lds + PG8_SB(b, h) + boff + n * 2048 + k * 1024); } while (0)
; #define PG8_MMA(ai, bj, At, Bt) do { __builtin_amdgcn_s_setprio(1); _Pragma("unroll") for (int m = 0; m < 4; ++m) _Pragma("unroll") for (int n = 0; n < 2; ++n) _Pragma("unroll") for (int k = 0; k < 2; ++k) \
;         acc[ai][bj][m][n] = __builtin_amdgcn_mfma_f32_16x16x32_bf16(Bt[n][k], At[m][k], acc[ai][bj][m][n], 0, 0, 0); __builtin_amdgcn_s_setprio(0); } while (0)
; #define PG8_WAIT_V(n) asm volatile("s_waitcnt vmcnt(" #n ")" ::: "memory")
; #define PG8_WAIT_L(n) asm volatile("s_waitcnt lgkmcnt(" #n ")" ::: "memory")
; #define PG8_BAR __builtin_amdgcn_s_barrier()
; #define PG8_SCHED __builtin_amdgcn_sched_barrier(0)
; template <class Epi, class Sched, bool ALIGN_EPI = false, bool SP2 = false>
; __device__ __forceinline__ void gemm_phase(PG8_LAS unsigned char* lds, const Gemm g, const Sched& S, const Epi& E) {
;     ...
;             PG8_WAIT_V(8); PG8_WAIT_L(0); PG8_BAR; PG8_MMA(1, 0, At, B0); PG8_MMA(1, 1, At, B1); PG8_BAR; PG8_SCHED;
;             PG8_LDB(B0, 1, 0); PG8_LDB(B1, 1, 1); PG8_SCHED; PG8_LDA(At, 1, 0); PG8_STAGE(PG8_SA(0, 1), a2 + hstep, voffA);
;             PG8_WAIT_V(8); PG8_WAIT_L(0); PG8_BAR; PG8_MMA(0, 0, At, B0); PG8_MMA(0, 1, At, B1); PG8_BAR; PG8_SCHED;
	s_setprio 1
	s_waitcnt lgkmcnt(0)
	v_mfma_f32_16x16x32_bf16 v[60:63], v[124:127], v[160:163], 0
	v_mfma_f32_16x16x32_bf16 v[56:59], v[136:139], v[160:163], 0
	v_mfma_f32_16x16x32_bf16 v[44:47], v[124:127], v[168:171], 0
	v_mfma_f32_16x16x32_bf16 v[40:43], v[136:139], v[168:171], 0
	v_mfma_f32_16x16x32_bf16 v[28:31], v[124:127], v[176:179], 0
	v_mfma_f32_16x16x32_bf16 v[24:27], v[136:139], v[176:179], 0
	v_mfma_f32_16x16x32_bf16 v[12:15], v[124:127], v[198:201], 0
	v_mfma_f32_16x16x32_bf16 v[8:11], v[136:139], v[198:201], 0
	v_mfma_f32_16x16x32_bf16 v[60:63], v[132:135], v[164:167], v[60:63]
	v_mfma_f32_16x16x32_bf16 v[56:59], v[140:143], v[164:167], v[56:59]
	v_mfma_f32_16x16x32_bf16 v[44:47], v[132:135], v[172:175], v[44:47]
	v_mfma_f32_16x16x32_bf16 v[40:43], v[140:143], v[172:175], v[40:43]
	v_mfma_f32_16x16x32_bf16 v[28:31], v[132:135], v[180:183], v[28:31]
	v_mfma_f32_16x16x32_bf16 v[24:27], v[140:143], v[180:183], v[24:27]
	v_mfma_f32_16x16x32_bf16 v[12:15], v[132:135], v[202:205], v[12:15]
	v_mfma_f32_16x16x32_bf16 v[8:11], v[140:143], v[202:205], v[8:11]
	s_setprio 0
	s_setprio 1
	v_mfma_f32_16x16x32_bf16 v[52:55], v[144:147], v[160:163], 0
	v_mfma_f32_16x16x32_bf16 v[48:51], v[152:155], v[160:163], 0
	v_mfma_f32_16x16x32_bf16 v[36:39], v[144:147], v[168:171], 0
	v_mfma_f32_16x16x32_bf16 v[32:35], v[152:155], v[168:171], 0
	v_mfma_f32_16x16x32_bf16 v[20:23], v[144:147], v[176:179], 0
	v_mfma_f32_16x16x32_bf16 v[16:19], v[152:155], v[176:179], 0
	v_mfma_f32_16x16x32_bf16 v[4:7], v[144:147], v[198:201], 0
	v_mfma_f32_16x16x32_bf16 v[0:3], v[152:155], v[198:201], 0
	v_mfma_f32_16x16x32_bf16 v[52:55], v[148:151], v[164:167], v[52:55]
	v_mfma_f32_16x16x32_bf16 v[48:51], v[156:159], v[164:167], v[48:51]
	v_mfma_f32_16x16x32_bf16 v[36:39], v[148:151], v[172:175], v[36:39]
	v_mfma_f32_16x16x32_bf16 v[32:35], v[156:159], v[172:175], v[32:35]
	v_mfma_f32_16x16x32_bf16 v[20:23], v[148:151], v[180:183], v[20:23]
	v_mfma_f32_16x16x32_bf16 v[16:19], v[156:159], v[180:183], v[16:19]
	v_mfma_f32_16x16x32_bf16 v[4:7], v[148:151], v[202:205], v[4:7]
	v_mfma_f32_16x16x32_bf16 v[0:3], v[156:159], v[202:205], v[0:3]
	s_setprio 0
	s_barrier
	s_add_i32 s63, 0, 0x18000
	s_add_i32 s64, 0, 0x1c000
	v_add_u32_e32 v140, s63, v232
	v_add_u32_e32 v156, s64, v232
	ds_read_b128 v[124:127], v140
	ds_read_b128 v[132:135], v140 offset:1024
	ds_read_b128 v[136:139], v140 offset:2048
	ds_read_b128 v[140:143], v140 offset:3072
	ds_read_b128 v[144:147], v156
	ds_read_b128 v[148:151], v156 offset:1024
	ds_read_b128 v[152:155], v156 offset:2048
	ds_read_b128 v[156:159], v156 offset:3072
	s_add_u32 s52, s52, 0x40000
	s_addc_u32 s53, s53, 0
	s_mov_b32 m0, s28
	ds_read_b128 v[160:163], v236 offset:32768
	ds_read_b128 v[164:167], v236 offset:33792
	ds_read_b128 v[168:171], v236 offset:34816
	ds_read_b128 v[172:175], v236 offset:35840
	ds_read_b128 v[176:179], v236 offset:36864
	ds_read_b128 v[180:183], v236 offset:37888
	ds_read_b128 v[198:201], v236 offset:38912
	ds_read_b128 v[202:205], v236 offset:39936
	global_load_lds_dwordx4 v184, s[52:53]
	v_lshl_add_u64 v[214:215], s[52:53], 0, v[188:189]
	s_mov_b32 m0, s29
	s_nop 0
	global_load_lds_dwordx4 v[214:215], off
	s_waitcnt vmcnt(8)
	s_waitcnt lgkmcnt(0)
	s_barrier
	s_setprio 1
	s_waitcnt lgkmcnt(0)
	v_mfma_f32_16x16x32_bf16 v[128:131], v[124:127], v[160:163], v[128:131]
	v_mfma_f32_16x16x32_bf16 v[120:123], v[136:139], v[160:163], v[120:123]
	v_mfma_f32_16x16x32_bf16 v[108:111], v[124:127], v[168:171], v[108:111]
	v_mfma_f32_16x16x32_bf16 v[104:107], v[136:139], v[168:171], v[104:107]
	v_mfma_f32_16x16x32_bf16 v[92:95], v[124:127], v[176:179], v[92:95]
	v_mfma_f32_16x16x32_bf16 v[88:91], v[136:139], v[176:179], v[88:91]
	v_mfma_f32_16x16x32_bf16 v[76:79], v[124:127], v[198:201], v[76:79]
	v_mfma_f32_16x16x32_bf16 v[72:75], v[136:139], v[198:201], v[72:75]
	v_mfma_f32_16x16x32_bf16 v[128:131], v[132:135], v[164:167], v[128:131]
	v_mfma_f32_16x16x32_bf16 v[120:123], v[140:143], v[164:167], v[120:123]
	v_mfma_f32_16x16x32_bf16 v[108:111], v[132:135], v[172:175], v[108:111]
	v_mfma_f32_16x16x32_bf16 v[104:107], v[140:143], v[172:175], v[104:107]
	v_mfma_f32_16x16x32_bf16 v[92:95], v[132:135], v[180:183], v[92:95]
	v_mfma_f32_16x16x32_bf16 v[88:91], v[140:143], v[180:183], v[88:91]
	v_mfma_f32_16x16x32_bf16 v[76:79], v[132:135], v[202:205], v[76:79]
	v_mfma_f32_16x16x32_bf16 v[72:75], v[140:143], v[202:205], v[72:75]
	s_setprio 0
	s_setprio 1
	v_mfma_f32_16x16x32_bf16 v[116:119], v[144:147], v[160:163], v[116:119]
	v_mfma_f32_16x16x32_bf16 v[112:115], v[152:155], v[160:163], v[112:115]
	v_mfma_f32_16x16x32_bf16 v[100:103], v[144:147], v[168:171], v[100:103]
	v_mfma_f32_16x16x32_bf16 v[96:99], v[152:155], v[168:171], v[96:99]
	v_mfma_f32_16x16x32_bf16 v[84:87], v[144:147], v[176:179], v[84:87]
	v_mfma_f32_16x16x32_bf16 v[80:83], v[152:155], v[176:179], v[80:83]
	v_mfma_f32_16x16x32_bf16 v[68:71], v[144:147], v[198:201], v[68:71]
	v_mfma_f32_16x16x32_bf16 v[64:67], v[152:155], v[198:201], v[64:67]
	v_mfma_f32_16x16x32_bf16 v[116:119], v[148:151], v[164:167], v[116:119]
	v_mfma_f32_16x16x32_bf16 v[112:115], v[156:159], v[164:167], v[112:115]
	v_mfma_f32_16x16x32_bf16 v[100:103], v[148:151], v[172:175], v[100:103]
	v_mfma_f32_16x16x32_bf16 v[96:99], v[156:159], v[172:175], v[96:99]
	v_mfma_f32_16x16x32_bf16 v[84:87], v[148:151], v[180:183], v[84:87]
	v_mfma_f32_16x16x32_bf16 v[80:83], v[156:159], v[180:183], v[80:83]
	v_mfma_f32_16x16x32_bf16 v[68:71], v[148:151], v[202:205], v[68:71]
	v_mfma_f32_16x16x32_bf16 v[64:67], v[156:159], v[202:205], v[64:67]
	s_setprio 0
	s_barrier
; #define PG8_STAGE(bufoff, gbase, voff) do { _Pragma("unroll") for (int _i = 0; _i < 2; ++_i) \
;         __builtin_amdgcn_global_load_lds((const unsigned*)((const char*)(gbase) + (voff)[_i]), (PG8_LAS unsigned*)(lds + (bufoff) + ldsw + _i * 8192), 16, 0, 0); } while (0)
; #define PG8_LDA(dst, b, h) do { _Pragma("unroll") for (int m = 0; m < 4; ++m) _Pragma("unroll") for (int k = 0; k < 2; ++k) dst[m][k] = *(const PG8_LAS bf16x8*)(lds + PG8_SA(b, h) + aoff + m * 2048 + k * 1024); } while (0)
; #define PG8_LDB(dst, b, h) do { _Pragma("unroll") for (int n = 0; n < 2; ++n) _Pragma("unroll") for (int k = 0; k < 2; ++k) dst[n][k] = *(const PG8_LAS bf16x8*)(lds + PG8_SB(b, h) + boff + n * 2048 + k * 1024); } while (0)
; #define PG8_MMA(ai, bj, At, Bt) do { __builtin_amdgcn_s_setprio(1); _Pragma("unroll") for (int m = 0; m < 4; ++m) _Pragma("unroll") for (int n = 0; n < 2; ++n) _Pragma("unroll") for (int k = 0; k < 2; ++k) \
;         acc[ai][bj][m][n] = __builtin_amdgcn_mfma_f32_16x16x32_bf16(Bt[n][k], At[m][k], acc[ai][bj][m][n], 0, 0, 0); __builtin_amdgcn_s_setprio(0); } while (0)
; #define PG8_WAIT_V(n) asm volatile("s_waitcnt vmcnt(" #n ")" ::: "memory")
; #define PG8_WAIT_L(n) asm volatile("s_waitcnt lgkmcnt(" #n ")" ::: "memory")
; #define PG8_BAR __builtin_amdgcn_s_barrier()
; #define PG8_SCHED __builtin_amdgcn_sched_barrier(0)
; template <class Epi, class Sched, bool ALIGN_EPI = false, bool SP2 = false>
; __device__ __forceinline__ void gemm_phase(PG8_LAS unsigned char* lds, const Gemm g, const Sched& S, const Epi& E) {
;     ...
;             PG8_LDB(B0, 0, 0); PG8_LDB(B1, 0, 1); PG8_SCHED; PG8_LDA(At, 0, 0); PG8_STAGE(PG8_SA(1, 1), a1 + hstep, voffA);
;             PG8_WAIT_V(8); PG8_WAIT_L(0); PG8_BAR; PG8_MMA(0, 0, At, B0); PG8_MMA(0, 1, At, B1); PG8_BAR; PG8_SCHED;
;     ...
;             PG8_LDA(At, 1, 1); PG8_STAGE(PG8_SB(1, 0), b3, voffB); PG8_STAGE(PG8_SB(1, 1), b3 + hstep, voffB); PG8_STAGE(PG8_SA(1, 0), a3, voffA);
;             PG8_WAIT_V(8); PG8_WAIT_L(0); PG8_BAR; PG8_MMA(1, 0, At, B0); PG8_MMA(1, 1, At, B1); PG8_BAR; PG8_SCHED;
	s_add_i32 s52, s63, s25
	v_lshl_add_u64 v[206:207], v[206:207], 0, s[18:19]
	s_mov_b32 m0, s52
	ds_read_b128 v[160:163], v236 offset:49152
	ds_read_b128 v[164:167], v236 offset:50176
	ds_read_b128 v[168:171], v236 offset:51200
	ds_read_b128 v[172:175], v236 offset:52224
	ds_read_b128 v[176:179], v236 offset:53248
	ds_read_b128 v[180:183], v236 offset:54272
	ds_read_b128 v[198:201], v236 offset:55296
	ds_read_b128 v[202:205], v236 offset:56320
	global_load_lds_dwordx4 v[206:207], off
	s_add_i32 m0, s52, 0x2000
	s_add_u32 s50, s50, 0x40080
	v_lshl_add_u64 v[206:207], v[208:209], 0, s[18:19]
	s_addc_u32 s51, s51, 0
	s_add_i32 s52, s64, s25
	global_load_lds_dwordx4 v[206:207], off
	s_mov_b32 m0, s52
	s_nop 0
	global_load_lds_dwordx4 v186, s[50:51]
	s_add_i32 m0, s52, 0x2000
	s_nop 0
	global_load_lds_dwordx4 v190, s[50:51]
	v_lshl_add_u64 v[206:207], v[210:211], 0, s[18:19]
	s_mov_b32 m0, s31
	s_nop 0
	global_load_lds_dwordx4 v[206:207], off
	v_lshl_add_u64 v[206:207], v[212:213], 0, s[18:19]
	s_mov_b32 m0, s33
	s_nop 0
	global_load_lds_dwordx4 v[206:207], off
	s_waitcnt vmcnt(8)
	s_waitcnt lgkmcnt(0)
	s_barrier
	s_setprio 1
	s_waitcnt lgkmcnt(0)
	v_mfma_f32_16x16x32_bf16 v[60:63], v[124:127], v[160:163], v[60:63]
	v_mfma_f32_16x16x32_bf16 v[56:59], v[136:139], v[160:163], v[56:59]
	v_mfma_f32_16x16x32_bf16 v[44:47], v[124:127], v[168:171], v[44:47]
	v_mfma_f32_16x16x32_bf16 v[40:43], v[136:139], v[168:171], v[40:43]
	v_mfma_f32_16x16x32_bf16 v[28:31], v[124:127], v[176:179], v[28:31]
	v_mfma_f32_16x16x32_bf16 v[24:27], v[136:139], v[176:179], v[24:27]
	v_mfma_f32_16x16x32_bf16 v[12:15], v[124:127], v[198:201], v[12:15]
	v_mfma_f32_16x16x32_bf16 v[8:11], v[136:139], v[198:201], v[8:11]
	v_mfma_f32_16x16x32_bf16 v[60:63], v[132:135], v[164:167], v[60:63]
	v_mfma_f32_16x16x32_bf16 v[56:59], v[140:143], v[164:167], v[56:59]
	v_mfma_f32_16x16x32_bf16 v[44:47], v[132:135], v[172:175], v[44:47]
	v_mfma_f32_16x16x32_bf16 v[40:43], v[140:143], v[172:175], v[40:43]
	v_mfma_f32_16x16x32_bf16 v[28:31], v[132:135], v[180:183], v[28:31]
	v_mfma_f32_16x16x32_bf16 v[24:27], v[140:143], v[180:183], v[24:27]
	v_mfma_f32_16x16x32_bf16 v[12:15], v[132:135], v[202:205], v[12:15]
	v_mfma_f32_16x16x32_bf16 v[8:11], v[140:143], v[202:205], v[8:11]
	s_setprio 0
	s_setprio 1
	v_mfma_f32_16x16x32_bf16 v[52:55], v[144:147], v[160:163], v[52:55]
	v_mfma_f32_16x16x32_bf16 v[48:51], v[152:155], v[160:163], v[48:51]
	v_mfma_f32_16x16x32_bf16 v[36:39], v[144:147], v[168:171], v[36:39]
	v_mfma_f32_16x16x32_bf16 v[32:35], v[152:155], v[168:171], v[32:35]
	v_mfma_f32_16x16x32_bf16 v[20:23], v[144:147], v[176:179], v[20:23]
	v_mfma_f32_16x16x32_bf16 v[16:19], v[152:155], v[176:179], v[16:19]
	v_mfma_f32_16x16x32_bf16 v[4:7], v[144:147], v[198:201], v[4:7]
	v_mfma_f32_16x16x32_bf16 v[0:3], v[152:155], v[198:201], v[0:3]
	v_mfma_f32_16x16x32_bf16 v[52:55], v[148:151], v[164:167], v[52:55]
	v_mfma_f32_16x16x32_bf16 v[48:51], v[156:159], v[164:167], v[48:51]
	v_mfma_f32_16x16x32_bf16 v[36:39], v[148:151], v[172:175], v[36:39]
	v_mfma_f32_16x16x32_bf16 v[32:35], v[156:159], v[172:175], v[32:35]
	v_mfma_f32_16x16x32_bf16 v[20:23], v[148:151], v[180:183], v[20:23]
	v_mfma_f32_16x16x32_bf16 v[16:19], v[156:159], v[180:183], v[16:19]
	v_mfma_f32_16x16x32_bf16 v[4:7], v[148:151], v[202:205], v[4:7]
	v_mfma_f32_16x16x32_bf16 v[0:3], v[156:159], v[202:205], v[0:3]
	s_setprio 0
	s_add_i32 s62, s62, 2
	s_add_u32 s48, s48, 0x100
	s_addc_u32 s49, s49, 0
	s_add_u32 s60, s60, 0x100
	s_addc_u32 s61, s61, 0
	s_cmp_gt_u32 s62, 13
	s_barrier
.LBB0_393:
	ds_read_b128 v[124:127], v234
	ds_read_b128 v[132:135], v234 offset:1024
	ds_read_b128 v[136:139], v234 offset:2048
	ds_read_b128 v[140:143], v234 offset:3072
	ds_read_b128 v[144:147], v235
	ds_read_b128 v[148:151], v235 offset:1024
	ds_read_b128 v[152:155], v235 offset:2048
	ds_read_b128 v[156:159], v235 offset:3072
	s_add_u32 s50, s48, 0xfffc0080
	s_addc_u32 s51, s49, -1
	s_cmp_eq_u32 s62, 12
	s_cselect_b32 s53, s39, s51
	s_cselect_b32 s52, s47, s50
	s_cselect_b32 s51, s37, s61
	s_cselect_b32 s50, s59, s60
	s_add_i32 m0, s26, 0xc000
	ds_read_b128 v[160:163], v236
	ds_read_b128 v[164:167], v236 offset:1024
	ds_read_b128 v[168:171], v236 offset:2048
	ds_read_b128 v[172:175], v236 offset:3072
	ds_read_b128 v[176:179], v236 offset:4096
	ds_read_b128 v[180:183], v236 offset:5120
	ds_read_b128 v[198:201], v236 offset:6144
	ds_read_b128 v[202:205], v236 offset:7168
	global_load_lds_dwordx4 v192, s[48:49]
	s_add_i32 m0, s26, 0xe000
	s_nop 0
	global_load_lds_dwordx4 v194, s[48:49]
	s_waitcnt vmcnt(8)
	s_waitcnt lgkmcnt(0)
	s_barrier
; #define PG8_STAGE(bufoff, gbase, voff) do { _Pragma("unroll") for (int _i = 0; _i < 2; ++_i) \
;         __builtin_amdgcn_global_load_lds((const unsigned*)((const char*)(gbase) + (voff)[_i]), (PG8_LAS unsigned*)(lds + (bufoff) + ldsw + _i * 8192), 16, 0, 0); } while (0)
; #define PG8_LDA(dst, b, h) do { _Pragma("unroll") for (int m = 0; m < 4; ++m) _Pragma("unroll") for (int k = 0; k < 2; ++k) dst[m][k] = *(const PG8_LAS bf16x8*)(lds + PG8_SA(b, h) + aoff + m * 2048 + k * 1024); } while (0)
; #define PG8_LDB(dst, b, h) do { _Pragma("unroll") for (int n = 0; n < 2; ++n) _Pragma("unroll") for (int k = 0; k < 2; ++k) dst[n][k] = *(const PG8_LAS bf16x8*)(lds + PG8_SB(b, h) + boff + n * 2048 + k * 1024); } while (0)
; #define PG8_MMA(ai, bj, At, Bt) do { __builtin_amdgcn_s_setprio(1); _Pragma("unroll") for (int m = 0; m < 4; ++m) _Pragma("unroll") for (int n = 0; n < 2; ++n) _Pragma("unroll") for (int k = 0; k < 2; ++k) \
;         acc[ai][bj][m][n] = __builtin_amdgcn_mfma_f32_16x16x32_bf16(Bt[n][k], At[m][k], acc[ai][bj][m][n], 0, 0, 0); __builtin_amdgcn_s_setprio(0); } while (0)
; #define PG8_WAIT_V(n) asm volatile("s_waitcnt vmcnt(" #n ")" ::: "memory")
; #define PG8_WAIT_L(n) asm volatile("s_waitcnt lgkmcnt(" #n ")" ::: "memory")
; #define PG8_BAR __builtin_amdgcn_s_barrier()
; #define PG8_SCHED __builtin_amdgcn_sched_barrier(0)
; template <class Epi, class Sched, bool ALIGN_EPI = false, bool SP2 = false>
; __device__ __forceinline__ void gemm_phase(PG8_LAS unsigned char* lds, const Gemm g, const Sched& S, const Epi& E) {
;     ...
;             PG8_LDB(B0, 0, 0); PG8_LDB(B1, 0, 1); PG8_SCHED; PG8_LDA(At, 0, 0); PG8_STAGE(PG8_SA(1, 1), a1 + hstep, voffA);
;             PG8_WAIT_V(8); PG8_WAIT_L(0); PG8_BAR; PG8_MMA(0, 0, At, B0); PG8_MMA(0, 1, At, B1); PG8_BAR; PG8_SCHED;
;             PG8_LDA(At, 0, 1); PG8_STAGE(PG8_SB(0, 0), b2, voffB); PG8_STAGE(PG8_SB(0, 1), b2 + hstep, voffB); PG8_STAGE(PG8_SA(0, 0), a2, voffA);
;             PG8_WAIT_V(8); PG8_WAIT_L(0); PG8_BAR; PG8_MMA(1, 0, At, B0); PG8_MMA(1, 1, At, B1); PG8_BAR; PG8_SCHED;
	s_setprio 1
	s_waitcnt lgkmcnt(0)
	v_mfma_f32_16x16x32_bf16 v[128:131], v[124:127], v[160:163], v[128:131]
	v_mfma_f32_16x16x32_bf16 v[120:123], v[136:139], v[160:163], v[120:123]
	v_mfma_f32_16x16x32_bf16 v[108:111], v[124:127], v[168:171], v[108:111]
	v_mfma_f32_16x16x32_bf16 v[104:107], v[136:139], v[168:171], v[104:107]
	v_mfma_f32_16x16x32_bf16 v[92:95], v[124:127], v[176:179], v[92:95]
	v_mfma_f32_16x16x32_bf16 v[88:91], v[136:139], v[176:179], v[88:91]
	v_mfma_f32_16x16x32_bf16 v[76:79], v[124:127], v[198:201], v[76:79]
	v_mfma_f32_16x16x32_bf16 v[72:75], v[136:139], v[198:201], v[72:75]
	v_mfma_f32_16x16x32_bf16 v[128:131], v[132:135], v[164:167], v[128:131]
	v_mfma_f32_16x16x32_bf16 v[120:123], v[140:143], v[164:167], v[120:123]
	v_mfma_f32_16x16x32_bf16 v[108:111], v[132:135], v[172:175], v[108:111]
	v_mfma_f32_16x16x32_bf16 v[104:107], v[140:143], v[172:175], v[104:107]
	v_mfma_f32_16x16x32_bf16 v[92:95], v[132:135], v[180:183], v[92:95]
	v_mfma_f32_16x16x32_bf16 v[88:91], v[140:143], v[180:183], v[88:91]
	v_mfma_f32_16x16x32_bf16 v[76:79], v[132:135], v[202:205], v[76:79]
	v_mfma_f32_16x16x32_bf16 v[72:75], v[140:143], v[202:205], v[72:75]
	s_setprio 0
	s_setprio 1
	v_mfma_f32_16x16x32_bf16 v[116:119], v[144:147], v[160:163], v[116:119]
	v_mfma_f32_16x16x32_bf16 v[112:115], v[152:155], v[160:163], v[112:115]
	v_mfma_f32_16x16x32_bf16 v[100:103], v[144:147], v[168:171], v[100:103]
	v_mfma_f32_16x16x32_bf16 v[96:99], v[152:155], v[168:171], v[96:99]
	v_mfma_f32_16x16x32_bf16 v[84:87], v[144:147], v[176:179], v[84:87]
	v_mfma_f32_16x16x32_bf16 v[80:83], v[152:155], v[176:179], v[80:83]
	v_mfma_f32_16x16x32_bf16 v[68:71], v[144:147], v[198:201], v[68:71]
	v_mfma_f32_16x16x32_bf16 v[64:67], v[152:155], v[198:201], v[64:67]
	v_mfma_f32_16x16x32_bf16 v[116:119], v[148:151], v[164:167], v[116:119]
	v_mfma_f32_16x16x32_bf16 v[112:115], v[156:159], v[164:167], v[112:115]
	v_mfma_f32_16x16x32_bf16 v[100:103], v[148:151], v[172:175], v[100:103]
	v_mfma_f32_16x16x32_bf16 v[96:99], v[156:159], v[172:175], v[96:99]
	v_mfma_f32_16x16x32_bf16 v[84:87], v[148:151], v[180:183], v[84:87]
	v_mfma_f32_16x16x32_bf16 v[80:83], v[156:159], v[180:183], v[80:83]
	v_mfma_f32_16x16x32_bf16 v[68:71], v[148:151], v[202:205], v[68:71]
	v_mfma_f32_16x16x32_bf16 v[64:67], v[156:159], v[202:205], v[64:67]
	s_setprio 0
	s_barrier
	s_add_i32 s63, s56, s25
	v_lshl_add_u64 v[206:207], s[50:51], 0, v[186:187]
	s_mov_b32 m0, s63
	ds_read_b128 v[160:163], v236 offset:16384
	ds_read_b128 v[164:167], v236 offset:17408
	ds_read_b128 v[168:171], v236 offset:18432
	ds_read_b128 v[172:175], v236 offset:19456
	ds_read_b128 v[176:179], v236 offset:20480
	ds_read_b128 v[180:183], v236 offset:21504
	ds_read_b128 v[198:201], v236 offset:22528
	ds_read_b128 v[202:205], v236 offset:23552
	global_load_lds_dwordx4 v[206:207], off
	s_add_i32 m0, s63, 0x2000
	s_add_u32 s64, s50, 0x40000
	v_lshl_add_u64 v[208:209], s[50:51], 0, v[190:191]
	s_addc_u32 s65, s51, 0
	s_add_i32 s63, s57, s25
	global_load_lds_dwordx4 v[208:209], off
	s_mov_b32 m0, s63
	v_lshl_add_u64 v[212:213], s[52:53], 0, v[188:189]
	global_load_lds_dwordx4 v186, s[64:65]
	s_add_i32 m0, s63, 0x2000
	s_nop 0
	global_load_lds_dwordx4 v190, s[64:65]
	v_lshl_add_u64 v[210:211], s[52:53], 0, v[184:185]
	s_mov_b32 m0, s26
	s_nop 0
	global_load_lds_dwordx4 v[210:211], off
	s_mov_b32 m0, s27
	s_nop 0
	global_load_lds_dwordx4 v[212:213], off
	s_waitcnt vmcnt(8)
	s_waitcnt lgkmcnt(0)
	s_barrier
	s_setprio 1
	s_waitcnt lgkmcnt(0)
	v_mfma_f32_16x16x32_bf16 v[60:63], v[124:127], v[160:163], v[60:63]
	v_mfma_f32_16x16x32_bf16 v[56:59], v[136:139], v[160:163], v[56:59]
	v_mfma_f32_16x16x32_bf16 v[44:47], v[124:127], v[168:171], v[44:47]
	v_mfma_f32_16x16x32_bf16 v[40:43], v[136:139], v[168:171], v[40:43]
	v_mfma_f32_16x16x32_bf16 v[28:31], v[124:127], v[176:179], v[28:31]
	v_mfma_f32_16x16x32_bf16 v[24:27], v[136:139], v[176:179], v[24:27]
	v_mfma_f32_16x16x32_bf16 v[12:15], v[124:127], v[198:201], v[12:15]
	v_mfma_f32_16x16x32_bf16 v[8:11], v[136:139], v[198:201], v[8:11]
	v_mfma_f32_16x16x32_bf16 v[60:63], v[132:135], v[164:167], v[60:63]
	v_mfma_f32_16x16x32_bf16 v[56:59], v[140:143], v[164:167], v[56:59]
	v_mfma_f32_16x16x32_bf16 v[44:47], v[132:135], v[172:175], v[44:47]
	v_mfma_f32_16x16x32_bf16 v[40:43], v[140:143], v[172:175], v[40:43]
	v_mfma_f32_16x16x32_bf16 v[28:31], v[132:135], v[180:183], v[28:31]
	v_mfma_f32_16x16x32_bf16 v[24:27], v[140:143], v[180:183], v[24:27]
	v_mfma_f32_16x16x32_bf16 v[12:15], v[132:135], v[202:205], v[12:15]
	v_mfma_f32_16x16x32_bf16 v[8:11], v[140:143], v[202:205], v[8:11]
	s_setprio 0
	s_setprio 1
	v_mfma_f32_16x16x32_bf16 v[52:55], v[144:147], v[160:163], v[52:55]
	v_mfma_f32_16x16x32_bf16 v[48:51], v[152:155], v[160:163], v[48:51]
	v_mfma_f32_16x16x32_bf16 v[36:39], v[144:147], v[168:171], v[36:39]
	v_mfma_f32_16x16x32_bf16 v[32:35], v[152:155], v[168:171], v[32:35]
	v_mfma_f32_16x16x32_bf16 v[20:23], v[144:147], v[176:179], v[20:23]
	v_mfma_f32_16x16x32_bf16 v[16:19], v[152:155], v[176:179], v[16:19]
	v_mfma_f32_16x16x32_bf16 v[4:7], v[144:147], v[198:201], v[4:7]
	v_mfma_f32_16x16x32_bf16 v[0:3], v[152:155], v[198:201], v[0:3]
	v_mfma_f32_16x16x32_bf16 v[52:55], v[148:151], v[164:167], v[52:55]
	v_mfma_f32_16x16x32_bf16 v[48:51], v[156:159], v[164:167], v[48:51]
	v_mfma_f32_16x16x32_bf16 v[36:39], v[148:151], v[172:175], v[36:39]
	v_mfma_f32_16x16x32_bf16 v[32:35], v[156:159], v[172:175], v[32:35]
	v_mfma_f32_16x16x32_bf16 v[20:23], v[148:151], v[180:183], v[20:23]
	v_mfma_f32_16x16x32_bf16 v[16:19], v[156:159], v[180:183], v[16:19]
	v_mfma_f32_16x16x32_bf16 v[4:7], v[148:151], v[202:205], v[4:7]
	v_mfma_f32_16x16x32_bf16 v[0:3], v[156:159], v[202:205], v[0:3]
	s_setprio 0
	s_barrier
; #define PG8_STAGE(bufoff, gbase, voff) do { _Pragma("unroll") for (int _i = 0; _i < 2; ++_i) \
;         __builtin_amdgcn_global_load_lds((const unsigned*)((const char*)(gbase) + (voff)[_i]), (PG8_LAS unsigned*)(lds + (bufoff) + ldsw + _i * 8192), 16, 0, 0); } while (0)
; #define PG8_LDA(dst, b, h) do { _Pragma("unroll") for (int m = 0; m < 4; ++m) _Pragma("unroll") for (int k = 0; k < 2; ++k) dst[m][k] = *(const PG8_LAS bf16x8*)(lds + PG8_SA(b, h) + aoff + m * 2048 + k * 1024); } while (0)
; #define PG8_LDB(dst, b, h) do { _Pragma("unroll") for (int n = 0; n < 2; ++n) _Pragma("unroll") for (int k = 0; k < 2; ++k) dst[n][k] = *(const PG8_LAS bf16x8*)(lds + PG8_SB(b, h) + boff + n * 2048 + k * 1024); } while (0)
; #define PG8_MMA(ai, bj, At, Bt) do { __builtin_amdgcn_s_setprio(1); _Pragma("unroll") for (int m = 0; m < 4; ++m) _Pragma("unroll") for (int n = 0; n < 2; ++n) _Pragma("unroll") for (int k = 0; k < 2; ++k) \
;         acc[ai][bj][m][n] = __builtin_amdgcn_mfma_f32_16x16x32_bf16(Bt[n][k], At[m][k], acc[ai][bj][m][n], 0, 0, 0); __builtin_amdgcn_s_setprio(0); } while (0)
; #define PG8_WAIT_V(n) asm volatile("s_waitcnt vmcnt(" #n ")" ::: "memory")
; #define PG8_WAIT_L(n) asm volatile("s_waitcnt lgkmcnt(" #n ")" ::: "memory")
; #define PG8_BAR __builtin_amdgcn_s_barrier()
; #define PG8_SCHED __builtin_amdgcn_sched_barrier(0)
; template <class Epi, class Sched, bool ALIGN_EPI = false, bool SP2 = false>
; __device__ __forceinline__ void gemm_phase(PG8_LAS unsigned char* lds, const Gemm g, const Sched& S, const Epi& E) {
;     ...
;             PG8_LDB(B0, 1, 0); PG8_LDB(B1, 1, 1); PG8_SCHED; PG8_LDA(At, 1, 0); PG8_STAGE(PG8_SA(0, 1), a2 + hstep, voffA);
;             PG8_WAIT_V(8); PG8_WAIT_L(0); PG8_BAR; PG8_MMA(0, 0, At, B0); PG8_MMA(0, 1, At, B1); PG8_BAR; PG8_SCHED;
	s_add_i32 s63, 0, 0x18000
	s_add_i32 s64, 0, 0x1c000
	v_add_u32_e32 v140, s63, v232
	v_add_u32_e32 v156, s64, v232
	ds_read_b128 v[124:127], v140
	ds_read_b128 v[132:135], v140 offset:1024
	ds_read_b128 v[136:139], v140 offset:2048
	ds_read_b128 v[140:143], v140 offset:3072
	ds_read_b128 v[144:147], v156
	ds_read_b128 v[148:151], v156 offset:1024
	ds_read_b128 v[152:155], v156 offset:2048
	ds_read_b128 v[156:159], v156 offset:3072
	s_add_u32 s52, s52, 0x40000
	s_addc_u32 s53, s53, 0
	s_mov_b32 m0, s28
	ds_read_b128 v[160:163], v236 offset:32768
	ds_read_b128 v[164:167], v236 offset:33792
	ds_read_b128 v[168:171], v236 offset:34816
	ds_read_b128 v[172:175], v236 offset:35840
	ds_read_b128 v[176:179], v236 offset:36864
	ds_read_b128 v[180:183], v236 offset:37888
	ds_read_b128 v[198:201], v236 offset:38912
	ds_read_b128 v[202:205], v236 offset:39936
	global_load_lds_dwordx4 v184, s[52:53]
	v_lshl_add_u64 v[214:215], s[52:53], 0, v[188:189]
	s_mov_b32 m0, s29
	s_nop 0
	global_load_lds_dwordx4 v[214:215], off
	s_waitcnt vmcnt(8)
	s_waitcnt lgkmcnt(0)
	s_barrier
	s_setprio 1
	s_waitcnt lgkmcnt(0)
	v_mfma_f32_16x16x32_bf16 v[128:131], v[124:127], v[160:163], v[128:131]
	v_mfma_f32_16x16x32_bf16 v[120:123], v[136:139], v[160:163], v[120:123]
	v_mfma_f32_16x16x32_bf16 v[108:111], v[124:127], v[168:171], v[108:111]
	v_mfma_f32_16x16x32_bf16 v[104:107], v[136:139], v[168:171], v[104:107]
	v_mfma_f32_16x16x32_bf16 v[92:95], v[124:127], v[176:179], v[92:95]
	v_mfma_f32_16x16x32_bf16 v[88:91], v[136:139], v[176:179], v[88:91]
	v_mfma_f32_16x16x32_bf16 v[76:79], v[124:127], v[198:201], v[76:79]
	v_mfma_f32_16x16x32_bf16 v[72:75], v[136:139], v[198:201], v[72:75]
	v_mfma_f32_16x16x32_bf16 v[128:131], v[132:135], v[164:167], v[128:131]
	v_mfma_f32_16x16x32_bf16 v[120:123], v[140:143], v[164:167], v[120:123]
	v_mfma_f32_16x16x32_bf16 v[108:111], v[132:135], v[172:175], v[108:111]
	v_mfma_f32_16x16x32_bf16 v[104:107], v[140:143], v[172:175], v[104:107]
	v_mfma_f32_16x16x32_bf16 v[92:95], v[132:135], v[180:183], v[92:95]
	v_mfma_f32_16x16x32_bf16 v[88:91], v[140:143], v[180:183], v[88:91]
	v_mfma_f32_16x16x32_bf16 v[76:79], v[132:135], v[202:205], v[76:79]
	v_mfma_f32_16x16x32_bf16 v[72:75], v[140:143], v[202:205], v[72:75]
	s_setprio 0
	s_setprio 1
	v_mfma_f32_16x16x32_bf16 v[116:119], v[144:147], v[160:163], v[116:119]
	v_mfma_f32_16x16x32_bf16 v[112:115], v[152:155], v[160:163], v[112:115]
	v_mfma_f32_16x16x32_bf16 v[100:103], v[144:147], v[168:171], v[100:103]
	v_mfma_f32_16x16x32_bf16 v[96:99], v[152:155], v[168:171], v[96:99]
	v_mfma_f32_16x16x32_bf16 v[84:87], v[144:147], v[176:179], v[84:87]
	v_mfma_f32_16x16x32_bf16 v[80:83], v[152:155], v[176:179], v[80:83]
	v_mfma_f32_16x16x32_bf16 v[68:71], v[144:147], v[198:201], v[68:71]
	v_mfma_f32_16x16x32_bf16 v[64:67], v[152:155], v[198:201], v[64:67]
	v_mfma_f32_16x16x32_bf16 v[116:119], v[148:151], v[164:167], v[116:119]
	v_mfma_f32_16x16x32_bf16 v[112:115], v[156:159], v[164:167], v[112:115]
	v_mfma_f32_16x16x32_bf16 v[100:103], v[148:151], v[172:175], v[100:103]
	v_mfma_f32_16x16x32_bf16 v[96:99], v[156:159], v[172:175], v[96:99]
	v_mfma_f32_16x16x32_bf16 v[84:87], v[148:151], v[180:183], v[84:87]
	v_mfma_f32_16x16x32_bf16 v[80:83], v[156:159], v[180:183], v[80:83]
	v_mfma_f32_16x16x32_bf16 v[68:71], v[148:151], v[202:205], v[68:71]
	v_mfma_f32_16x16x32_bf16 v[64:67], v[156:159], v[202:205], v[64:67]
	s_setprio 0
	s_barrier
; #define PG8_STAGE(bufoff, gbase, voff) do { _Pragma("unroll") for (int _i = 0; _i < 2; ++_i) \
;         __builtin_amdgcn_global_load_lds((const unsigned*)((const char*)(gbase) + (voff)[_i]), (PG8_LAS unsigned*)(lds + (bufoff) + ldsw + _i * 8192), 16, 0, 0); } while (0)
; #define PG8_LDA(dst, b, h) do { _Pragma("unroll") for (int m = 0; m < 4; ++m) _Pragma("unroll") for (int k = 0; k < 2; ++k) dst[m][k] = *(const PG8_LAS bf16x8*)(lds + PG8_SA(b, h) + aoff + m * 2048 + k * 1024); } while (0)
; #define PG8_MMA(ai, bj, At, Bt) do { __builtin_amdgcn_s_setprio(1); _Pragma("unroll") for (int m = 0; m < 4; ++m) _Pragma("unroll") for (int n = 0; n < 2; ++n) _Pragma("unroll") for (int k = 0; k < 2; ++k) \
;         acc[ai][bj][m][n] = __builtin_amdgcn_mfma_f32_16x16x32_bf16(Bt[n][k], At[m][k], acc[ai][bj][m][n], 0, 0, 0); __builtin_amdgcn_s_setprio(0); } while (0)
; #define PG8_WAIT_V(n) asm volatile("s_waitcnt vmcnt(" #n ")" ::: "memory")
; #define PG8_WAIT_L(n) asm volatile("s_waitcnt lgkmcnt(" #n ")" ::: "memory")
; #define PG8_BAR __builtin_amdgcn_s_barrier()
; #define PG8_SCHED __builtin_amdgcn_sched_barrier(0)
; template <class Epi, class Sched, bool ALIGN_EPI = false, bool SP2 = false>
; __device__ __forceinline__ void gemm_phase(PG8_LAS unsigned char* lds, const Gemm g, const Sched& S, const Epi& E) {
;     ...
;             PG8_LDA(At, 1, 1); PG8_STAGE(PG8_SB(1, 0), b3, voffB); PG8_STAGE(PG8_SB(1, 1), b3 + hstep, voffB); PG8_STAGE(PG8_SA(1, 0), a3, voffA);
;             PG8_WAIT_V(8); PG8_WAIT_L(0); PG8_BAR; PG8_MMA(1, 0, At, B0); PG8_MMA(1, 1, At, B1); PG8_BAR; PG8_SCHED;
;     ...
;         if constexpr (ALIGN_EPI) { if (wr == 0) PG8_BAR; }
	s_add_i32 s52, s63, s25
	v_lshl_add_u64 v[206:207], v[206:207], 0, s[18:19]
	s_mov_b32 m0, s52
	ds_read_b128 v[160:163], v236 offset:49152
	ds_read_b128 v[164:167], v236 offset:50176
	ds_read_b128 v[168:171], v236 offset:51200
	ds_read_b128 v[172:175], v236 offset:52224
	ds_read_b128 v[176:179], v236 offset:53248
	ds_read_b128 v[180:183], v236 offset:54272
	ds_read_b128 v[198:201], v236 offset:55296
	ds_read_b128 v[202:205], v236 offset:56320
	global_load_lds_dwordx4 v[206:207], off
	s_add_i32 m0, s52, 0x2000
	s_add_u32 s50, s50, 0x40080
	v_lshl_add_u64 v[206:207], v[208:209], 0, s[18:19]
	s_addc_u32 s51, s51, 0
	s_add_i32 s52, s64, s25
	global_load_lds_dwordx4 v[206:207], off
	s_mov_b32 m0, s52
	s_nop 0
	global_load_lds_dwordx4 v186, s[50:51]
	s_add_i32 m0, s52, 0x2000
	s_nop 0
	global_load_lds_dwordx4 v190, s[50:51]
	v_lshl_add_u64 v[206:207], v[210:211], 0, s[18:19]
	s_mov_b32 m0, s31
	s_nop 0
	global_load_lds_dwordx4 v[206:207], off
	v_lshl_add_u64 v[206:207], v[212:213], 0, s[18:19]
	s_mov_b32 m0, s33
	s_nop 0
	global_load_lds_dwordx4 v[206:207], off
	s_waitcnt vmcnt(8)
	s_waitcnt lgkmcnt(0)
	s_barrier
	s_setprio 1
	s_waitcnt lgkmcnt(0)
	v_mfma_f32_16x16x32_bf16 v[60:63], v[124:127], v[160:163], v[60:63]
	v_mfma_f32_16x16x32_bf16 v[56:59], v[136:139], v[160:163], v[56:59]
	v_mfma_f32_16x16x32_bf16 v[44:47], v[124:127], v[168:171], v[44:47]
	v_mfma_f32_16x16x32_bf16 v[40:43], v[136:139], v[168:171], v[40:43]
	v_mfma_f32_16x16x32_bf16 v[28:31], v[124:127], v[176:179], v[28:31]
	v_mfma_f32_16x16x32_bf16 v[24:27], v[136:139], v[176:179], v[24:27]
	v_mfma_f32_16x16x32_bf16 v[12:15], v[124:127], v[198:201], v[12:15]
	v_mfma_f32_16x16x32_bf16 v[8:11], v[136:139], v[198:201], v[8:11]
	v_mfma_f32_16x16x32_bf16 v[60:63], v[132:135], v[164:167], v[60:63]
	v_mfma_f32_16x16x32_bf16 v[56:59], v[140:143], v[164:167], v[56:59]
	v_mfma_f32_16x16x32_bf16 v[44:47], v[132:135], v[172:175], v[44:47]
	v_mfma_f32_16x16x32_bf16 v[40:43], v[140:143], v[172:175], v[40:43]
	v_mfma_f32_16x16x32_bf16 v[28:31], v[132:135], v[180:183], v[28:31]
	v_mfma_f32_16x16x32_bf16 v[24:27], v[140:143], v[180:183], v[24:27]
	v_mfma_f32_16x16x32_bf16 v[12:15], v[132:135], v[202:205], v[12:15]
	v_mfma_f32_16x16x32_bf16 v[8:11], v[140:143], v[202:205], v[8:11]
	s_setprio 0
	s_setprio 1
	v_mfma_f32_16x16x32_bf16 v[52:55], v[144:147], v[160:163], v[52:55]
	v_mfma_f32_16x16x32_bf16 v[48:51], v[152:155], v[160:163], v[48:51]
	v_mfma_f32_16x16x32_bf16 v[36:39], v[144:147], v[168:171], v[36:39]
	v_mfma_f32_16x16x32_bf16 v[32:35], v[152:155], v[168:171], v[32:35]
	v_mfma_f32_16x16x32_bf16 v[20:23], v[144:147], v[176:179], v[20:23]
	v_mfma_f32_16x16x32_bf16 v[16:19], v[152:155], v[176:179], v[16:19]
	v_mfma_f32_16x16x32_bf16 v[4:7], v[144:147], v[198:201], v[4:7]
	v_mfma_f32_16x16x32_bf16 v[0:3], v[152:155], v[198:201], v[0:3]
	v_mfma_f32_16x16x32_bf16 v[52:55], v[148:151], v[164:167], v[52:55]
	v_mfma_f32_16x16x32_bf16 v[48:51], v[156:159], v[164:167], v[48:51]
	v_mfma_f32_16x16x32_bf16 v[36:39], v[148:151], v[172:175], v[36:39]
	v_mfma_f32_16x16x32_bf16 v[32:35], v[156:159], v[172:175], v[32:35]
	v_mfma_f32_16x16x32_bf16 v[20:23], v[148:151], v[180:183], v[20:23]
	v_mfma_f32_16x16x32_bf16 v[16:19], v[156:159], v[180:183], v[16:19]
	v_mfma_f32_16x16x32_bf16 v[4:7], v[148:151], v[202:205], v[4:7]
	v_mfma_f32_16x16x32_bf16 v[0:3], v[156:159], v[202:205], v[0:3]
	s_setprio 0
	s_add_i32 s62, s62, 2
	s_add_u32 s48, s48, 0x100
	s_addc_u32 s49, s49, 0
	s_add_u32 s60, s60, 0x100
	s_addc_u32 s61, s61, 0
	s_cmp_gt_u32 s62, 13
	s_barrier
	s_cbranch_scc0 .LBB0_393
	s_and_b64 vcc, exec, s[20:21]
	s_cbranch_vccz .LBB0_396
	s_barrier

; #define PG8_STAGE(bufoff, gbase, voff) do { _Pragma("unroll") for (int _i = 0; _i < 2; ++_i) \
;         __builtin_amdgcn_global_load_lds((const unsigned*)((const char*)(gbase) + (voff)[_i]), (PG8_LAS unsigned*)(lds + (bufoff) + ldsw + _i * 8192), 16, 0, 0); } while (0)
; #define PG8_LDA(dst, b, h) do { _Pragma("unroll") for (int m = 0; m < 4; ++m) _Pragma("unroll") for (int k = 0; k < 2; ++k) dst[m][k] = *(const PG8_LAS bf16x8*)(lds + PG8_SA(b, h) + aoff + m * 2048 + k * 1024); } while (0)
; #define PG8_MMA(ai, bj, At, Bt) do { __builtin_amdgcn_s_setprio(1); _Pragma("unroll") for (int m = 0; m < 4; ++m) _Pragma("unroll") for (int n = 0; n < 2; ++n) _Pragma("unroll") for (int k = 0; k < 2; ++k) \
;         acc[ai][bj][m][n] = __builtin_amdgcn_mfma_f32_16x16x32_bf16(Bt[n][k], At[m][k], acc[ai][bj][m][n], 0, 0, 0); __builtin_amdgcn_s_setprio(0); } while (0)
; #define PG8_WAIT_V(n) asm volatile("s_waitcnt vmcnt(" #n ")" ::: "memory")
; #define PG8_WAIT_L(n) asm volatile("s_waitcnt lgkmcnt(" #n ")" ::: "memory")
; #define PG8_BAR __builtin_amdgcn_s_barrier()
; #define PG8_SCHED __builtin_amdgcn_sched_barrier(0)
; template <class Epi, class Sched, bool ALIGN_EPI = false, bool SP2 = false>
; __device__ __forceinline__ void gemm_phase(PG8_LAS unsigned char* lds, const Gemm g, const Sched& S, const Epi& E) {
;     ...
;             PG8_WAIT_V(8); PG8_WAIT_L(0); PG8_BAR; PG8_MMA(0, 0, At, B0); PG8_MMA(0, 1, At, B1); PG8_BAR; PG8_SCHED;
;             PG8_LDA(At, 1, 1); PG8_STAGE(PG8_SB(1, 0), b3, voffB); PG8_STAGE(PG8_SB(1, 1), b3 + hstep, voffB); PG8_STAGE(PG8_SA(1, 0), a3, voffA);
;             PG8_WAIT_V(8); PG8_WAIT_L(0); PG8_BAR; PG8_MMA(1, 0, At, B0); PG8_MMA(1, 1, At, B1); PG8_BAR; PG8_SCHED;
.Lrsa_d_pl:
	s_waitcnt lgkmcnt(0)
	s_barrier
	s_setprio 1
	s_waitcnt lgkmcnt(0)
	v_mfma_f32_16x16x32_bf16 v[124:127], v[144:147], v[202:205], v[124:127]
	v_mfma_f32_16x16x32_bf16 v[116:119], v[178:181], v[202:205], v[116:119]
	v_mfma_f32_16x16x32_bf16 v[108:111], v[144:147], v[210:213], v[108:111]
	v_mfma_f32_16x16x32_bf16 v[100:103], v[178:181], v[210:213], v[100:103]
	v_mfma_f32_16x16x32_bf16 v[92:95], v[144:147], v[218:221], v[92:95]
	v_mfma_f32_16x16x32_bf16 v[84:87], v[178:181], v[218:221], v[84:87]
	v_mfma_f32_16x16x32_bf16 v[76:79], v[144:147], v[226:229], v[76:79]
	v_mfma_f32_16x16x32_bf16 v[68:71], v[178:181], v[226:229], v[68:71]
	v_mfma_f32_16x16x32_bf16 v[124:127], v[170:173], v[206:209], v[124:127]
	v_mfma_f32_16x16x32_bf16 v[116:119], v[182:185], v[206:209], v[116:119]
	v_mfma_f32_16x16x32_bf16 v[108:111], v[170:173], v[214:217], v[108:111]
	v_mfma_f32_16x16x32_bf16 v[100:103], v[182:185], v[214:217], v[100:103]
	v_mfma_f32_16x16x32_bf16 v[92:95], v[170:173], v[222:225], v[92:95]
	v_mfma_f32_16x16x32_bf16 v[84:87], v[182:185], v[222:225], v[84:87]
	v_mfma_f32_16x16x32_bf16 v[76:79], v[170:173], v[232:235], v[76:79]
	v_mfma_f32_16x16x32_bf16 v[68:71], v[182:185], v[232:235], v[68:71]
	s_setprio 0
	s_setprio 1
	v_mfma_f32_16x16x32_bf16 v[120:123], v[186:189], v[202:205], v[120:123]
	v_mfma_f32_16x16x32_bf16 v[112:115], v[194:197], v[202:205], v[112:115]
	v_mfma_f32_16x16x32_bf16 v[104:107], v[186:189], v[210:213], v[104:107]
	v_mfma_f32_16x16x32_bf16 v[96:99], v[194:197], v[210:213], v[96:99]
	v_mfma_f32_16x16x32_bf16 v[88:91], v[186:189], v[218:221], v[88:91]
	v_mfma_f32_16x16x32_bf16 v[80:83], v[194:197], v[218:221], v[80:83]
	v_mfma_f32_16x16x32_bf16 v[72:75], v[186:189], v[226:229], v[72:75]
	v_mfma_f32_16x16x32_bf16 v[64:67], v[194:197], v[226:229], v[64:67]
	v_mfma_f32_16x16x32_bf16 v[120:123], v[190:193], v[206:209], v[120:123]
	v_mfma_f32_16x16x32_bf16 v[112:115], v[198:201], v[206:209], v[112:115]
	v_mfma_f32_16x16x32_bf16 v[104:107], v[190:193], v[214:217], v[104:107]
	v_mfma_f32_16x16x32_bf16 v[96:99], v[198:201], v[214:217], v[96:99]
	v_mfma_f32_16x16x32_bf16 v[88:91], v[190:193], v[222:225], v[88:91]
	v_mfma_f32_16x16x32_bf16 v[80:83], v[198:201], v[222:225], v[80:83]
	v_mfma_f32_16x16x32_bf16 v[72:75], v[190:193], v[232:235], v[72:75]
	v_mfma_f32_16x16x32_bf16 v[64:67], v[198:201], v[232:235], v[64:67]
	s_setprio 0
	s_barrier
	s_add_i32 s46, s60, s25
	v_lshl_add_u64 v[150:151], v[150:151], 0, s[8:9]
	s_mov_b32 m0, s46
	ds_read_b128 v[202:205], v169 offset:49152
	ds_read_b128 v[206:209], v169 offset:50176
	ds_read_b128 v[210:213], v169 offset:51200
	ds_read_b128 v[214:217], v169 offset:52224
	ds_read_b128 v[218:221], v169 offset:53248
	ds_read_b128 v[222:225], v169 offset:54272
	ds_read_b128 v[226:229], v169 offset:55296
	ds_read_b128 v[232:235], v169 offset:56320
	global_load_lds_dwordx4 v[150:151], off
	s_add_i32 m0, s46, 0x2000
	s_add_u32 s44, s44, 0x40080
	v_lshl_add_u64 v[150:151], v[154:155], 0, s[8:9]
	s_addc_u32 s45, s45, 0
	s_add_i32 s46, s61, s25
	global_load_lds_dwordx4 v[150:151], off
	s_mov_b32 m0, s46
	s_nop 0
	global_load_lds_dwordx4 v130, s[44:45]
	s_add_i32 m0, s46, 0x2000
	s_nop 0
	global_load_lds_dwordx4 v134, s[44:45]
	v_lshl_add_u64 v[150:151], v[158:159], 0, s[8:9]
	s_mov_b32 m0, s48
	s_nop 0
	global_load_lds_dwordx4 v[150:151], off
	v_lshl_add_u64 v[150:151], v[162:163], 0, s[8:9]
	s_mov_b32 m0, s49
	s_nop 0
	global_load_lds_dwordx4 v[150:151], off
	s_waitcnt vmcnt(8)
	s_waitcnt lgkmcnt(0)
	s_barrier
	s_setprio 1
	s_waitcnt lgkmcnt(0)
	v_mfma_f32_16x16x32_bf16 v[60:63], v[144:147], v[202:205], v[60:63]
	v_mfma_f32_16x16x32_bf16 v[52:55], v[178:181], v[202:205], v[52:55]
	v_mfma_f32_16x16x32_bf16 v[44:47], v[144:147], v[210:213], v[44:47]
	v_mfma_f32_16x16x32_bf16 v[36:39], v[178:181], v[210:213], v[36:39]
	v_mfma_f32_16x16x32_bf16 v[28:31], v[144:147], v[218:221], v[28:31]
	v_mfma_f32_16x16x32_bf16 v[20:23], v[178:181], v[218:221], v[20:23]
	v_mfma_f32_16x16x32_bf16 v[12:15], v[144:147], v[226:229], v[12:15]
	v_mfma_f32_16x16x32_bf16 v[4:7], v[178:181], v[226:229], v[4:7]
	v_mfma_f32_16x16x32_bf16 v[60:63], v[170:173], v[206:209], v[60:63]
	v_mfma_f32_16x16x32_bf16 v[52:55], v[182:185], v[206:209], v[52:55]
	v_mfma_f32_16x16x32_bf16 v[44:47], v[170:173], v[214:217], v[44:47]
	v_mfma_f32_16x16x32_bf16 v[36:39], v[182:185], v[214:217], v[36:39]
	v_mfma_f32_16x16x32_bf16 v[28:31], v[170:173], v[222:225], v[28:31]
	v_mfma_f32_16x16x32_bf16 v[20:23], v[182:185], v[222:225], v[20:23]
	v_mfma_f32_16x16x32_bf16 v[12:15], v[170:173], v[232:235], v[12:15]
	v_mfma_f32_16x16x32_bf16 v[4:7], v[182:185], v[232:235], v[4:7]
	s_setprio 0
	s_setprio 1
	v_mfma_f32_16x16x32_bf16 v[56:59], v[186:189], v[202:205], v[56:59]
	v_mfma_f32_16x16x32_bf16 v[48:51], v[194:197], v[202:205], v[48:51]
	v_mfma_f32_16x16x32_bf16 v[40:43], v[186:189], v[210:213], v[40:43]
	v_mfma_f32_16x16x32_bf16 v[32:35], v[194:197], v[210:213], v[32:35]
	v_mfma_f32_16x16x32_bf16 v[24:27], v[186:189], v[218:221], v[24:27]
	v_mfma_f32_16x16x32_bf16 v[16:19], v[194:197], v[218:221], v[16:19]
	v_mfma_f32_16x16x32_bf16 v[8:11], v[186:189], v[226:229], v[8:11]
	v_mfma_f32_16x16x32_bf16 v[0:3], v[194:197], v[226:229], v[0:3]
	v_mfma_f32_16x16x32_bf16 v[56:59], v[190:193], v[206:209], v[56:59]
	v_mfma_f32_16x16x32_bf16 v[48:51], v[198:201], v[206:209], v[48:51]
	v_mfma_f32_16x16x32_bf16 v[40:43], v[190:193], v[214:217], v[40:43]
	v_mfma_f32_16x16x32_bf16 v[32:35], v[198:201], v[214:217], v[32:35]
	v_mfma_f32_16x16x32_bf16 v[24:27], v[190:193], v[222:225], v[24:27]
	v_mfma_f32_16x16x32_bf16 v[16:19], v[198:201], v[222:225], v[16:19]
	v_mfma_f32_16x16x32_bf16 v[8:11], v[190:193], v[232:235], v[8:11]
	v_mfma_f32_16x16x32_bf16 v[0:3], v[198:201], v[232:235], v[0:3]
	s_setprio 0
	s_add_i32 s59, s59, 2
	s_add_u32 s42, s42, 0x100
	s_addc_u32 s43, s43, 0
	s_add_u32 s57, s57, 0x100
	s_addc_u32 s58, s58, 0
	s_cmp_gt_u32 s59, 13
	s_barrier

; #define PG8_STAGE(bufoff, gbase, voff) do { _Pragma("unroll") for (int _i = 0; _i < 2; ++_i) \
;         __builtin_amdgcn_global_load_lds((const unsigned*)((const char*)(gbase) + (voff)[_i]), (PG8_LAS unsigned*)(lds + (bufoff) + ldsw + _i * 8192), 16, 0, 0); } while (0)
; #define PG8_LDA(dst, b, h) do { _Pragma("unroll") for (int m = 0; m < 4; ++m) _Pragma("unroll") for (int k = 0; k < 2; ++k) dst[m][k] = *(const PG8_LAS bf16x8*)(lds + PG8_SA(b, h) + aoff + m * 2048 + k * 1024); } while (0)
; #define PG8_MMA(ai, bj, At, Bt) do { __builtin_amdgcn_s_setprio(1); _Pragma("unroll") for (int m = 0; m < 4; ++m) _Pragma("unroll") for (int n = 0; n < 2; ++n) _Pragma("unroll") for (int k = 0; k < 2; ++k) \
;         acc[ai][bj][m][n] = __builtin_amdgcn_mfma_f32_16x16x32_bf16(Bt[n][k], At[m][k], acc[ai][bj][m][n], 0, 0, 0); __builtin_amdgcn_s_setprio(0); } while (0)
; #define PG8_WAIT_V(n) asm volatile("s_waitcnt vmcnt(" #n ")" ::: "memory")
; #define PG8_WAIT_L(n) asm volatile("s_waitcnt lgkmcnt(" #n ")" ::: "memory")
; #define PG8_BAR __builtin_amdgcn_s_barrier()
; #define PG8_SCHED __builtin_amdgcn_sched_barrier(0)
; template <class Epi, class Sched, bool ALIGN_EPI = false, bool SP2 = false>
; __device__ __forceinline__ void gemm_phase(PG8_LAS unsigned char* lds, const Gemm g, const Sched& S, const Epi& E) {
;     ...
;             PG8_WAIT_V(8); PG8_WAIT_L(0); PG8_BAR; PG8_MMA(0, 0, At, B0); PG8_MMA(0, 1, At, B1); PG8_BAR; PG8_SCHED;
;             PG8_LDA(At, 1, 1); PG8_STAGE(PG8_SB(1, 0), b3, voffB); PG8_STAGE(PG8_SB(1, 1), b3 + hstep, voffB); PG8_STAGE(PG8_SA(1, 0), a3, voffA);
;             PG8_WAIT_V(8); PG8_WAIT_L(0); PG8_BAR; PG8_MMA(1, 0, At, B0); PG8_MMA(1, 1, At, B1); PG8_BAR; PG8_SCHED;
;     ...
;         if constexpr (ALIGN_EPI) { if (wr == 0) PG8_BAR; }
.Lrsa_d:
	s_waitcnt lgkmcnt(0)
	s_barrier
	s_setprio 1
	s_waitcnt lgkmcnt(0)
	v_mfma_f32_16x16x32_bf16 v[124:127], v[144:147], v[202:205], v[124:127]
	v_mfma_f32_16x16x32_bf16 v[116:119], v[178:181], v[202:205], v[116:119]
	v_mfma_f32_16x16x32_bf16 v[108:111], v[144:147], v[210:213], v[108:111]
	v_mfma_f32_16x16x32_bf16 v[100:103], v[178:181], v[210:213], v[100:103]
	v_mfma_f32_16x16x32_bf16 v[92:95], v[144:147], v[218:221], v[92:95]
	v_mfma_f32_16x16x32_bf16 v[84:87], v[178:181], v[218:221], v[84:87]
	v_mfma_f32_16x16x32_bf16 v[76:79], v[144:147], v[226:229], v[76:79]
	v_mfma_f32_16x16x32_bf16 v[68:71], v[178:181], v[226:229], v[68:71]
	v_mfma_f32_16x16x32_bf16 v[124:127], v[170:173], v[206:209], v[124:127]
	v_mfma_f32_16x16x32_bf16 v[116:119], v[182:185], v[206:209], v[116:119]
	v_mfma_f32_16x16x32_bf16 v[108:111], v[170:173], v[214:217], v[108:111]
	v_mfma_f32_16x16x32_bf16 v[100:103], v[182:185], v[214:217], v[100:103]
	v_mfma_f32_16x16x32_bf16 v[92:95], v[170:173], v[222:225], v[92:95]
	v_mfma_f32_16x16x32_bf16 v[84:87], v[182:185], v[222:225], v[84:87]
	v_mfma_f32_16x16x32_bf16 v[76:79], v[170:173], v[232:235], v[76:79]
	v_mfma_f32_16x16x32_bf16 v[68:71], v[182:185], v[232:235], v[68:71]
	s_setprio 0
	s_setprio 1
	v_mfma_f32_16x16x32_bf16 v[120:123], v[186:189], v[202:205], v[120:123]
	v_mfma_f32_16x16x32_bf16 v[112:115], v[194:197], v[202:205], v[112:115]
	v_mfma_f32_16x16x32_bf16 v[104:107], v[186:189], v[210:213], v[104:107]
	v_mfma_f32_16x16x32_bf16 v[96:99], v[194:197], v[210:213], v[96:99]
	v_mfma_f32_16x16x32_bf16 v[88:91], v[186:189], v[218:221], v[88:91]
	v_mfma_f32_16x16x32_bf16 v[80:83], v[194:197], v[218:221], v[80:83]
	v_mfma_f32_16x16x32_bf16 v[72:75], v[186:189], v[226:229], v[72:75]
	v_mfma_f32_16x16x32_bf16 v[64:67], v[194:197], v[226:229], v[64:67]
	v_mfma_f32_16x16x32_bf16 v[120:123], v[190:193], v[206:209], v[120:123]
	v_mfma_f32_16x16x32_bf16 v[112:115], v[198:201], v[206:209], v[112:115]
	v_mfma_f32_16x16x32_bf16 v[104:107], v[190:193], v[214:217], v[104:107]
	v_mfma_f32_16x16x32_bf16 v[96:99], v[198:201], v[214:217], v[96:99]
	v_mfma_f32_16x16x32_bf16 v[88:91], v[190:193], v[222:225], v[88:91]
	v_mfma_f32_16x16x32_bf16 v[80:83], v[198:201], v[222:225], v[80:83]
	v_mfma_f32_16x16x32_bf16 v[72:75], v[190:193], v[232:235], v[72:75]
	v_mfma_f32_16x16x32_bf16 v[64:67], v[198:201], v[232:235], v[64:67]
	s_setprio 0
	s_barrier
	s_add_i32 s46, s60, s25
	v_lshl_add_u64 v[150:151], v[150:151], 0, s[8:9]
	s_mov_b32 m0, s46
	ds_read_b128 v[202:205], v169 offset:49152
	ds_read_b128 v[206:209], v169 offset:50176
	ds_read_b128 v[210:213], v169 offset:51200
	ds_read_b128 v[214:217], v169 offset:52224
	ds_read_b128 v[218:221], v169 offset:53248
	ds_read_b128 v[222:225], v169 offset:54272
	ds_read_b128 v[226:229], v169 offset:55296
	ds_read_b128 v[232:235], v169 offset:56320
	global_load_lds_dwordx4 v[150:151], off
	s_add_i32 m0, s46, 0x2000
	s_add_u32 s44, s44, 0x40080
	v_lshl_add_u64 v[150:151], v[154:155], 0, s[8:9]
	s_addc_u32 s45, s45, 0
	s_add_i32 s46, s61, s25
	global_load_lds_dwordx4 v[150:151], off
	s_mov_b32 m0, s46
	s_nop 0
	global_load_lds_dwordx4 v130, s[44:45]
	s_add_i32 m0, s46, 0x2000
	s_nop 0
	global_load_lds_dwordx4 v134, s[44:45]
	v_lshl_add_u64 v[150:151], v[158:159], 0, s[8:9]
	s_mov_b32 m0, s48
	s_nop 0
	global_load_lds_dwordx4 v[150:151], off
	v_lshl_add_u64 v[150:151], v[162:163], 0, s[8:9]
	s_mov_b32 m0, s49
	s_nop 0
	global_load_lds_dwordx4 v[150:151], off
	s_waitcnt vmcnt(8)
	s_waitcnt lgkmcnt(0)
	s_barrier
	s_setprio 1
	s_waitcnt lgkmcnt(0)
	v_mfma_f32_16x16x32_bf16 v[60:63], v[144:147], v[202:205], v[60:63]
	v_mfma_f32_16x16x32_bf16 v[52:55], v[178:181], v[202:205], v[52:55]
	v_mfma_f32_16x16x32_bf16 v[44:47], v[144:147], v[210:213], v[44:47]
	v_mfma_f32_16x16x32_bf16 v[36:39], v[178:181], v[210:213], v[36:39]
	v_mfma_f32_16x16x32_bf16 v[28:31], v[144:147], v[218:221], v[28:31]
	v_mfma_f32_16x16x32_bf16 v[20:23], v[178:181], v[218:221], v[20:23]
	v_mfma_f32_16x16x32_bf16 v[12:15], v[144:147], v[226:229], v[12:15]
	v_mfma_f32_16x16x32_bf16 v[4:7], v[178:181], v[226:229], v[4:7]
	v_mfma_f32_16x16x32_bf16 v[60:63], v[170:173], v[206:209], v[60:63]
	v_mfma_f32_16x16x32_bf16 v[52:55], v[182:185], v[206:209], v[52:55]
	v_mfma_f32_16x16x32_bf16 v[44:47], v[170:173], v[214:217], v[44:47]
	v_mfma_f32_16x16x32_bf16 v[36:39], v[182:185], v[214:217], v[36:39]
	v_mfma_f32_16x16x32_bf16 v[28:31], v[170:173], v[222:225], v[28:31]
	v_mfma_f32_16x16x32_bf16 v[20:23], v[182:185], v[222:225], v[20:23]
	v_mfma_f32_16x16x32_bf16 v[12:15], v[170:173], v[232:235], v[12:15]
	v_mfma_f32_16x16x32_bf16 v[4:7], v[182:185], v[232:235], v[4:7]
	s_setprio 0
	s_setprio 1
	v_mfma_f32_16x16x32_bf16 v[56:59], v[186:189], v[202:205], v[56:59]
	v_mfma_f32_16x16x32_bf16 v[48:51], v[194:197], v[202:205], v[48:51]
	v_mfma_f32_16x16x32_bf16 v[40:43], v[186:189], v[210:213], v[40:43]
	v_mfma_f32_16x16x32_bf16 v[32:35], v[194:197], v[210:213], v[32:35]
	v_mfma_f32_16x16x32_bf16 v[24:27], v[186:189], v[218:221], v[24:27]
	v_mfma_f32_16x16x32_bf16 v[16:19], v[194:197], v[218:221], v[16:19]
	v_mfma_f32_16x16x32_bf16 v[8:11], v[186:189], v[226:229], v[8:11]
	v_mfma_f32_16x16x32_bf16 v[0:3], v[194:197], v[226:229], v[0:3]
	v_mfma_f32_16x16x32_bf16 v[56:59], v[190:193], v[206:209], v[56:59]
	v_mfma_f32_16x16x32_bf16 v[48:51], v[198:201], v[206:209], v[48:51]
	v_mfma_f32_16x16x32_bf16 v[40:43], v[190:193], v[214:217], v[40:43]
	v_mfma_f32_16x16x32_bf16 v[32:35], v[198:201], v[214:217], v[32:35]
	v_mfma_f32_16x16x32_bf16 v[24:27], v[190:193], v[222:225], v[24:27]
	v_mfma_f32_16x16x32_bf16 v[16:19], v[198:201], v[222:225], v[16:19]
	v_mfma_f32_16x16x32_bf16 v[8:11], v[190:193], v[232:235], v[8:11]
	v_mfma_f32_16x16x32_bf16 v[0:3], v[198:201], v[232:235], v[0:3]
	s_setprio 0
	s_add_i32 s59, s59, 2
	s_add_u32 s42, s42, 0x100
	s_addc_u32 s43, s43, 0
	s_add_u32 s57, s57, 0x100
	s_addc_u32 s58, s58, 0
	s_cmp_gt_u32 s59, 13
	s_barrier
	s_cbranch_scc0 .LBB0_482
	s_and_b64 vcc, exec, s[12:13]
	s_cbranch_vccz .LBB0_485
	s_barrier

; #define PG8_STAGE(bufoff, gbase, voff) do { _Pragma("unroll") for (int _i = 0; _i < 2; ++_i) \
;         __builtin_amdgcn_global_load_lds((const unsigned*)((const char*)(gbase) + (voff)[_i]), (PG8_LAS unsigned*)(lds + (bufoff) + ldsw + _i * 8192), 16, 0, 0); } while (0)
; #define PG8_LDA(dst, b, h) do { _Pragma("unroll") for (int m = 0; m < 4; ++m) _Pragma("unroll") for (int k = 0; k < 2; ++k) dst[m][k] = *(const PG8_LAS bf16x8*)(lds + PG8_SA(b, h) + aoff + m * 2048 + k * 1024); } while (0)
; #define PG8_LDB(dst, b, h) do { _Pragma("unroll") for (int n = 0; n < 2; ++n) _Pragma("unroll") for (int k = 0; k < 2; ++k) dst[n][k] = *(const PG8_LAS bf16x8*)(lds + PG8_SB(b, h) + boff + n * 2048 + k * 1024); } while (0)
; #define PG8_WAIT_V(n) asm volatile("s_waitcnt vmcnt(" #n ")" ::: "memory")
; #define PG8_WAIT_L(n) asm volatile("s_waitcnt lgkmcnt(" #n ")" ::: "memory")
; #define PG8_BAR __builtin_amdgcn_s_barrier()
; #define PG8_SCHED __builtin_amdgcn_sched_barrier(0)
; template <class Epi, class Sched, bool ALIGN_EPI = false, bool SP2 = false>
; __device__ __forceinline__ void gemm_phase(PG8_LAS unsigned char* lds, const Gemm g, const Sched& S, const Epi& E) {
;     ...
;         const bool has_next = S.next(ui + 1, nxt);
;         const char* nA = has_next ? (const char*)g.A + (size_t)nxt.pm * tstep : cA; const char* nB = has_next ? (const char*)g.Bt + (size_t)nxt.pn * tstep : cB;
;         for (int t = 0; t < nt; t += 2) {
;             const bool last = (t == nt - 2);
;             const char* a1 = cA + (size_t)(t + 1) * kstep;
;             const char* a2 = last ? nA : cA + (size_t)(t + 2) * kstep; const char* b2 = last ? nB : cB + (size_t)(t + 2) * kstep;
;             const char* a3 = a2 + kstep; const char* b3 = b2 + kstep;
;             if (last && has_next) S.a_ready(nxt);
;             if constexpr (SP2) {
;             PG8_LDB(B0, 0, 0); PG8_LDB(B1, 0, 1); PG8_SCHED; PG8_LDA(At, 0, 0); PG8_STAGE(PG8_SA(1, 1), a1 + hstep, voffA);
;             PG8_WAIT_V(8); PG8_WAIT_L(0); PG8_BAR; PG8_MMA(0, 0, At, B0); PG8_MMA(0, 1, At, B1); PG8_BAR; PG8_SCHED;
;             PG8_LDA(At, 0, 1); PG8_STAGE(PG8_SB(0, 0), b2, voffB); PG8_STAGE(PG8_SB(0, 1), b2 + hstep, voffB); PG8_STAGE(PG8_SA(0, 0), a2, voffA);
;             PG8_WAIT_V(8); PG8_WAIT_L(0); PG8_BAR; PG8_MMA(1, 0, At, B0); PG8_MMA(1, 1, At, B1); PG8_BAR; PG8_SCHED;
.LBB0_569:
	s_add_u32 s42, s42, 0xb0080
	s_addc_u32 s43, s43, 0
	s_add_u32 s56, s44, 0x100
	s_addc_u32 s57, s45, 0
	s_mov_b32 s58, -2
	s_waitcnt lgkmcnt(0)
	ds_read_b128 v[124:127], v234
	ds_read_b128 v[132:135], v234 offset:1024
	ds_read_b128 v[136:139], v234 offset:2048
	ds_read_b128 v[140:143], v234 offset:3072
	ds_read_b128 v[144:147], v235
	ds_read_b128 v[148:151], v235 offset:1024
	ds_read_b128 v[152:155], v235 offset:2048
	ds_read_b128 v[156:159], v235 offset:3072
	s_add_u32 s44, s42, 0xfff50080
	s_addc_u32 s45, s43, -1
	s_cmp_eq_u32 s58, 40
	s_cselect_b32 s47, s39, s45
	s_cselect_b32 s46, s38, s44
	s_cselect_b32 s45, s41, s57
	s_cselect_b32 s44, s40, s56
	s_add_i32 m0, s26, 0xc000
	ds_read_b128 v[160:163], v236
	ds_read_b128 v[164:167], v236 offset:1024
	ds_read_b128 v[168:171], v236 offset:2048
	ds_read_b128 v[172:175], v236 offset:3072
	ds_read_b128 v[176:179], v236 offset:4096
	ds_read_b128 v[180:183], v236 offset:5120
	ds_read_b128 v[198:201], v236 offset:6144
	ds_read_b128 v[202:205], v236 offset:7168
	global_load_lds_dwordx4 v192, s[42:43]
	s_add_i32 m0, s26, 0xe000
	s_nop 0
	global_load_lds_dwordx4 v194, s[42:43]
	s_waitcnt vmcnt(8)
	s_waitcnt lgkmcnt(0)
	s_barrier
	s_setprio 1
	s_waitcnt lgkmcnt(0)
	v_mfma_f32_16x16x32_bf16 v[128:131], v[124:127], v[160:163], 0
	v_mfma_f32_16x16x32_bf16 v[120:123], v[136:139], v[160:163], 0
	v_mfma_f32_16x16x32_bf16 v[108:111], v[124:127], v[168:171], 0
	v_mfma_f32_16x16x32_bf16 v[104:107], v[136:139], v[168:171], 0
	v_mfma_f32_16x16x32_bf16 v[92:95], v[124:127], v[176:179], 0
	v_mfma_f32_16x16x32_bf16 v[88:91], v[136:139], v[176:179], 0
	v_mfma_f32_16x16x32_bf16 v[76:79], v[124:127], v[198:201], 0
	v_mfma_f32_16x16x32_bf16 v[72:75], v[136:139], v[198:201], 0
	v_mfma_f32_16x16x32_bf16 v[128:131], v[132:135], v[164:167], v[128:131]
	v_mfma_f32_16x16x32_bf16 v[120:123], v[140:143], v[164:167], v[120:123]
	v_mfma_f32_16x16x32_bf16 v[108:111], v[132:135], v[172:175], v[108:111]
	v_mfma_f32_16x16x32_bf16 v[104:107], v[140:143], v[172:175], v[104:107]
	v_mfma_f32_16x16x32_bf16 v[92:95], v[132:135], v[180:183], v[92:95]
	v_mfma_f32_16x16x32_bf16 v[88:91], v[140:143], v[180:183], v[88:91]
	v_mfma_f32_16x16x32_bf16 v[76:79], v[132:135], v[202:205], v[76:79]
	v_mfma_f32_16x16x32_bf16 v[72:75], v[140:143], v[202:205], v[72:75]
	s_setprio 0
	s_setprio 1
	v_mfma_f32_16x16x32_bf16 v[116:119], v[144:147], v[160:163], 0
	v_mfma_f32_16x16x32_bf16 v[112:115], v[152:155], v[160:163], 0
	v_mfma_f32_16x16x32_bf16 v[100:103], v[144:147], v[168:171], 0
	v_mfma_f32_16x16x32_bf16 v[96:99], v[152:155], v[168:171], 0
	v_mfma_f32_16x16x32_bf16 v[84:87], v[144:147], v[176:179], 0
	v_mfma_f32_16x16x32_bf16 v[80:83], v[152:155], v[176:179], 0
	v_mfma_f32_16x16x32_bf16 v[68:71], v[144:147], v[198:201], 0
	v_mfma_f32_16x16x32_bf16 v[64:67], v[152:155], v[198:201], 0
	v_mfma_f32_16x16x32_bf16 v[116:119], v[148:151], v[164:167], v[116:119]
	v_mfma_f32_16x16x32_bf16 v[112:115], v[156:159], v[164:167], v[112:115]
	v_mfma_f32_16x16x32_bf16 v[100:103], v[148:151], v[172:175], v[100:103]
	v_mfma_f32_16x16x32_bf16 v[96:99], v[156:159], v[172:175], v[96:99]
	v_mfma_f32_16x16x32_bf16 v[84:87], v[148:151], v[180:183], v[84:87]
	v_mfma_f32_16x16x32_bf16 v[80:83], v[156:159], v[180:183], v[80:83]
	v_mfma_f32_16x16x32_bf16 v[68:71], v[148:151], v[202:205], v[68:71]
	v_mfma_f32_16x16x32_bf16 v[64:67], v[156:159], v[202:205], v[64:67]
	s_setprio 0
	s_barrier
	s_add_i32 s59, s50, s25
	v_lshl_add_u64 v[206:207], s[44:45], 0, v[186:187]
	s_mov_b32 m0, s59
	ds_read_b128 v[160:163], v236 offset:16384
	ds_read_b128 v[164:167], v236 offset:17408
	ds_read_b128 v[168:171], v236 offset:18432
	ds_read_b128 v[172:175], v236 offset:19456
	ds_read_b128 v[176:179], v236 offset:20480
	ds_read_b128 v[180:183], v236 offset:21504
	ds_read_b128 v[198:201], v236 offset:22528
	ds_read_b128 v[202:205], v236 offset:23552
	global_load_lds_dwordx4 v[206:207], off
	s_add_i32 m0, s59, 0x2000
	s_add_u32 s60, s44, 0xb0000
	v_lshl_add_u64 v[208:209], s[44:45], 0, v[190:191]
	s_addc_u32 s61, s45, 0
	s_add_i32 s59, s51, s25
	global_load_lds_dwordx4 v[208:209], off
	s_mov_b32 m0, s59
	v_lshl_add_u64 v[212:213], s[46:47], 0, v[188:189]
	global_load_lds_dwordx4 v186, s[60:61]
	s_add_i32 m0, s59, 0x2000
	s_nop 0
	global_load_lds_dwordx4 v190, s[60:61]
	v_lshl_add_u64 v[210:211], s[46:47], 0, v[184:185]
	s_mov_b32 m0, s26
	s_nop 0
	global_load_lds_dwordx4 v[210:211], off
	s_mov_b32 m0, s27
	s_nop 0
	global_load_lds_dwordx4 v[212:213], off
	s_waitcnt vmcnt(8)
	s_waitcnt lgkmcnt(0)
	s_barrier
	s_setprio 1
	s_waitcnt lgkmcnt(0)
	v_mfma_f32_16x16x32_bf16 v[60:63], v[124:127], v[160:163], 0
	v_mfma_f32_16x16x32_bf16 v[56:59], v[136:139], v[160:163], 0
	v_mfma_f32_16x16x32_bf16 v[44:47], v[124:127], v[168:171], 0
	v_mfma_f32_16x16x32_bf16 v[40:43], v[136:139], v[168:171], 0
	v_mfma_f32_16x16x32_bf16 v[28:31], v[124:127], v[176:179], 0
	v_mfma_f32_16x16x32_bf16 v[24:27], v[136:139], v[176:179], 0
	v_mfma_f32_16x16x32_bf16 v[12:15], v[124:127], v[198:201], 0
	v_mfma_f32_16x16x32_bf16 v[8:11], v[136:139], v[198:201], 0
	v_mfma_f32_16x16x32_bf16 v[60:63], v[132:135], v[164:167], v[60:63]
	v_mfma_f32_16x16x32_bf16 v[56:59], v[140:143], v[164:167], v[56:59]
	v_mfma_f32_16x16x32_bf16 v[44:47], v[132:135], v[172:175], v[44:47]
	v_mfma_f32_16x16x32_bf16 v[40:43], v[140:143], v[172:175], v[40:43]
	v_mfma_f32_16x16x32_bf16 v[28:31], v[132:135], v[180:183], v[28:31]
	v_mfma_f32_16x16x32_bf16 v[24:27], v[140:143], v[180:183], v[24:27]
	v_mfma_f32_16x16x32_bf16 v[12:15], v[132:135], v[202:205], v[12:15]
	v_mfma_f32_16x16x32_bf16 v[8:11], v[140:143], v[202:205], v[8:11]
	s_setprio 0
	s_setprio 1
	v_mfma_f32_16x16x32_bf16 v[52:55], v[144:147], v[160:163], 0
	v_mfma_f32_16x16x32_bf16 v[48:51], v[152:155], v[160:163], 0
	v_mfma_f32_16x16x32_bf16 v[36:39], v[144:147], v[168:171], 0
	v_mfma_f32_16x16x32_bf16 v[32:35], v[152:155], v[168:171], 0
	v_mfma_f32_16x16x32_bf16 v[20:23], v[144:147], v[176:179], 0
	v_mfma_f32_16x16x32_bf16 v[16:19], v[152:155], v[176:179], 0
	v_mfma_f32_16x16x32_bf16 v[4:7], v[144:147], v[198:201], 0
	v_mfma_f32_16x16x32_bf16 v[0:3], v[152:155], v[198:201], 0
	v_mfma_f32_16x16x32_bf16 v[52:55], v[148:151], v[164:167], v[52:55]
	v_mfma_f32_16x16x32_bf16 v[48:51], v[156:159], v[164:167], v[48:51]
	v_mfma_f32_16x16x32_bf16 v[36:39], v[148:151], v[172:175], v[36:39]
	v_mfma_f32_16x16x32_bf16 v[32:35], v[156:159], v[172:175], v[32:35]
	v_mfma_f32_16x16x32_bf16 v[20:23], v[148:151], v[180:183], v[20:23]
	v_mfma_f32_16x16x32_bf16 v[16:19], v[156:159], v[180:183], v[16:19]
	v_mfma_f32_16x16x32_bf16 v[4:7], v[148:151], v[202:205], v[4:7]
	v_mfma_f32_16x16x32_bf16 v[0:3], v[156:159], v[202:205], v[0:3]
	s_setprio 0
	s_barrier
; #define PG8_STAGE(bufoff, gbase, voff) do { _Pragma("unroll") for (int _i = 0; _i < 2; ++_i) \
;         __builtin_amdgcn_global_load_lds((const unsigned*)((const char*)(gbase) + (voff)[_i]), (PG8_LAS unsigned*)(lds + (bufoff) + ldsw + _i * 8192), 16, 0, 0); } while (0)
; #define PG8_LDA(dst, b, h) do { _Pragma("unroll") for (int m = 0; m < 4; ++m) _Pragma("unroll") for (int k = 0; k < 2; ++k) dst[m][k] = *(const PG8_LAS bf16x8*)(lds + PG8_SA(b, h) + aoff + m * 2048 + k * 1024); } while (0)
; #define PG8_LDB(dst, b, h) do { _Pragma("unroll") for (int n = 0; n < 2; ++n) _Pragma("unroll") for (int k = 0; k < 2; ++k) dst[n][k] = *(const PG8_LAS bf16x8*)(lds + PG8_SB(b, h) + boff + n * 2048 + k * 1024); } while (0)
; #define PG8_MMA(ai, bj, At, Bt) do { __builtin_amdgcn_s_setprio(1); _Pragma("unroll") for (int m = 0; m < 4; ++m) _Pragma("unroll") for (int n = 0; n < 2; ++n) _Pragma("unroll") for (int k = 0; k < 2; ++k) \
;         acc[ai][bj][m][n] = __builtin_amdgcn_mfma_f32_16x16x32_bf16(Bt[n][k], At[m][k], acc[ai][bj][m][n], 0, 0, 0); __builtin_amdgcn_s_setprio(0); } while (0)
; #define PG8_WAIT_V(n) asm volatile("s_waitcnt vmcnt(" #n ")" ::: "memory")
; #define PG8_WAIT_L(n) asm volatile("s_waitcnt lgkmcnt(" #n ")" ::: "memory")
; #define PG8_BAR __builtin_amdgcn_s_barrier()
; #define PG8_SCHED __builtin_amdgcn_sched_barrier(0)
; template <class Epi, class Sched, bool ALIGN_EPI = false, bool SP2 = false>
; __device__ __forceinline__ void gemm_phase(PG8_LAS unsigned char* lds, const Gemm g, const Sched& S, const Epi& E) {
;     ...
;             PG8_LDB(B0, 1, 0); PG8_LDB(B1, 1, 1); PG8_SCHED; PG8_LDA(At, 1, 0); PG8_STAGE(PG8_SA(0, 1), a2 + hstep, voffA);
;             PG8_WAIT_V(8); PG8_WAIT_L(0); PG8_BAR; PG8_MMA(0, 0, At, B0); PG8_MMA(0, 1, At, B1); PG8_BAR; PG8_SCHED;
;             PG8_LDA(At, 1, 1); PG8_STAGE(PG8_SB(1, 0), b3, voffB); PG8_STAGE(PG8_SB(1, 1), b3 + hstep, voffB); PG8_STAGE(PG8_SA(1, 0), a3, voffA);
;             PG8_WAIT_V(8); PG8_WAIT_L(0); PG8_BAR; PG8_MMA(1, 0, At, B0); PG8_MMA(1, 1, At, B1); PG8_BAR; PG8_SCHED;
	s_add_i32 s59, 0, 0x18000
	s_add_i32 s60, 0, 0x1c000
	v_add_u32_e32 v140, s59, v232
	v_add_u32_e32 v156, s60, v232
	ds_read_b128 v[124:127], v140
	ds_read_b128 v[132:135], v140 offset:1024
	ds_read_b128 v[136:139], v140 offset:2048
	ds_read_b128 v[140:143], v140 offset:3072
	ds_read_b128 v[144:147], v156
	ds_read_b128 v[148:151], v156 offset:1024
	ds_read_b128 v[152:155], v156 offset:2048
	ds_read_b128 v[156:159], v156 offset:3072
	s_add_u32 s46, s46, 0xb0000
	s_addc_u32 s47, s47, 0
	s_mov_b32 m0, s28
	ds_read_b128 v[160:163], v236 offset:32768
	ds_read_b128 v[164:167], v236 offset:33792
	ds_read_b128 v[168:171], v236 offset:34816
	ds_read_b128 v[172:175], v236 offset:35840
	ds_read_b128 v[176:179], v236 offset:36864
	ds_read_b128 v[180:183], v236 offset:37888
	ds_read_b128 v[198:201], v236 offset:38912
	ds_read_b128 v[202:205], v236 offset:39936
	global_load_lds_dwordx4 v184, s[46:47]
	v_lshl_add_u64 v[214:215], s[46:47], 0, v[188:189]
	s_mov_b32 m0, s29
	s_nop 0
	global_load_lds_dwordx4 v[214:215], off
	s_waitcnt vmcnt(8)
	s_waitcnt lgkmcnt(0)
	s_barrier
	s_setprio 1
	s_waitcnt lgkmcnt(0)
	v_mfma_f32_16x16x32_bf16 v[128:131], v[124:127], v[160:163], v[128:131]
	v_mfma_f32_16x16x32_bf16 v[120:123], v[136:139], v[160:163], v[120:123]
	v_mfma_f32_16x16x32_bf16 v[108:111], v[124:127], v[168:171], v[108:111]
	v_mfma_f32_16x16x32_bf16 v[104:107], v[136:139], v[168:171], v[104:107]
	v_mfma_f32_16x16x32_bf16 v[92:95], v[124:127], v[176:179], v[92:95]
	v_mfma_f32_16x16x32_bf16 v[88:91], v[136:139], v[176:179], v[88:91]
	v_mfma_f32_16x16x32_bf16 v[76:79], v[124:127], v[198:201], v[76:79]
	v_mfma_f32_16x16x32_bf16 v[72:75], v[136:139], v[198:201], v[72:75]
	v_mfma_f32_16x16x32_bf16 v[128:131], v[132:135], v[164:167], v[128:131]
	v_mfma_f32_16x16x32_bf16 v[120:123], v[140:143], v[164:167], v[120:123]
	v_mfma_f32_16x16x32_bf16 v[108:111], v[132:135], v[172:175], v[108:111]
	v_mfma_f32_16x16x32_bf16 v[104:107], v[140:143], v[172:175], v[104:107]
	v_mfma_f32_16x16x32_bf16 v[92:95], v[132:135], v[180:183], v[92:95]
	v_mfma_f32_16x16x32_bf16 v[88:91], v[140:143], v[180:183], v[88:91]
	v_mfma_f32_16x16x32_bf16 v[76:79], v[132:135], v[202:205], v[76:79]
	v_mfma_f32_16x16x32_bf16 v[72:75], v[140:143], v[202:205], v[72:75]
	s_setprio 0
	s_setprio 1
	v_mfma_f32_16x16x32_bf16 v[116:119], v[144:147], v[160:163], v[116:119]
	v_mfma_f32_16x16x32_bf16 v[112:115], v[152:155], v[160:163], v[112:115]
	v_mfma_f32_16x16x32_bf16 v[100:103], v[144:147], v[168:171], v[100:103]
	v_mfma_f32_16x16x32_bf16 v[96:99], v[152:155], v[168:171], v[96:99]
	v_mfma_f32_16x16x32_bf16 v[84:87], v[144:147], v[176:179], v[84:87]
	v_mfma_f32_16x16x32_bf16 v[80:83], v[152:155], v[176:179], v[80:83]
	v_mfma_f32_16x16x32_bf16 v[68:71], v[144:147], v[198:201], v[68:71]
	v_mfma_f32_16x16x32_bf16 v[64:67], v[152:155], v[198:201], v[64:67]
	v_mfma_f32_16x16x32_bf16 v[116:119], v[148:151], v[164:167], v[116:119]
	v_mfma_f32_16x16x32_bf16 v[112:115], v[156:159], v[164:167], v[112:115]
	v_mfma_f32_16x16x32_bf16 v[100:103], v[148:151], v[172:175], v[100:103]
	v_mfma_f32_16x16x32_bf16 v[96:99], v[156:159], v[172:175], v[96:99]
	v_mfma_f32_16x16x32_bf16 v[84:87], v[148:151], v[180:183], v[84:87]
	v_mfma_f32_16x16x32_bf16 v[80:83], v[156:159], v[180:183], v[80:83]
	v_mfma_f32_16x16x32_bf16 v[68:71], v[148:151], v[202:205], v[68:71]
	v_mfma_f32_16x16x32_bf16 v[64:67], v[156:159], v[202:205], v[64:67]
	s_setprio 0
	s_barrier
	s_add_i32 s46, s59, s25
	v_lshl_add_u64 v[206:207], v[206:207], 0, s[20:21]
	s_mov_b32 m0, s46
	ds_read_b128 v[160:163], v236 offset:49152
	ds_read_b128 v[164:167], v236 offset:50176
	ds_read_b128 v[168:171], v236 offset:51200
	ds_read_b128 v[172:175], v236 offset:52224
	ds_read_b128 v[176:179], v236 offset:53248
	ds_read_b128 v[180:183], v236 offset:54272
	ds_read_b128 v[198:201], v236 offset:55296
	ds_read_b128 v[202:205], v236 offset:56320
	global_load_lds_dwordx4 v[206:207], off
	s_add_i32 m0, s46, 0x2000
	s_add_u32 s44, s44, 0xb0080
	v_lshl_add_u64 v[206:207], v[208:209], 0, s[20:21]
	s_addc_u32 s45, s45, 0
	s_add_i32 s46, s60, s25
	global_load_lds_dwordx4 v[206:207], off
	s_mov_b32 m0, s46
	s_nop 0
	global_load_lds_dwordx4 v186, s[44:45]
	s_add_i32 m0, s46, 0x2000
	s_nop 0
	global_load_lds_dwordx4 v190, s[44:45]
	v_lshl_add_u64 v[206:207], v[210:211], 0, s[20:21]
	s_mov_b32 m0, s31
	s_nop 0
	global_load_lds_dwordx4 v[206:207], off
	v_lshl_add_u64 v[206:207], v[212:213], 0, s[20:21]
	s_mov_b32 m0, s33
	s_nop 0
	global_load_lds_dwordx4 v[206:207], off
	s_waitcnt vmcnt(8)
	s_waitcnt lgkmcnt(0)
	s_barrier
	s_setprio 1
	s_waitcnt lgkmcnt(0)
	v_mfma_f32_16x16x32_bf16 v[60:63], v[124:127], v[160:163], v[60:63]
	v_mfma_f32_16x16x32_bf16 v[56:59], v[136:139], v[160:163], v[56:59]
	v_mfma_f32_16x16x32_bf16 v[44:47], v[124:127], v[168:171], v[44:47]
	v_mfma_f32_16x16x32_bf16 v[40:43], v[136:139], v[168:171], v[40:43]
	v_mfma_f32_16x16x32_bf16 v[28:31], v[124:127], v[176:179], v[28:31]
	v_mfma_f32_16x16x32_bf16 v[24:27], v[136:139], v[176:179], v[24:27]
	v_mfma_f32_16x16x32_bf16 v[12:15], v[124:127], v[198:201], v[12:15]
	v_mfma_f32_16x16x32_bf16 v[8:11], v[136:139], v[198:201], v[8:11]
	v_mfma_f32_16x16x32_bf16 v[60:63], v[132:135], v[164:167], v[60:63]
	v_mfma_f32_16x16x32_bf16 v[56:59], v[140:143], v[164:167], v[56:59]
	v_mfma_f32_16x16x32_bf16 v[44:47], v[132:135], v[172:175], v[44:47]
	v_mfma_f32_16x16x32_bf16 v[40:43], v[140:143], v[172:175], v[40:43]
	v_mfma_f32_16x16x32_bf16 v[28:31], v[132:135], v[180:183], v[28:31]
	v_mfma_f32_16x16x32_bf16 v[24:27], v[140:143], v[180:183], v[24:27]
	v_mfma_f32_16x16x32_bf16 v[12:15], v[132:135], v[202:205], v[12:15]
	v_mfma_f32_16x16x32_bf16 v[8:11], v[140:143], v[202:205], v[8:11]
	s_setprio 0
	s_setprio 1
	v_mfma_f32_16x16x32_bf16 v[52:55], v[144:147], v[160:163], v[52:55]
	v_mfma_f32_16x16x32_bf16 v[48:51], v[152:155], v[160:163], v[48:51]
	v_mfma_f32_16x16x32_bf16 v[36:39], v[144:147], v[168:171], v[36:39]
	v_mfma_f32_16x16x32_bf16 v[32:35], v[152:155], v[168:171], v[32:35]
	v_mfma_f32_16x16x32_bf16 v[20:23], v[144:147], v[176:179], v[20:23]
	v_mfma_f32_16x16x32_bf16 v[16:19], v[152:155], v[176:179], v[16:19]
	v_mfma_f32_16x16x32_bf16 v[4:7], v[144:147], v[198:201], v[4:7]
	v_mfma_f32_16x16x32_bf16 v[0:3], v[152:155], v[198:201], v[0:3]
	v_mfma_f32_16x16x32_bf16 v[52:55], v[148:151], v[164:167], v[52:55]
	v_mfma_f32_16x16x32_bf16 v[48:51], v[156:159], v[164:167], v[48:51]
	v_mfma_f32_16x16x32_bf16 v[36:39], v[148:151], v[172:175], v[36:39]
	v_mfma_f32_16x16x32_bf16 v[32:35], v[156:159], v[172:175], v[32:35]
	v_mfma_f32_16x16x32_bf16 v[20:23], v[148:151], v[180:183], v[20:23]
	v_mfma_f32_16x16x32_bf16 v[16:19], v[156:159], v[180:183], v[16:19]
	v_mfma_f32_16x16x32_bf16 v[4:7], v[148:151], v[202:205], v[4:7]
	v_mfma_f32_16x16x32_bf16 v[0:3], v[156:159], v[202:205], v[0:3]
	s_setprio 0
	s_add_i32 s58, s58, 2
	s_add_u32 s42, s42, 0x100
	s_addc_u32 s43, s43, 0
	s_add_u32 s56, s56, 0x100
	s_addc_u32 s57, s57, 0
	s_cmp_gt_u32 s58, 41
	s_barrier
; #define PG8_STAGE(bufoff, gbase, voff) do { _Pragma("unroll") for (int _i = 0; _i < 2; ++_i) \
;         __builtin_amdgcn_global_load_lds((const unsigned*)((const char*)(gbase) + (voff)[_i]), (PG8_LAS unsigned*)(lds + (bufoff) + ldsw + _i * 8192), 16, 0, 0); } while (0)
; #define PG8_LDA(dst, b, h) do { _Pragma("unroll") for (int m = 0; m < 4; ++m) _Pragma("unroll") for (int k = 0; k < 2; ++k) dst[m][k] = *(const PG8_LAS bf16x8*)(lds + PG8_SA(b, h) + aoff + m * 2048 + k * 1024); } while (0)
; #define PG8_LDB(dst, b, h) do { _Pragma("unroll") for (int n = 0; n < 2; ++n) _Pragma("unroll") for (int k = 0; k < 2; ++k) dst[n][k] = *(const PG8_LAS bf16x8*)(lds + PG8_SB(b, h) + boff + n * 2048 + k * 1024); } while (0)
; #define PG8_MMA(ai, bj, At, Bt) do { __builtin_amdgcn_s_setprio(1); _Pragma("unroll") for (int m = 0; m < 4; ++m) _Pragma("unroll") for (int n = 0; n < 2; ++n) _Pragma("unroll") for (int k = 0; k < 2; ++k) \
;         acc[ai][bj][m][n] = __builtin_amdgcn_mfma_f32_16x16x32_bf16(Bt[n][k], At[m][k], acc[ai][bj][m][n], 0, 0, 0); __builtin_amdgcn_s_setprio(0); } while (0)
; #define PG8_WAIT_V(n) asm volatile("s_waitcnt vmcnt(" #n ")" ::: "memory")
; #define PG8_WAIT_L(n) asm volatile("s_waitcnt lgkmcnt(" #n ")" ::: "memory")
; #define PG8_BAR __builtin_amdgcn_s_barrier()
; #define PG8_SCHED __builtin_amdgcn_sched_barrier(0)
; template <class Epi, class Sched, bool ALIGN_EPI = false, bool SP2 = false>
; __device__ __forceinline__ void gemm_phase(PG8_LAS unsigned char* lds, const Gemm g, const Sched& S, const Epi& E) {
;     ...
;             PG8_LDB(B0, 0, 0); PG8_LDB(B1, 0, 1); PG8_SCHED; PG8_LDA(At, 0, 0); PG8_STAGE(PG8_SA(1, 1), a1 + hstep, voffA);
;             PG8_WAIT_V(8); PG8_WAIT_L(0); PG8_BAR; PG8_MMA(0, 0, At, B0); PG8_MMA(0, 1, At, B1); PG8_BAR; PG8_SCHED;
;             PG8_LDA(At, 0, 1); PG8_STAGE(PG8_SB(0, 0), b2, voffB); PG8_STAGE(PG8_SB(0, 1), b2 + hstep, voffB); PG8_STAGE(PG8_SA(0, 0), a2, voffA);
;             PG8_WAIT_V(8); PG8_WAIT_L(0); PG8_BAR; PG8_MMA(1, 0, At, B0); PG8_MMA(1, 1, At, B1); PG8_BAR; PG8_SCHED;
.LBB0_570:
	ds_read_b128 v[124:127], v234
	ds_read_b128 v[132:135], v234 offset:1024
	ds_read_b128 v[136:139], v234 offset:2048
	ds_read_b128 v[140:143], v234 offset:3072
	ds_read_b128 v[144:147], v235
	ds_read_b128 v[148:151], v235 offset:1024
	ds_read_b128 v[152:155], v235 offset:2048
	ds_read_b128 v[156:159], v235 offset:3072
	s_add_u32 s44, s42, 0xfff50080
	s_addc_u32 s45, s43, -1
	s_cmp_eq_u32 s58, 40
	s_cselect_b32 s47, s39, s45
	s_cselect_b32 s46, s38, s44
	s_cselect_b32 s45, s41, s57
	s_cselect_b32 s44, s40, s56
	s_add_i32 m0, s26, 0xc000
	ds_read_b128 v[160:163], v236
	ds_read_b128 v[164:167], v236 offset:1024
	ds_read_b128 v[168:171], v236 offset:2048
	ds_read_b128 v[172:175], v236 offset:3072
	ds_read_b128 v[176:179], v236 offset:4096
	ds_read_b128 v[180:183], v236 offset:5120
	ds_read_b128 v[198:201], v236 offset:6144
	ds_read_b128 v[202:205], v236 offset:7168
	global_load_lds_dwordx4 v192, s[42:43]
	s_add_i32 m0, s26, 0xe000
	s_nop 0
	global_load_lds_dwordx4 v194, s[42:43]
	s_waitcnt vmcnt(8)
	s_waitcnt lgkmcnt(0)
	s_barrier
	s_setprio 1
	s_waitcnt lgkmcnt(0)
	v_mfma_f32_16x16x32_bf16 v[128:131], v[124:127], v[160:163], v[128:131]
	v_mfma_f32_16x16x32_bf16 v[120:123], v[136:139], v[160:163], v[120:123]
	v_mfma_f32_16x16x32_bf16 v[108:111], v[124:127], v[168:171], v[108:111]
	v_mfma_f32_16x16x32_bf16 v[104:107], v[136:139], v[168:171], v[104:107]
	v_mfma_f32_16x16x32_bf16 v[92:95], v[124:127], v[176:179], v[92:95]
	v_mfma_f32_16x16x32_bf16 v[88:91], v[136:139], v[176:179], v[88:91]
	v_mfma_f32_16x16x32_bf16 v[76:79], v[124:127], v[198:201], v[76:79]
	v_mfma_f32_16x16x32_bf16 v[72:75], v[136:139], v[198:201], v[72:75]
	v_mfma_f32_16x16x32_bf16 v[128:131], v[132:135], v[164:167], v[128:131]
	v_mfma_f32_16x16x32_bf16 v[120:123], v[140:143], v[164:167], v[120:123]
	v_mfma_f32_16x16x32_bf16 v[108:111], v[132:135], v[172:175], v[108:111]
	v_mfma_f32_16x16x32_bf16 v[104:107], v[140:143], v[172:175], v[104:107]
	v_mfma_f32_16x16x32_bf16 v[92:95], v[132:135], v[180:183], v[92:95]
	v_mfma_f32_16x16x32_bf16 v[88:91], v[140:143], v[180:183], v[88:91]
	v_mfma_f32_16x16x32_bf16 v[76:79], v[132:135], v[202:205], v[76:79]
	v_mfma_f32_16x16x32_bf16 v[72:75], v[140:143], v[202:205], v[72:75]
	s_setprio 0
	s_setprio 1
	v_mfma_f32_16x16x32_bf16 v[116:119], v[144:147], v[160:163], v[116:119]
	v_mfma_f32_16x16x32_bf16 v[112:115], v[152:155], v[160:163], v[112:115]
	v_mfma_f32_16x16x32_bf16 v[100:103], v[144:147], v[168:171], v[100:103]
	v_mfma_f32_16x16x32_bf16 v[96:99], v[152:155], v[168:171], v[96:99]
	v_mfma_f32_16x16x32_bf16 v[84:87], v[144:147], v[176:179], v[84:87]
	v_mfma_f32_16x16x32_bf16 v[80:83], v[152:155], v[176:179], v[80:83]
	v_mfma_f32_16x16x32_bf16 v[68:71], v[144:147], v[198:201], v[68:71]
	v_mfma_f32_16x16x32_bf16 v[64:67], v[152:155], v[198:201], v[64:67]
	v_mfma_f32_16x16x32_bf16 v[116:119], v[148:151], v[164:167], v[116:119]
	v_mfma_f32_16x16x32_bf16 v[112:115], v[156:159], v[164:167], v[112:115]
	v_mfma_f32_16x16x32_bf16 v[100:103], v[148:151], v[172:175], v[100:103]
	v_mfma_f32_16x16x32_bf16 v[96:99], v[156:159], v[172:175], v[96:99]
	v_mfma_f32_16x16x32_bf16 v[84:87], v[148:151], v[180:183], v[84:87]
	v_mfma_f32_16x16x32_bf16 v[80:83], v[156:159], v[180:183], v[80:83]
	v_mfma_f32_16x16x32_bf16 v[68:71], v[148:151], v[202:205], v[68:71]
	v_mfma_f32_16x16x32_bf16 v[64:67], v[156:159], v[202:205], v[64:67]
	s_setprio 0
	s_barrier
	s_add_i32 s59, s50, s25
	v_lshl_add_u64 v[206:207], s[44:45], 0, v[186:187]
	s_mov_b32 m0, s59
	ds_read_b128 v[160:163], v236 offset:16384
	ds_read_b128 v[164:167], v236 offset:17408
	ds_read_b128 v[168:171], v236 offset:18432
	ds_read_b128 v[172:175], v236 offset:19456
	ds_read_b128 v[176:179], v236 offset:20480
	ds_read_b128 v[180:183], v236 offset:21504
	ds_read_b128 v[198:201], v236 offset:22528
	ds_read_b128 v[202:205], v236 offset:23552
	global_load_lds_dwordx4 v[206:207], off
	s_add_i32 m0, s59, 0x2000
	s_add_u32 s60, s44, 0xb0000
	v_lshl_add_u64 v[208:209], s[44:45], 0, v[190:191]
	s_addc_u32 s61, s45, 0
	s_add_i32 s59, s51, s25
	global_load_lds_dwordx4 v[208:209], off
	s_mov_b32 m0, s59
	v_lshl_add_u64 v[212:213], s[46:47], 0, v[188:189]
	global_load_lds_dwordx4 v186, s[60:61]
	s_add_i32 m0, s59, 0x2000
	s_nop 0
	global_load_lds_dwordx4 v190, s[60:61]
	v_lshl_add_u64 v[210:211], s[46:47], 0, v[184:185]
	s_mov_b32 m0, s26
	s_nop 0
	global_load_lds_dwordx4 v[210:211], off
	s_mov_b32 m0, s27
	s_nop 0
	global_load_lds_dwordx4 v[212:213], off
	s_waitcnt vmcnt(8)
	s_waitcnt lgkmcnt(0)
	s_barrier
; #define PG8_STAGE(bufoff, gbase, voff) do { _Pragma("unroll") for (int _i = 0; _i < 2; ++_i) \
;         __builtin_amdgcn_global_load_lds((const unsigned*)((const char*)(gbase) + (voff)[_i]), (PG8_LAS unsigned*)(lds + (bufoff) + ldsw + _i * 8192), 16, 0, 0); } while (0)
; #define PG8_LDA(dst, b, h) do { _Pragma("unroll") for (int m = 0; m < 4; ++m) _Pragma("unroll") for (int k = 0; k < 2; ++k) dst[m][k] = *(const PG8_LAS bf16x8*)(lds + PG8_SA(b, h) + aoff + m * 2048 + k * 1024); } while (0)
; #define PG8_LDB(dst, b, h) do { _Pragma("unroll") for (int n = 0; n < 2; ++n) _Pragma("unroll") for (int k = 0; k < 2; ++k) dst[n][k] = *(const PG8_LAS bf16x8*)(lds + PG8_SB(b, h) + boff + n * 2048 + k * 1024); } while (0)
; #define PG8_MMA(ai, bj, At, Bt) do { __builtin_amdgcn_s_setprio(1); _Pragma("unroll") for (int m = 0; m < 4; ++m) _Pragma("unroll") for (int n = 0; n < 2; ++n) _Pragma("unroll") for (int k = 0; k < 2; ++k) \
;         acc[ai][bj][m][n] = __builtin_amdgcn_mfma_f32_16x16x32_bf16(Bt[n][k], At[m][k], acc[ai][bj][m][n], 0, 0, 0); __builtin_amdgcn_s_setprio(0); } while (0)
; #define PG8_WAIT_V(n) asm volatile("s_waitcnt vmcnt(" #n ")" ::: "memory")
; #define PG8_WAIT_L(n) asm volatile("s_waitcnt lgkmcnt(" #n ")" ::: "memory")
; #define PG8_BAR __builtin_amdgcn_s_barrier()
; #define PG8_SCHED __builtin_amdgcn_sched_barrier(0)
; template <class Epi, class Sched, bool ALIGN_EPI = false, bool SP2 = false>
; __device__ __forceinline__ void gemm_phase(PG8_LAS unsigned char* lds, const Gemm g, const Sched& S, const Epi& E) {
;     ...
;             PG8_WAIT_V(8); PG8_WAIT_L(0); PG8_BAR; PG8_MMA(1, 0, At, B0); PG8_MMA(1, 1, At, B1); PG8_BAR; PG8_SCHED;
;             PG8_LDB(B0, 1, 0); PG8_LDB(B1, 1, 1); PG8_SCHED; PG8_LDA(At, 1, 0); PG8_STAGE(PG8_SA(0, 1), a2 + hstep, voffA);
;             PG8_WAIT_V(8); PG8_WAIT_L(0); PG8_BAR; PG8_MMA(0, 0, At, B0); PG8_MMA(0, 1, At, B1); PG8_BAR; PG8_SCHED;
	s_setprio 1
	s_waitcnt lgkmcnt(0)
	v_mfma_f32_16x16x32_bf16 v[60:63], v[124:127], v[160:163], v[60:63]
	v_mfma_f32_16x16x32_bf16 v[56:59], v[136:139], v[160:163], v[56:59]
	v_mfma_f32_16x16x32_bf16 v[44:47], v[124:127], v[168:171], v[44:47]
	v_mfma_f32_16x16x32_bf16 v[40:43], v[136:139], v[168:171], v[40:43]
	v_mfma_f32_16x16x32_bf16 v[28:31], v[124:127], v[176:179], v[28:31]
	v_mfma_f32_16x16x32_bf16 v[24:27], v[136:139], v[176:179], v[24:27]
	v_mfma_f32_16x16x32_bf16 v[12:15], v[124:127], v[198:201], v[12:15]
	v_mfma_f32_16x16x32_bf16 v[8:11], v[136:139], v[198:201], v[8:11]
	v_mfma_f32_16x16x32_bf16 v[60:63], v[132:135], v[164:167], v[60:63]
	v_mfma_f32_16x16x32_bf16 v[56:59], v[140:143], v[164:167], v[56:59]
	v_mfma_f32_16x16x32_bf16 v[44:47], v[132:135], v[172:175], v[44:47]
	v_mfma_f32_16x16x32_bf16 v[40:43], v[140:143], v[172:175], v[40:43]
	v_mfma_f32_16x16x32_bf16 v[28:31], v[132:135], v[180:183], v[28:31]
	v_mfma_f32_16x16x32_bf16 v[24:27], v[140:143], v[180:183], v[24:27]
	v_mfma_f32_16x16x32_bf16 v[12:15], v[132:135], v[202:205], v[12:15]
	v_mfma_f32_16x16x32_bf16 v[8:11], v[140:143], v[202:205], v[8:11]
	s_setprio 0
	s_setprio 1
	v_mfma_f32_16x16x32_bf16 v[52:55], v[144:147], v[160:163], v[52:55]
	v_mfma_f32_16x16x32_bf16 v[48:51], v[152:155], v[160:163], v[48:51]
	v_mfma_f32_16x16x32_bf16 v[36:39], v[144:147], v[168:171], v[36:39]
	v_mfma_f32_16x16x32_bf16 v[32:35], v[152:155], v[168:171], v[32:35]
	v_mfma_f32_16x16x32_bf16 v[20:23], v[144:147], v[176:179], v[20:23]
	v_mfma_f32_16x16x32_bf16 v[16:19], v[152:155], v[176:179], v[16:19]
	v_mfma_f32_16x16x32_bf16 v[4:7], v[144:147], v[198:201], v[4:7]
	v_mfma_f32_16x16x32_bf16 v[0:3], v[152:155], v[198:201], v[0:3]
	v_mfma_f32_16x16x32_bf16 v[52:55], v[148:151], v[164:167], v[52:55]
	v_mfma_f32_16x16x32_bf16 v[48:51], v[156:159], v[164:167], v[48:51]
	v_mfma_f32_16x16x32_bf16 v[36:39], v[148:151], v[172:175], v[36:39]
	v_mfma_f32_16x16x32_bf16 v[32:35], v[156:159], v[172:175], v[32:35]
	v_mfma_f32_16x16x32_bf16 v[20:23], v[148:151], v[180:183], v[20:23]
	v_mfma_f32_16x16x32_bf16 v[16:19], v[156:159], v[180:183], v[16:19]
	v_mfma_f32_16x16x32_bf16 v[4:7], v[148:151], v[202:205], v[4:7]
	v_mfma_f32_16x16x32_bf16 v[0:3], v[156:159], v[202:205], v[0:3]
	s_setprio 0
	s_barrier
	s_add_i32 s59, 0, 0x18000
	s_add_i32 s60, 0, 0x1c000
	v_add_u32_e32 v140, s59, v232
	v_add_u32_e32 v156, s60, v232
	ds_read_b128 v[124:127], v140
	ds_read_b128 v[132:135], v140 offset:1024
	ds_read_b128 v[136:139], v140 offset:2048
	ds_read_b128 v[140:143], v140 offset:3072
	ds_read_b128 v[144:147], v156
	ds_read_b128 v[148:151], v156 offset:1024
	ds_read_b128 v[152:155], v156 offset:2048
	ds_read_b128 v[156:159], v156 offset:3072
	s_add_u32 s46, s46, 0xb0000
	s_addc_u32 s47, s47, 0
	s_mov_b32 m0, s28
	ds_read_b128 v[160:163], v236 offset:32768
	ds_read_b128 v[164:167], v236 offset:33792
	ds_read_b128 v[168:171], v236 offset:34816
	ds_read_b128 v[172:175], v236 offset:35840
	ds_read_b128 v[176:179], v236 offset:36864
	ds_read_b128 v[180:183], v236 offset:37888
	ds_read_b128 v[198:201], v236 offset:38912
	ds_read_b128 v[202:205], v236 offset:39936
	global_load_lds_dwordx4 v184, s[46:47]
	v_lshl_add_u64 v[214:215], s[46:47], 0, v[188:189]
	s_mov_b32 m0, s29
	s_nop 0
	global_load_lds_dwordx4 v[214:215], off
	s_waitcnt vmcnt(8)
	s_waitcnt lgkmcnt(0)
	s_barrier
	s_setprio 1
	s_waitcnt lgkmcnt(0)
	v_mfma_f32_16x16x32_bf16 v[128:131], v[124:127], v[160:163], v[128:131]
	v_mfma_f32_16x16x32_bf16 v[120:123], v[136:139], v[160:163], v[120:123]
	v_mfma_f32_16x16x32_bf16 v[108:111], v[124:127], v[168:171], v[108:111]
	v_mfma_f32_16x16x32_bf16 v[104:107], v[136:139], v[168:171], v[104:107]
	v_mfma_f32_16x16x32_bf16 v[92:95], v[124:127], v[176:179], v[92:95]
	v_mfma_f32_16x16x32_bf16 v[88:91], v[136:139], v[176:179], v[88:91]
	v_mfma_f32_16x16x32_bf16 v[76:79], v[124:127], v[198:201], v[76:79]
	v_mfma_f32_16x16x32_bf16 v[72:75], v[136:139], v[198:201], v[72:75]
	v_mfma_f32_16x16x32_bf16 v[128:131], v[132:135], v[164:167], v[128:131]
	v_mfma_f32_16x16x32_bf16 v[120:123], v[140:143], v[164:167], v[120:123]
	v_mfma_f32_16x16x32_bf16 v[108:111], v[132:135], v[172:175], v[108:111]
	v_mfma_f32_16x16x32_bf16 v[104:107], v[140:143], v[172:175], v[104:107]
	v_mfma_f32_16x16x32_bf16 v[92:95], v[132:135], v[180:183], v[92:95]
	v_mfma_f32_16x16x32_bf16 v[88:91], v[140:143], v[180:183], v[88:91]
	v_mfma_f32_16x16x32_bf16 v[76:79], v[132:135], v[202:205], v[76:79]
	v_mfma_f32_16x16x32_bf16 v[72:75], v[140:143], v[202:205], v[72:75]
	s_setprio 0
	s_setprio 1
	v_mfma_f32_16x16x32_bf16 v[116:119], v[144:147], v[160:163], v[116:119]
	v_mfma_f32_16x16x32_bf16 v[112:115], v[152:155], v[160:163], v[112:115]
	v_mfma_f32_16x16x32_bf16 v[100:103], v[144:147], v[168:171], v[100:103]
	v_mfma_f32_16x16x32_bf16 v[96:99], v[152:155], v[168:171], v[96:99]
	v_mfma_f32_16x16x32_bf16 v[84:87], v[144:147], v[176:179], v[84:87]
	v_mfma_f32_16x16x32_bf16 v[80:83], v[152:155], v[176:179], v[80:83]
	v_mfma_f32_16x16x32_bf16 v[68:71], v[144:147], v[198:201], v[68:71]
	v_mfma_f32_16x16x32_bf16 v[64:67], v[152:155], v[198:201], v[64:67]
	v_mfma_f32_16x16x32_bf16 v[116:119], v[148:151], v[164:167], v[116:119]
	v_mfma_f32_16x16x32_bf16 v[112:115], v[156:159], v[164:167], v[112:115]
	v_mfma_f32_16x16x32_bf16 v[100:103], v[148:151], v[172:175], v[100:103]
	v_mfma_f32_16x16x32_bf16 v[96:99], v[156:159], v[172:175], v[96:99]
	v_mfma_f32_16x16x32_bf16 v[84:87], v[148:151], v[180:183], v[84:87]
	v_mfma_f32_16x16x32_bf16 v[80:83], v[156:159], v[180:183], v[80:83]
	v_mfma_f32_16x16x32_bf16 v[68:71], v[148:151], v[202:205], v[68:71]
	v_mfma_f32_16x16x32_bf16 v[64:67], v[156:159], v[202:205], v[64:67]
	s_setprio 0
	s_barrier
; #define PG8_STAGE(bufoff, gbase, voff) do { _Pragma("unroll") for (int _i = 0; _i < 2; ++_i) \
;         __builtin_amdgcn_global_load_lds((const unsigned*)((const char*)(gbase) + (voff)[_i]), (PG8_LAS unsigned*)(lds + (bufoff) + ldsw + _i * 8192), 16, 0, 0); } while (0)
; #define PG8_LDA(dst, b, h) do { _Pragma("unroll") for (int m = 0; m < 4; ++m) _Pragma("unroll") for (int k = 0; k < 2; ++k) dst[m][k] = *(const PG8_LAS bf16x8*)(lds + PG8_SA(b, h) + aoff + m * 2048 + k * 1024); } while (0)
; #define PG8_LDB(dst, b, h) do { _Pragma("unroll") for (int n = 0; n < 2; ++n) _Pragma("unroll") for (int k = 0; k < 2; ++k) dst[n][k] = *(const PG8_LAS bf16x8*)(lds + PG8_SB(b, h) + boff + n * 2048 + k * 1024); } while (0)
; template <class Epi, class Sched, bool ALIGN_EPI = false, bool SP2 = false>
; __device__ __forceinline__ void gemm_phase(PG8_LAS unsigned char* lds, const Gemm g, const Sched& S, const Epi& E) {
;     ...
;         for (int t = 0; t < nt; t += 2) {
;             const bool last = (t == nt - 2);
;             const char* a1 = cA + (size_t)(t + 1) * kstep;
;             const char* a2 = last ? nA : cA + (size_t)(t + 2) * kstep; const char* b2 = last ? nB : cB + (size_t)(t + 2) * kstep;
;             const char* a3 = a2 + kstep; const char* b3 = b2 + kstep;
;             if (last && has_next) S.a_ready(nxt);
;             if constexpr (SP2) {
;             PG8_LDB(B0, 0, 0); PG8_LDB(B1, 0, 1); PG8_SCHED; PG8_LDA(At, 0, 0); PG8_STAGE(PG8_SA(1, 1), a1 + hstep, voffA);
;             PG8_WAIT_V(8); PG8_WAIT_L(0); PG8_BAR; PG8_MMA(0, 0, At, B0); PG8_MMA(0, 1, At, B1); PG8_BAR; PG8_SCHED;
;             PG8_LDA(At, 0, 1); PG8_STAGE(PG8_SB(0, 0), b2, voffB); PG8_STAGE(PG8_SB(0, 1), b2 + hstep, voffB); PG8_STAGE(PG8_SA(0, 0), a2, voffA);
;             PG8_WAIT_V(8); PG8_WAIT_L(0); PG8_BAR; PG8_MMA(1, 0, At, B0); PG8_MMA(1, 1, At, B1); PG8_BAR; PG8_SCHED;
;             PG8_LDB(B0, 1, 0); PG8_LDB(B1, 1, 1); PG8_SCHED; PG8_LDA(At, 1, 0); PG8_STAGE(PG8_SA(0, 1), a2 + hstep, voffA);
;             PG8_WAIT_V(8); PG8_WAIT_L(0); PG8_BAR; PG8_MMA(0, 0, At, B0); PG8_MMA(0, 1, At, B1); PG8_BAR; PG8_SCHED;
;             PG8_LDA(At, 1, 1); PG8_STAGE(PG8_SB(1, 0), b3, voffB); PG8_STAGE(PG8_SB(1, 1), b3 + hstep, voffB); PG8_STAGE(PG8_SA(1, 0), a3, voffA);
;             PG8_WAIT_V(8); PG8_WAIT_L(0); PG8_BAR; PG8_MMA(1, 0, At, B0); PG8_MMA(1, 1, At, B1); PG8_BAR; PG8_SCHED;
	s_add_i32 s46, s59, s25
	v_lshl_add_u64 v[206:207], v[206:207], 0, s[20:21]
	s_mov_b32 m0, s46
	ds_read_b128 v[160:163], v236 offset:49152
	ds_read_b128 v[164:167], v236 offset:50176
	ds_read_b128 v[168:171], v236 offset:51200
	ds_read_b128 v[172:175], v236 offset:52224
	ds_read_b128 v[176:179], v236 offset:53248
	ds_read_b128 v[180:183], v236 offset:54272
	ds_read_b128 v[198:201], v236 offset:55296
	ds_read_b128 v[202:205], v236 offset:56320
	global_load_lds_dwordx4 v[206:207], off
	s_add_i32 m0, s46, 0x2000
	s_add_u32 s44, s44, 0xb0080
	v_lshl_add_u64 v[206:207], v[208:209], 0, s[20:21]
	s_addc_u32 s45, s45, 0
	s_add_i32 s46, s60, s25
	global_load_lds_dwordx4 v[206:207], off
	s_mov_b32 m0, s46
	s_nop 0
	global_load_lds_dwordx4 v186, s[44:45]
	s_add_i32 m0, s46, 0x2000
	s_nop 0
	global_load_lds_dwordx4 v190, s[44:45]
	v_lshl_add_u64 v[206:207], v[210:211], 0, s[20:21]
	s_mov_b32 m0, s31
	s_nop 0
	global_load_lds_dwordx4 v[206:207], off
	v_lshl_add_u64 v[206:207], v[212:213], 0, s[20:21]
	s_mov_b32 m0, s33
	s_nop 0
	global_load_lds_dwordx4 v[206:207], off
	s_waitcnt vmcnt(8)
	s_waitcnt lgkmcnt(0)
	s_barrier
	s_setprio 1
	s_waitcnt lgkmcnt(0)
	v_mfma_f32_16x16x32_bf16 v[60:63], v[124:127], v[160:163], v[60:63]
	v_mfma_f32_16x16x32_bf16 v[56:59], v[136:139], v[160:163], v[56:59]
	v_mfma_f32_16x16x32_bf16 v[44:47], v[124:127], v[168:171], v[44:47]
	v_mfma_f32_16x16x32_bf16 v[40:43], v[136:139], v[168:171], v[40:43]
	v_mfma_f32_16x16x32_bf16 v[28:31], v[124:127], v[176:179], v[28:31]
	v_mfma_f32_16x16x32_bf16 v[24:27], v[136:139], v[176:179], v[24:27]
	v_mfma_f32_16x16x32_bf16 v[12:15], v[124:127], v[198:201], v[12:15]
	v_mfma_f32_16x16x32_bf16 v[8:11], v[136:139], v[198:201], v[8:11]
	v_mfma_f32_16x16x32_bf16 v[60:63], v[132:135], v[164:167], v[60:63]
	v_mfma_f32_16x16x32_bf16 v[56:59], v[140:143], v[164:167], v[56:59]
	v_mfma_f32_16x16x32_bf16 v[44:47], v[132:135], v[172:175], v[44:47]
	v_mfma_f32_16x16x32_bf16 v[40:43], v[140:143], v[172:175], v[40:43]
	v_mfma_f32_16x16x32_bf16 v[28:31], v[132:135], v[180:183], v[28:31]
	v_mfma_f32_16x16x32_bf16 v[24:27], v[140:143], v[180:183], v[24:27]
	v_mfma_f32_16x16x32_bf16 v[12:15], v[132:135], v[202:205], v[12:15]
	v_mfma_f32_16x16x32_bf16 v[8:11], v[140:143], v[202:205], v[8:11]
	s_setprio 0
	s_setprio 1
	v_mfma_f32_16x16x32_bf16 v[52:55], v[144:147], v[160:163], v[52:55]
	v_mfma_f32_16x16x32_bf16 v[48:51], v[152:155], v[160:163], v[48:51]
	v_mfma_f32_16x16x32_bf16 v[36:39], v[144:147], v[168:171], v[36:39]
	v_mfma_f32_16x16x32_bf16 v[32:35], v[152:155], v[168:171], v[32:35]
	v_mfma_f32_16x16x32_bf16 v[20:23], v[144:147], v[176:179], v[20:23]
	v_mfma_f32_16x16x32_bf16 v[16:19], v[152:155], v[176:179], v[16:19]
	v_mfma_f32_16x16x32_bf16 v[4:7], v[144:147], v[198:201], v[4:7]
	v_mfma_f32_16x16x32_bf16 v[0:3], v[152:155], v[198:201], v[0:3]
	v_mfma_f32_16x16x32_bf16 v[52:55], v[148:151], v[164:167], v[52:55]
	v_mfma_f32_16x16x32_bf16 v[48:51], v[156:159], v[164:167], v[48:51]
	v_mfma_f32_16x16x32_bf16 v[36:39], v[148:151], v[172:175], v[36:39]
	v_mfma_f32_16x16x32_bf16 v[32:35], v[156:159], v[172:175], v[32:35]
	v_mfma_f32_16x16x32_bf16 v[20:23], v[148:151], v[180:183], v[20:23]
	v_mfma_f32_16x16x32_bf16 v[16:19], v[156:159], v[180:183], v[16:19]
	v_mfma_f32_16x16x32_bf16 v[4:7], v[148:151], v[202:205], v[4:7]
	v_mfma_f32_16x16x32_bf16 v[0:3], v[156:159], v[202:205], v[0:3]
	s_setprio 0
	s_add_i32 s58, s58, 2
	s_add_u32 s42, s42, 0x100
	s_addc_u32 s43, s43, 0
	s_add_u32 s56, s56, 0x100
	s_addc_u32 s57, s57, 0
	s_cmp_gt_u32 s58, 41
	s_barrier
	s_cbranch_scc0 .LBB0_570
	s_and_b64 vcc, exec, s[36:37]
	s_cbranch_vccz .LBB0_573
	s_barrier

; #define PG8_STAGE(bufoff, gbase, voff) do { _Pragma("unroll") for (int _i = 0; _i < 2; ++_i) \
;         __builtin_amdgcn_global_load_lds((const unsigned*)((const char*)(gbase) + (voff)[_i]), (PG8_LAS unsigned*)(lds + (bufoff) + ldsw + _i * 8192), 16, 0, 0); } while (0)
; #define PG8_LDA(dst, b, h) do { _Pragma("unroll") for (int m = 0; m < 4; ++m) _Pragma("unroll") for (int k = 0; k < 2; ++k) dst[m][k] = *(const PG8_LAS bf16x8*)(lds + PG8_SA(b, h) + aoff + m * 2048 + k * 1024); } while (0)
; #define PG8_LDB(dst, b, h) do { _Pragma("unroll") for (int n = 0; n < 2; ++n) _Pragma("unroll") for (int k = 0; k < 2; ++k) dst[n][k] = *(const PG8_LAS bf16x8*)(lds + PG8_SB(b, h) + boff + n * 2048 + k * 1024); } while (0)
; #define PG8_MMA(ai, bj, At, Bt) do { __builtin_amdgcn_s_setprio(1); _Pragma("unroll") for (int m = 0; m < 4; ++m) _Pragma("unroll") for (int n = 0; n < 2; ++n) _Pragma("unroll") for (int k = 0; k < 2; ++k) \
;         acc[ai][bj][m][n] = __builtin_amdgcn_mfma_f32_16x16x32_bf16(Bt[n][k], At[m][k], acc[ai][bj][m][n], 0, 0, 0); __builtin_amdgcn_s_setprio(0); } while (0)
; #define PG8_WAIT_V(n) asm volatile("s_waitcnt vmcnt(" #n ")" ::: "memory")
; template <class Epi, class Sched, bool ALIGN_EPI = false, bool SP2 = false>
; __device__ __forceinline__ void gemm_phase(PG8_LAS unsigned char* lds, const Gemm g, const Sched& S, const Epi& E) {
;     ...
;             PG8_LDB(B0, 0, 0); PG8_LDB(B1, 0, 1); PG8_SCHED; PG8_LDA(At, 0, 0); PG8_STAGE(PG8_SA(1, 1), a1 + hstep, voffA);
;             PG8_WAIT_V(8); PG8_WAIT_L(0); PG8_BAR; PG8_MMA(0, 0, At, B0); PG8_MMA(0, 1, At, B1); PG8_BAR; PG8_SCHED;
;             PG8_LDA(At, 0, 1); PG8_STAGE(PG8_SB(0, 0), b2, voffB); PG8_STAGE(PG8_SB(0, 1), b2 + hstep, voffB); PG8_STAGE(PG8_SA(0, 0), a2, voffA);
;             PG8_WAIT_V(8); PG8_WAIT_L(0); PG8_BAR; PG8_MMA(1, 0, At, B0); PG8_MMA(1, 1, At, B1); PG8_BAR; PG8_SCHED;
;             PG8_LDB(B0, 1, 0); PG8_LDB(B1, 1, 1); PG8_SCHED; PG8_LDA(At, 1, 0); PG8_STAGE(PG8_SA(0, 1), a2 + hstep, voffA);
;             PG8_WAIT_V(8); PG8_WAIT_L(0); PG8_BAR; PG8_MMA(0, 0, At, B0); PG8_MMA(0, 1, At, B1); PG8_BAR; PG8_SCHED;
;             PG8_LDA(At, 1, 1); PG8_STAGE(PG8_SB(1, 0), b3, voffB); PG8_STAGE(PG8_SB(1, 1), b3 + hstep, voffB); PG8_STAGE(PG8_SA(1, 0), a3, voffA);
;             PG8_WAIT_V(8); PG8_WAIT_L(0); PG8_BAR; PG8_MMA(1, 0, At, B0); PG8_MMA(1, 1, At, B1); PG8_BAR; PG8_SCHED;
.Lrsc_d_pl:
	s_waitcnt lgkmcnt(0)
	s_barrier
	s_setprio 1
	s_waitcnt lgkmcnt(0)
	v_mfma_f32_16x16x32_bf16 v[124:127], v[146:149], v[190:193], v[124:127]
	v_mfma_f32_16x16x32_bf16 v[120:123], v[154:157], v[190:193], v[120:123]
	v_mfma_f32_16x16x32_bf16 v[108:111], v[146:149], v[198:201], v[108:111]
	v_mfma_f32_16x16x32_bf16 v[104:107], v[154:157], v[198:201], v[104:107]
	v_mfma_f32_16x16x32_bf16 v[92:95], v[146:149], v[206:209], v[92:95]
	v_mfma_f32_16x16x32_bf16 v[88:91], v[154:157], v[206:209], v[88:91]
	v_mfma_f32_16x16x32_bf16 v[76:79], v[146:149], v[214:217], v[76:79]
	v_mfma_f32_16x16x32_bf16 v[72:75], v[154:157], v[214:217], v[72:75]
	v_mfma_f32_16x16x32_bf16 v[124:127], v[150:153], v[194:197], v[124:127]
	v_mfma_f32_16x16x32_bf16 v[120:123], v[170:173], v[194:197], v[120:123]
	v_mfma_f32_16x16x32_bf16 v[108:111], v[150:153], v[202:205], v[108:111]
	v_mfma_f32_16x16x32_bf16 v[104:107], v[170:173], v[202:205], v[104:107]
	v_mfma_f32_16x16x32_bf16 v[92:95], v[150:153], v[210:213], v[92:95]
	v_mfma_f32_16x16x32_bf16 v[88:91], v[170:173], v[210:213], v[88:91]
	v_mfma_f32_16x16x32_bf16 v[76:79], v[150:153], v[218:221], v[76:79]
	v_mfma_f32_16x16x32_bf16 v[72:75], v[170:173], v[218:221], v[72:75]
	s_setprio 0
	s_setprio 1
	v_mfma_f32_16x16x32_bf16 v[116:119], v[174:177], v[190:193], v[116:119]
	v_mfma_f32_16x16x32_bf16 v[112:115], v[182:185], v[190:193], v[112:115]
	v_mfma_f32_16x16x32_bf16 v[100:103], v[174:177], v[198:201], v[100:103]
	v_mfma_f32_16x16x32_bf16 v[96:99], v[182:185], v[198:201], v[96:99]
	v_mfma_f32_16x16x32_bf16 v[84:87], v[174:177], v[206:209], v[84:87]
	v_mfma_f32_16x16x32_bf16 v[80:83], v[182:185], v[206:209], v[80:83]
	v_mfma_f32_16x16x32_bf16 v[68:71], v[174:177], v[214:217], v[68:71]
	v_mfma_f32_16x16x32_bf16 v[64:67], v[182:185], v[214:217], v[64:67]
	v_mfma_f32_16x16x32_bf16 v[116:119], v[178:181], v[194:197], v[116:119]
	v_mfma_f32_16x16x32_bf16 v[112:115], v[186:189], v[194:197], v[112:115]
	v_mfma_f32_16x16x32_bf16 v[100:103], v[178:181], v[202:205], v[100:103]
	v_mfma_f32_16x16x32_bf16 v[96:99], v[186:189], v[202:205], v[96:99]
	v_mfma_f32_16x16x32_bf16 v[84:87], v[178:181], v[210:213], v[84:87]
	v_mfma_f32_16x16x32_bf16 v[80:83], v[186:189], v[210:213], v[80:83]
	v_mfma_f32_16x16x32_bf16 v[68:71], v[178:181], v[218:221], v[68:71]
	v_mfma_f32_16x16x32_bf16 v[64:67], v[186:189], v[218:221], v[64:67]
	s_setprio 0
	s_barrier
	s_add_i32 s48, s60, s25
	v_lshl_add_u64 v[158:159], v[158:159], 0, s[16:17]
	s_mov_b32 m0, s48
	ds_read_b128 v[190:193], v167 offset:49152
	ds_read_b128 v[194:197], v167 offset:50176
	ds_read_b128 v[198:201], v167 offset:51200
	ds_read_b128 v[202:205], v167 offset:52224
	ds_read_b128 v[206:209], v167 offset:53248
	ds_read_b128 v[210:213], v167 offset:54272
	ds_read_b128 v[214:217], v167 offset:55296
	ds_read_b128 v[218:221], v167 offset:56320
	global_load_lds_dwordx4 v[158:159], off
	s_add_i32 m0, s48, 0x2000
	s_add_u32 s46, s46, 0x40080
	v_lshl_add_u64 v[158:159], v[162:163], 0, s[16:17]
	s_addc_u32 s47, s47, 0
	s_add_i32 s48, s61, s25
	global_load_lds_dwordx4 v[158:159], off
	s_mov_b32 m0, s48
	s_nop 0
	global_load_lds_dwordx4 v130, s[46:47]
	s_add_i32 m0, s48, 0x2000
	s_nop 0
	global_load_lds_dwordx4 v134, s[46:47]
	v_lshl_add_u64 v[158:159], v[222:223], 0, s[16:17]
	s_mov_b32 m0, s31
	s_nop 0
	global_load_lds_dwordx4 v[158:159], off
	v_lshl_add_u64 v[158:159], v[224:225], 0, s[16:17]
	s_mov_b32 m0, s33
	s_nop 0
	global_load_lds_dwordx4 v[158:159], off
	s_waitcnt vmcnt(8)
	s_waitcnt lgkmcnt(0)
	s_barrier
	s_setprio 1
	s_waitcnt lgkmcnt(0)
	v_mfma_f32_16x16x32_bf16 v[60:63], v[146:149], v[190:193], v[60:63]
	v_mfma_f32_16x16x32_bf16 v[56:59], v[154:157], v[190:193], v[56:59]
	v_mfma_f32_16x16x32_bf16 v[44:47], v[146:149], v[198:201], v[44:47]
	v_mfma_f32_16x16x32_bf16 v[40:43], v[154:157], v[198:201], v[40:43]
	v_mfma_f32_16x16x32_bf16 v[28:31], v[146:149], v[206:209], v[28:31]
	v_mfma_f32_16x16x32_bf16 v[24:27], v[154:157], v[206:209], v[24:27]
	v_mfma_f32_16x16x32_bf16 v[12:15], v[146:149], v[214:217], v[12:15]
	v_mfma_f32_16x16x32_bf16 v[8:11], v[154:157], v[214:217], v[8:11]
	v_mfma_f32_16x16x32_bf16 v[60:63], v[150:153], v[194:197], v[60:63]
	v_mfma_f32_16x16x32_bf16 v[56:59], v[170:173], v[194:197], v[56:59]
	v_mfma_f32_16x16x32_bf16 v[44:47], v[150:153], v[202:205], v[44:47]
	v_mfma_f32_16x16x32_bf16 v[40:43], v[170:173], v[202:205], v[40:43]
	v_mfma_f32_16x16x32_bf16 v[28:31], v[150:153], v[210:213], v[28:31]
	v_mfma_f32_16x16x32_bf16 v[24:27], v[170:173], v[210:213], v[24:27]
	v_mfma_f32_16x16x32_bf16 v[12:15], v[150:153], v[218:221], v[12:15]
	v_mfma_f32_16x16x32_bf16 v[8:11], v[170:173], v[218:221], v[8:11]
	s_setprio 0
	s_setprio 1
	v_mfma_f32_16x16x32_bf16 v[52:55], v[174:177], v[190:193], v[52:55]
	v_mfma_f32_16x16x32_bf16 v[48:51], v[182:185], v[190:193], v[48:51]
	v_mfma_f32_16x16x32_bf16 v[36:39], v[174:177], v[198:201], v[36:39]
	v_mfma_f32_16x16x32_bf16 v[32:35], v[182:185], v[198:201], v[32:35]
	v_mfma_f32_16x16x32_bf16 v[20:23], v[174:177], v[206:209], v[20:23]
	v_mfma_f32_16x16x32_bf16 v[16:19], v[182:185], v[206:209], v[16:19]
	v_mfma_f32_16x16x32_bf16 v[4:7], v[174:177], v[214:217], v[4:7]
	v_mfma_f32_16x16x32_bf16 v[0:3], v[182:185], v[214:217], v[0:3]
	v_mfma_f32_16x16x32_bf16 v[52:55], v[178:181], v[194:197], v[52:55]
	v_mfma_f32_16x16x32_bf16 v[48:51], v[186:189], v[194:197], v[48:51]
	v_mfma_f32_16x16x32_bf16 v[36:39], v[178:181], v[202:205], v[36:39]
	v_mfma_f32_16x16x32_bf16 v[32:35], v[186:189], v[202:205], v[32:35]
	v_mfma_f32_16x16x32_bf16 v[20:23], v[178:181], v[210:213], v[20:23]
	v_mfma_f32_16x16x32_bf16 v[16:19], v[186:189], v[210:213], v[16:19]
	v_mfma_f32_16x16x32_bf16 v[4:7], v[178:181], v[218:221], v[4:7]
	v_mfma_f32_16x16x32_bf16 v[0:3], v[186:189], v[218:221], v[0:3]
	s_setprio 0
	s_add_i32 s59, s59, 2
	s_add_u32 s0, s0, 0x100
	s_addc_u32 s1, s1, 0
	s_add_u32 s50, s50, 0x100
	s_addc_u32 s51, s51, 0
	s_cmp_gt_u32 s59, 13
	s_barrier

; #define PG8_STAGE(bufoff, gbase, voff) do { _Pragma("unroll") for (int _i = 0; _i < 2; ++_i) \
;         __builtin_amdgcn_global_load_lds((const unsigned*)((const char*)(gbase) + (voff)[_i]), (PG8_LAS unsigned*)(lds + (bufoff) + ldsw + _i * 8192), 16, 0, 0); } while (0)
; #define PG8_LDA(dst, b, h) do { _Pragma("unroll") for (int m = 0; m < 4; ++m) _Pragma("unroll") for (int k = 0; k < 2; ++k) dst[m][k] = *(const PG8_LAS bf16x8*)(lds + PG8_SA(b, h) + aoff + m * 2048 + k * 1024); } while (0)
; #define PG8_LDB(dst, b, h) do { _Pragma("unroll") for (int n = 0; n < 2; ++n) _Pragma("unroll") for (int k = 0; k < 2; ++k) dst[n][k] = *(const PG8_LAS bf16x8*)(lds + PG8_SB(b, h) + boff + n * 2048 + k * 1024); } while (0)
; #define PG8_MMA(ai, bj, At, Bt) do { __builtin_amdgcn_s_setprio(1); _Pragma("unroll") for (int m = 0; m < 4; ++m) _Pragma("unroll") for (int n = 0; n < 2; ++n) _Pragma("unroll") for (int k = 0; k < 2; ++k) \
;         acc[ai][bj][m][n] = __builtin_amdgcn_mfma_f32_16x16x32_bf16(Bt[n][k], At[m][k], acc[ai][bj][m][n], 0, 0, 0); __builtin_amdgcn_s_setprio(0); } while (0)
; #define PG8_WAIT_V(n) asm volatile("s_waitcnt vmcnt(" #n ")" ::: "memory")
; template <class Epi, class Sched, bool ALIGN_EPI = false, bool SP2 = false>
; __device__ __forceinline__ void gemm_phase(PG8_LAS unsigned char* lds, const Gemm g, const Sched& S, const Epi& E) {
;     ...
;             PG8_LDB(B0, 0, 0); PG8_LDB(B1, 0, 1); PG8_SCHED; PG8_LDA(At, 0, 0); PG8_STAGE(PG8_SA(1, 1), a1 + hstep, voffA);
;             PG8_WAIT_V(8); PG8_WAIT_L(0); PG8_BAR; PG8_MMA(0, 0, At, B0); PG8_MMA(0, 1, At, B1); PG8_BAR; PG8_SCHED;
;             PG8_LDA(At, 0, 1); PG8_STAGE(PG8_SB(0, 0), b2, voffB); PG8_STAGE(PG8_SB(0, 1), b2 + hstep, voffB); PG8_STAGE(PG8_SA(0, 0), a2, voffA);
;             PG8_WAIT_V(8); PG8_WAIT_L(0); PG8_BAR; PG8_MMA(1, 0, At, B0); PG8_MMA(1, 1, At, B1); PG8_BAR; PG8_SCHED;
;             PG8_LDB(B0, 1, 0); PG8_LDB(B1, 1, 1); PG8_SCHED; PG8_LDA(At, 1, 0); PG8_STAGE(PG8_SA(0, 1), a2 + hstep, voffA);
;             PG8_WAIT_V(8); PG8_WAIT_L(0); PG8_BAR; PG8_MMA(0, 0, At, B0); PG8_MMA(0, 1, At, B1); PG8_BAR; PG8_SCHED;
;             PG8_LDA(At, 1, 1); PG8_STAGE(PG8_SB(1, 0), b3, voffB); PG8_STAGE(PG8_SB(1, 1), b3 + hstep, voffB); PG8_STAGE(PG8_SA(1, 0), a3, voffA);
;             PG8_WAIT_V(8); PG8_WAIT_L(0); PG8_BAR; PG8_MMA(1, 0, At, B0); PG8_MMA(1, 1, At, B1); PG8_BAR; PG8_SCHED;
.Lrsc_d:
	s_waitcnt lgkmcnt(0)
	s_barrier
	s_setprio 1
	s_waitcnt lgkmcnt(0)
	v_mfma_f32_16x16x32_bf16 v[124:127], v[146:149], v[190:193], v[124:127]
	v_mfma_f32_16x16x32_bf16 v[120:123], v[154:157], v[190:193], v[120:123]
	v_mfma_f32_16x16x32_bf16 v[108:111], v[146:149], v[198:201], v[108:111]
	v_mfma_f32_16x16x32_bf16 v[104:107], v[154:157], v[198:201], v[104:107]
	v_mfma_f32_16x16x32_bf16 v[92:95], v[146:149], v[206:209], v[92:95]
	v_mfma_f32_16x16x32_bf16 v[88:91], v[154:157], v[206:209], v[88:91]
	v_mfma_f32_16x16x32_bf16 v[76:79], v[146:149], v[214:217], v[76:79]
	v_mfma_f32_16x16x32_bf16 v[72:75], v[154:157], v[214:217], v[72:75]
	v_mfma_f32_16x16x32_bf16 v[124:127], v[150:153], v[194:197], v[124:127]
	v_mfma_f32_16x16x32_bf16 v[120:123], v[170:173], v[194:197], v[120:123]
	v_mfma_f32_16x16x32_bf16 v[108:111], v[150:153], v[202:205], v[108:111]
	v_mfma_f32_16x16x32_bf16 v[104:107], v[170:173], v[202:205], v[104:107]
	v_mfma_f32_16x16x32_bf16 v[92:95], v[150:153], v[210:213], v[92:95]
	v_mfma_f32_16x16x32_bf16 v[88:91], v[170:173], v[210:213], v[88:91]
	v_mfma_f32_16x16x32_bf16 v[76:79], v[150:153], v[218:221], v[76:79]
	v_mfma_f32_16x16x32_bf16 v[72:75], v[170:173], v[218:221], v[72:75]
	s_setprio 0
	s_setprio 1
	v_mfma_f32_16x16x32_bf16 v[116:119], v[174:177], v[190:193], v[116:119]
	v_mfma_f32_16x16x32_bf16 v[112:115], v[182:185], v[190:193], v[112:115]
	v_mfma_f32_16x16x32_bf16 v[100:103], v[174:177], v[198:201], v[100:103]
	v_mfma_f32_16x16x32_bf16 v[96:99], v[182:185], v[198:201], v[96:99]
	v_mfma_f32_16x16x32_bf16 v[84:87], v[174:177], v[206:209], v[84:87]
	v_mfma_f32_16x16x32_bf16 v[80:83], v[182:185], v[206:209], v[80:83]
	v_mfma_f32_16x16x32_bf16 v[68:71], v[174:177], v[214:217], v[68:71]
	v_mfma_f32_16x16x32_bf16 v[64:67], v[182:185], v[214:217], v[64:67]
	v_mfma_f32_16x16x32_bf16 v[116:119], v[178:181], v[194:197], v[116:119]
	v_mfma_f32_16x16x32_bf16 v[112:115], v[186:189], v[194:197], v[112:115]
	v_mfma_f32_16x16x32_bf16 v[100:103], v[178:181], v[202:205], v[100:103]
	v_mfma_f32_16x16x32_bf16 v[96:99], v[186:189], v[202:205], v[96:99]
	v_mfma_f32_16x16x32_bf16 v[84:87], v[178:181], v[210:213], v[84:87]
	v_mfma_f32_16x16x32_bf16 v[80:83], v[186:189], v[210:213], v[80:83]
	v_mfma_f32_16x16x32_bf16 v[68:71], v[178:181], v[218:221], v[68:71]
	v_mfma_f32_16x16x32_bf16 v[64:67], v[186:189], v[218:221], v[64:67]
	s_setprio 0
	s_barrier
	s_add_i32 s48, s60, s25
	v_lshl_add_u64 v[158:159], v[158:159], 0, s[16:17]
	s_mov_b32 m0, s48
	ds_read_b128 v[190:193], v167 offset:49152
	ds_read_b128 v[194:197], v167 offset:50176
	ds_read_b128 v[198:201], v167 offset:51200
	ds_read_b128 v[202:205], v167 offset:52224
	ds_read_b128 v[206:209], v167 offset:53248
	ds_read_b128 v[210:213], v167 offset:54272
	ds_read_b128 v[214:217], v167 offset:55296
	ds_read_b128 v[218:221], v167 offset:56320
	global_load_lds_dwordx4 v[158:159], off
	s_add_i32 m0, s48, 0x2000
	s_add_u32 s46, s46, 0x40080
	v_lshl_add_u64 v[158:159], v[162:163], 0, s[16:17]
	s_addc_u32 s47, s47, 0
	s_add_i32 s48, s61, s25
	global_load_lds_dwordx4 v[158:159], off
	s_mov_b32 m0, s48
	s_nop 0
	global_load_lds_dwordx4 v130, s[46:47]
	s_add_i32 m0, s48, 0x2000
	s_nop 0
	global_load_lds_dwordx4 v134, s[46:47]
	v_lshl_add_u64 v[158:159], v[222:223], 0, s[16:17]
	s_mov_b32 m0, s31
	s_nop 0
	global_load_lds_dwordx4 v[158:159], off
	v_lshl_add_u64 v[158:159], v[224:225], 0, s[16:17]
	s_mov_b32 m0, s33
	s_nop 0
	global_load_lds_dwordx4 v[158:159], off
	s_waitcnt vmcnt(8)
	s_waitcnt lgkmcnt(0)
	s_barrier
	s_setprio 1
	s_waitcnt lgkmcnt(0)
	v_mfma_f32_16x16x32_bf16 v[60:63], v[146:149], v[190:193], v[60:63]
	v_mfma_f32_16x16x32_bf16 v[56:59], v[154:157], v[190:193], v[56:59]
	v_mfma_f32_16x16x32_bf16 v[44:47], v[146:149], v[198:201], v[44:47]
	v_mfma_f32_16x16x32_bf16 v[40:43], v[154:157], v[198:201], v[40:43]
	v_mfma_f32_16x16x32_bf16 v[28:31], v[146:149], v[206:209], v[28:31]
	v_mfma_f32_16x16x32_bf16 v[24:27], v[154:157], v[206:209], v[24:27]
	v_mfma_f32_16x16x32_bf16 v[12:15], v[146:149], v[214:217], v[12:15]
	v_mfma_f32_16x16x32_bf16 v[8:11], v[154:157], v[214:217], v[8:11]
	v_mfma_f32_16x16x32_bf16 v[60:63], v[150:153], v[194:197], v[60:63]
	v_mfma_f32_16x16x32_bf16 v[56:59], v[170:173], v[194:197], v[56:59]
	v_mfma_f32_16x16x32_bf16 v[44:47], v[150:153], v[202:205], v[44:47]
	v_mfma_f32_16x16x32_bf16 v[40:43], v[170:173], v[202:205], v[40:43]
	v_mfma_f32_16x16x32_bf16 v[28:31], v[150:153], v[210:213], v[28:31]
	v_mfma_f32_16x16x32_bf16 v[24:27], v[170:173], v[210:213], v[24:27]
	v_mfma_f32_16x16x32_bf16 v[12:15], v[150:153], v[218:221], v[12:15]
	v_mfma_f32_16x16x32_bf16 v[8:11], v[170:173], v[218:221], v[8:11]
	s_setprio 0
	s_setprio 1
	v_mfma_f32_16x16x32_bf16 v[52:55], v[174:177], v[190:193], v[52:55]
	v_mfma_f32_16x16x32_bf16 v[48:51], v[182:185], v[190:193], v[48:51]
	v_mfma_f32_16x16x32_bf16 v[36:39], v[174:177], v[198:201], v[36:39]
	v_mfma_f32_16x16x32_bf16 v[32:35], v[182:185], v[198:201], v[32:35]
	v_mfma_f32_16x16x32_bf16 v[20:23], v[174:177], v[206:209], v[20:23]
	v_mfma_f32_16x16x32_bf16 v[16:19], v[182:185], v[206:209], v[16:19]
	v_mfma_f32_16x16x32_bf16 v[4:7], v[174:177], v[214:217], v[4:7]
	v_mfma_f32_16x16x32_bf16 v[0:3], v[182:185], v[214:217], v[0:3]
	v_mfma_f32_16x16x32_bf16 v[52:55], v[178:181], v[194:197], v[52:55]
	v_mfma_f32_16x16x32_bf16 v[48:51], v[186:189], v[194:197], v[48:51]
	v_mfma_f32_16x16x32_bf16 v[36:39], v[178:181], v[202:205], v[36:39]
	v_mfma_f32_16x16x32_bf16 v[32:35], v[186:189], v[202:205], v[32:35]
	v_mfma_f32_16x16x32_bf16 v[20:23], v[178:181], v[210:213], v[20:23]
	v_mfma_f32_16x16x32_bf16 v[16:19], v[186:189], v[210:213], v[16:19]
	v_mfma_f32_16x16x32_bf16 v[4:7], v[178:181], v[218:221], v[4:7]
	v_mfma_f32_16x16x32_bf16 v[0:3], v[186:189], v[218:221], v[0:3]
	s_setprio 0
	s_add_i32 s59, s59, 2
	s_add_u32 s0, s0, 0x100
	s_addc_u32 s1, s1, 0
	s_add_u32 s50, s50, 0x100
	s_addc_u32 s51, s51, 0
	s_cmp_gt_u32 s59, 13
	s_barrier
	s_cbranch_scc0 .LBB0_660
	s_and_b64 vcc, exec, s[18:19]
	s_cbranch_vccz .LBB0_663
	s_barrier

; #define PG8_STAGE(bufoff, gbase, voff) do { _Pragma("unroll") for (int _i = 0; _i < 2; ++_i) \
;         __builtin_amdgcn_global_load_lds((const unsigned*)((const char*)(gbase) + (voff)[_i]), (PG8_LAS unsigned*)(lds + (bufoff) + ldsw + _i * 8192), 16, 0, 0); } while (0)
; #define PG8_LDA(dst, b, h) do { _Pragma("unroll") for (int m = 0; m < 4; ++m) _Pragma("unroll") for (int k = 0; k < 2; ++k) dst[m][k] = *(const PG8_LAS bf16x8*)(lds + PG8_SA(b, h) + aoff + m * 2048 + k * 1024); } while (0)
; #define PG8_LDB(dst, b, h) do { _Pragma("unroll") for (int n = 0; n < 2; ++n) _Pragma("unroll") for (int k = 0; k < 2; ++k) dst[n][k] = *(const PG8_LAS bf16x8*)(lds + PG8_SB(b, h) + boff + n * 2048 + k * 1024); } while (0)
; #define PG8_WAIT_V(n) asm volatile("s_waitcnt vmcnt(" #n ")" ::: "memory")
; #define PG8_WAIT_L(n) asm volatile("s_waitcnt lgkmcnt(" #n ")" ::: "memory")
; #define PG8_BAR __builtin_amdgcn_s_barrier()
; #define PG8_SCHED __builtin_amdgcn_sched_barrier(0)
; template <class Epi, class Sched, bool ALIGN_EPI = false, bool SP2 = false>
; __device__ __forceinline__ void gemm_phase(PG8_LAS unsigned char* lds, const Gemm g, const Sched& S, const Epi& E) {
;     ...
;         const bool has_next = S.next(ui + 1, nxt);
;         const char* nA = has_next ? (const char*)g.A + (size_t)nxt.pm * tstep : cA; const char* nB = has_next ? (const char*)g.Bt + (size_t)nxt.pn * tstep : cB;
;         for (int t = 0; t < nt; t += 2) {
;             const bool last = (t == nt - 2);
;             const char* a1 = cA + (size_t)(t + 1) * kstep;
;             const char* a2 = last ? nA : cA + (size_t)(t + 2) * kstep; const char* b2 = last ? nB : cB + (size_t)(t + 2) * kstep;
;             const char* a3 = a2 + kstep; const char* b3 = b2 + kstep;
;             if (last && has_next) S.a_ready(nxt);
;             if constexpr (SP2) {
;             PG8_LDB(B0, 0, 0); PG8_LDB(B1, 0, 1); PG8_SCHED; PG8_LDA(At, 0, 0); PG8_STAGE(PG8_SA(1, 1), a1 + hstep, voffA);
;             PG8_WAIT_V(8); PG8_WAIT_L(0); PG8_BAR; PG8_MMA(0, 0, At, B0); PG8_MMA(0, 1, At, B1); PG8_BAR; PG8_SCHED;
;             PG8_LDA(At, 0, 1); PG8_STAGE(PG8_SB(0, 0), b2, voffB); PG8_STAGE(PG8_SB(0, 1), b2 + hstep, voffB); PG8_STAGE(PG8_SA(0, 0), a2, voffA);
;             PG8_WAIT_V(8); PG8_WAIT_L(0); PG8_BAR; PG8_MMA(1, 0, At, B0); PG8_MMA(1, 1, At, B1); PG8_BAR; PG8_SCHED;
.LBB0_887:
	s_ashr_i32 s23, s22, 31
	s_lshl_b64 s[26:27], s[22:23], 19
	s_add_u32 s26, s68, s26
	s_addc_u32 s27, s69, s27
	s_and_b64 s[28:29], s[24:25], exec
	s_cselect_b32 s23, s27, s37
	s_cselect_b32 s31, s26, s36
	s_ashr_i32 s21, s20, 31
	s_lshl_b64 s[28:29], s[20:21], 19
	s_add_u32 s28, s42, s28
	s_addc_u32 s29, s43, s29
	s_and_b64 s[40:41], s[24:25], exec
	s_cselect_b32 s21, s29, s39
	s_cselect_b32 s58, s28, s38
	s_add_u32 s36, s36, 0x40080
	s_addc_u32 s37, s37, 0
	s_add_u32 s59, s38, 0x100
	s_addc_u32 s60, s39, 0
	s_mov_b32 s61, -2
	s_waitcnt lgkmcnt(0)
	ds_read_b128 v[124:127], v234
	ds_read_b128 v[132:135], v234 offset:1024
	ds_read_b128 v[136:139], v234 offset:2048
	ds_read_b128 v[140:143], v234 offset:3072
	ds_read_b128 v[144:147], v235
	ds_read_b128 v[148:151], v235 offset:1024
	ds_read_b128 v[152:155], v235 offset:2048
	ds_read_b128 v[156:159], v235 offset:3072
	s_add_u32 s38, s36, 0xfffc0080
	s_addc_u32 s39, s37, -1
	s_cmp_eq_u32 s61, 12
	s_cselect_b32 s41, s23, s39
	s_cselect_b32 s40, s31, s38
	s_cselect_b32 s39, s21, s60
	s_cselect_b32 s38, s58, s59
	s_add_i32 m0, s45, 0xc000
	ds_read_b128 v[160:163], v236
	ds_read_b128 v[164:167], v236 offset:1024
	ds_read_b128 v[168:171], v236 offset:2048
	ds_read_b128 v[172:175], v236 offset:3072
	ds_read_b128 v[176:179], v236 offset:4096
	ds_read_b128 v[180:183], v236 offset:5120
	ds_read_b128 v[198:201], v236 offset:6144
	ds_read_b128 v[202:205], v236 offset:7168
	global_load_lds_dwordx4 v192, s[36:37]
	s_add_i32 m0, s45, 0xe000
	s_nop 0
	global_load_lds_dwordx4 v194, s[36:37]
	s_waitcnt vmcnt(8)
	s_waitcnt lgkmcnt(0)
	s_barrier
	s_setprio 1
	s_waitcnt lgkmcnt(0)
	v_mfma_f32_16x16x32_bf16 v[128:131], v[124:127], v[160:163], 0
	v_mfma_f32_16x16x32_bf16 v[120:123], v[136:139], v[160:163], 0
	v_mfma_f32_16x16x32_bf16 v[108:111], v[124:127], v[168:171], 0
	v_mfma_f32_16x16x32_bf16 v[104:107], v[136:139], v[168:171], 0
	v_mfma_f32_16x16x32_bf16 v[92:95], v[124:127], v[176:179], 0
	v_mfma_f32_16x16x32_bf16 v[88:91], v[136:139], v[176:179], 0
	v_mfma_f32_16x16x32_bf16 v[76:79], v[124:127], v[198:201], 0
	v_mfma_f32_16x16x32_bf16 v[72:75], v[136:139], v[198:201], 0
	v_mfma_f32_16x16x32_bf16 v[128:131], v[132:135], v[164:167], v[128:131]
	v_mfma_f32_16x16x32_bf16 v[120:123], v[140:143], v[164:167], v[120:123]
	v_mfma_f32_16x16x32_bf16 v[108:111], v[132:135], v[172:175], v[108:111]
	v_mfma_f32_16x16x32_bf16 v[104:107], v[140:143], v[172:175], v[104:107]
	v_mfma_f32_16x16x32_bf16 v[92:95], v[132:135], v[180:183], v[92:95]
	v_mfma_f32_16x16x32_bf16 v[88:91], v[140:143], v[180:183], v[88:91]
	v_mfma_f32_16x16x32_bf16 v[76:79], v[132:135], v[202:205], v[76:79]
	v_mfma_f32_16x16x32_bf16 v[72:75], v[140:143], v[202:205], v[72:75]
	s_setprio 0
	s_setprio 1
	v_mfma_f32_16x16x32_bf16 v[116:119], v[144:147], v[160:163], 0
	v_mfma_f32_16x16x32_bf16 v[112:115], v[152:155], v[160:163], 0
	v_mfma_f32_16x16x32_bf16 v[100:103], v[144:147], v[168:171], 0
	v_mfma_f32_16x16x32_bf16 v[96:99], v[152:155], v[168:171], 0
	v_mfma_f32_16x16x32_bf16 v[84:87], v[144:147], v[176:179], 0
	v_mfma_f32_16x16x32_bf16 v[80:83], v[152:155], v[176:179], 0
	v_mfma_f32_16x16x32_bf16 v[68:71], v[144:147], v[198:201], 0
	v_mfma_f32_16x16x32_bf16 v[64:67], v[152:155], v[198:201], 0
	v_mfma_f32_16x16x32_bf16 v[116:119], v[148:151], v[164:167], v[116:119]
	v_mfma_f32_16x16x32_bf16 v[112:115], v[156:159], v[164:167], v[112:115]
	v_mfma_f32_16x16x32_bf16 v[100:103], v[148:151], v[172:175], v[100:103]
	v_mfma_f32_16x16x32_bf16 v[96:99], v[156:159], v[172:175], v[96:99]
	v_mfma_f32_16x16x32_bf16 v[84:87], v[148:151], v[180:183], v[84:87]
	v_mfma_f32_16x16x32_bf16 v[80:83], v[156:159], v[180:183], v[80:83]
	v_mfma_f32_16x16x32_bf16 v[68:71], v[148:151], v[202:205], v[68:71]
	v_mfma_f32_16x16x32_bf16 v[64:67], v[156:159], v[202:205], v[64:67]
	s_setprio 0
	s_barrier
	s_add_i32 s62, s55, s44
	v_lshl_add_u64 v[206:207], s[38:39], 0, v[186:187]
	s_mov_b32 m0, s62
	ds_read_b128 v[160:163], v236 offset:16384
	ds_read_b128 v[164:167], v236 offset:17408
	ds_read_b128 v[168:171], v236 offset:18432
	ds_read_b128 v[172:175], v236 offset:19456
	ds_read_b128 v[176:179], v236 offset:20480
	ds_read_b128 v[180:183], v236 offset:21504
	ds_read_b128 v[198:201], v236 offset:22528
	ds_read_b128 v[202:205], v236 offset:23552
	global_load_lds_dwordx4 v[206:207], off
	s_add_i32 m0, s62, 0x2000
	s_add_u32 s62, s38, 0x40000
	v_lshl_add_u64 v[208:209], s[38:39], 0, v[190:191]
	s_addc_u32 s63, s39, 0
	s_add_i32 s64, s56, s44
	global_load_lds_dwordx4 v[208:209], off
	s_mov_b32 m0, s64
	v_lshl_add_u64 v[212:213], s[40:41], 0, v[188:189]
	global_load_lds_dwordx4 v186, s[62:63]
	s_add_i32 m0, s64, 0x2000
	s_nop 0
	global_load_lds_dwordx4 v190, s[62:63]
	v_lshl_add_u64 v[210:211], s[40:41], 0, v[184:185]
	s_mov_b32 m0, s45
	s_nop 0
	global_load_lds_dwordx4 v[210:211], off
	s_mov_b32 m0, s46
	s_nop 0
	global_load_lds_dwordx4 v[212:213], off
	s_waitcnt vmcnt(8)
	s_waitcnt lgkmcnt(0)
	s_barrier
; #define PG8_STAGE(bufoff, gbase, voff) do { _Pragma("unroll") for (int _i = 0; _i < 2; ++_i) \
;         __builtin_amdgcn_global_load_lds((const unsigned*)((const char*)(gbase) + (voff)[_i]), (PG8_LAS unsigned*)(lds + (bufoff) + ldsw + _i * 8192), 16, 0, 0); } while (0)
; #define PG8_LDA(dst, b, h) do { _Pragma("unroll") for (int m = 0; m < 4; ++m) _Pragma("unroll") for (int k = 0; k < 2; ++k) dst[m][k] = *(const PG8_LAS bf16x8*)(lds + PG8_SA(b, h) + aoff + m * 2048 + k * 1024); } while (0)
; #define PG8_LDB(dst, b, h) do { _Pragma("unroll") for (int n = 0; n < 2; ++n) _Pragma("unroll") for (int k = 0; k < 2; ++k) dst[n][k] = *(const PG8_LAS bf16x8*)(lds + PG8_SB(b, h) + boff + n * 2048 + k * 1024); } while (0)
; #define PG8_MMA(ai, bj, At, Bt) do { __builtin_amdgcn_s_setprio(1); _Pragma("unroll") for (int m = 0; m < 4; ++m) _Pragma("unroll") for (int n = 0; n < 2; ++n) _Pragma("unroll") for (int k = 0; k < 2; ++k) \
;         acc[ai][bj][m][n] = __builtin_amdgcn_mfma_f32_16x16x32_bf16(Bt[n][k], At[m][k], acc[ai][bj][m][n], 0, 0, 0); __builtin_amdgcn_s_setprio(0); } while (0)
; #define PG8_WAIT_V(n) asm volatile("s_waitcnt vmcnt(" #n ")" ::: "memory")
; #define PG8_WAIT_L(n) asm volatile("s_waitcnt lgkmcnt(" #n ")" ::: "memory")
; #define PG8_BAR __builtin_amdgcn_s_barrier()
; #define PG8_SCHED __builtin_amdgcn_sched_barrier(0)
; template <class Epi, class Sched, bool ALIGN_EPI = false, bool SP2 = false>
; __device__ __forceinline__ void gemm_phase(PG8_LAS unsigned char* lds, const Gemm g, const Sched& S, const Epi& E) {
;     ...
;             PG8_WAIT_V(8); PG8_WAIT_L(0); PG8_BAR; PG8_MMA(0, 0, At, B0); PG8_MMA(0, 1, At, B1); PG8_BAR; PG8_SCHED;
;             PG8_LDA(At, 0, 1); PG8_STAGE(PG8_SB(0, 0), b2, voffB); PG8_STAGE(PG8_SB(0, 1), b2 + hstep, voffB); PG8_STAGE(PG8_SA(0, 0), a2, voffA);
;             PG8_WAIT_V(8); PG8_WAIT_L(0); PG8_BAR; PG8_MMA(1, 0, At, B0); PG8_MMA(1, 1, At, B1); PG8_BAR; PG8_SCHED;
;             PG8_LDB(B0, 1, 0); PG8_LDB(B1, 1, 1); PG8_SCHED; PG8_LDA(At, 1, 0); PG8_STAGE(PG8_SA(0, 1), a2 + hstep, voffA);
;             PG8_WAIT_V(8); PG8_WAIT_L(0); PG8_BAR; PG8_MMA(0, 0, At, B0); PG8_MMA(0, 1, At, B1); PG8_BAR; PG8_SCHED;
	s_setprio 1
	s_waitcnt lgkmcnt(0)
	v_mfma_f32_16x16x32_bf16 v[60:63], v[124:127], v[160:163], 0
	v_mfma_f32_16x16x32_bf16 v[56:59], v[136:139], v[160:163], 0
	v_mfma_f32_16x16x32_bf16 v[44:47], v[124:127], v[168:171], 0
	v_mfma_f32_16x16x32_bf16 v[40:43], v[136:139], v[168:171], 0
	v_mfma_f32_16x16x32_bf16 v[28:31], v[124:127], v[176:179], 0
	v_mfma_f32_16x16x32_bf16 v[24:27], v[136:139], v[176:179], 0
	v_mfma_f32_16x16x32_bf16 v[12:15], v[124:127], v[198:201], 0
	v_mfma_f32_16x16x32_bf16 v[8:11], v[136:139], v[198:201], 0
	v_mfma_f32_16x16x32_bf16 v[60:63], v[132:135], v[164:167], v[60:63]
	v_mfma_f32_16x16x32_bf16 v[56:59], v[140:143], v[164:167], v[56:59]
	v_mfma_f32_16x16x32_bf16 v[44:47], v[132:135], v[172:175], v[44:47]
	v_mfma_f32_16x16x32_bf16 v[40:43], v[140:143], v[172:175], v[40:43]
	v_mfma_f32_16x16x32_bf16 v[28:31], v[132:135], v[180:183], v[28:31]
	v_mfma_f32_16x16x32_bf16 v[24:27], v[140:143], v[180:183], v[24:27]
	v_mfma_f32_16x16x32_bf16 v[12:15], v[132:135], v[202:205], v[12:15]
	v_mfma_f32_16x16x32_bf16 v[8:11], v[140:143], v[202:205], v[8:11]
	s_setprio 0
	s_setprio 1
	v_mfma_f32_16x16x32_bf16 v[52:55], v[144:147], v[160:163], 0
	v_mfma_f32_16x16x32_bf16 v[48:51], v[152:155], v[160:163], 0
	v_mfma_f32_16x16x32_bf16 v[36:39], v[144:147], v[168:171], 0
	v_mfma_f32_16x16x32_bf16 v[32:35], v[152:155], v[168:171], 0
	v_mfma_f32_16x16x32_bf16 v[20:23], v[144:147], v[176:179], 0
	v_mfma_f32_16x16x32_bf16 v[16:19], v[152:155], v[176:179], 0
	v_mfma_f32_16x16x32_bf16 v[4:7], v[144:147], v[198:201], 0
	v_mfma_f32_16x16x32_bf16 v[0:3], v[152:155], v[198:201], 0
	v_mfma_f32_16x16x32_bf16 v[52:55], v[148:151], v[164:167], v[52:55]
	v_mfma_f32_16x16x32_bf16 v[48:51], v[156:159], v[164:167], v[48:51]
	v_mfma_f32_16x16x32_bf16 v[36:39], v[148:151], v[172:175], v[36:39]
	v_mfma_f32_16x16x32_bf16 v[32:35], v[156:159], v[172:175], v[32:35]
	v_mfma_f32_16x16x32_bf16 v[20:23], v[148:151], v[180:183], v[20:23]
	v_mfma_f32_16x16x32_bf16 v[16:19], v[156:159], v[180:183], v[16:19]
	v_mfma_f32_16x16x32_bf16 v[4:7], v[148:151], v[202:205], v[4:7]
	v_mfma_f32_16x16x32_bf16 v[0:3], v[156:159], v[202:205], v[0:3]
	s_setprio 0
	s_barrier
	s_add_i32 s62, 0, 0x18000
	s_add_i32 s63, 0, 0x1c000
	v_add_u32_e32 v140, s62, v232
	v_add_u32_e32 v156, s63, v232
	ds_read_b128 v[124:127], v140
	ds_read_b128 v[132:135], v140 offset:1024
	ds_read_b128 v[136:139], v140 offset:2048
	ds_read_b128 v[140:143], v140 offset:3072
	ds_read_b128 v[144:147], v156
	ds_read_b128 v[148:151], v156 offset:1024
	ds_read_b128 v[152:155], v156 offset:2048
	ds_read_b128 v[156:159], v156 offset:3072
	s_add_u32 s40, s40, 0x40000
	s_addc_u32 s41, s41, 0
	s_mov_b32 m0, s47
	ds_read_b128 v[160:163], v236 offset:32768
	ds_read_b128 v[164:167], v236 offset:33792
	ds_read_b128 v[168:171], v236 offset:34816
	ds_read_b128 v[172:175], v236 offset:35840
	ds_read_b128 v[176:179], v236 offset:36864
	ds_read_b128 v[180:183], v236 offset:37888
	ds_read_b128 v[198:201], v236 offset:38912
	ds_read_b128 v[202:205], v236 offset:39936
	global_load_lds_dwordx4 v184, s[40:41]
	v_lshl_add_u64 v[214:215], s[40:41], 0, v[188:189]
	s_mov_b32 m0, s48
	s_nop 0
	global_load_lds_dwordx4 v[214:215], off
	s_waitcnt vmcnt(8)
	s_waitcnt lgkmcnt(0)
	s_barrier
	s_setprio 1
	s_waitcnt lgkmcnt(0)
	v_mfma_f32_16x16x32_bf16 v[128:131], v[124:127], v[160:163], v[128:131]
	v_mfma_f32_16x16x32_bf16 v[120:123], v[136:139], v[160:163], v[120:123]
	v_mfma_f32_16x16x32_bf16 v[108:111], v[124:127], v[168:171], v[108:111]
	v_mfma_f32_16x16x32_bf16 v[104:107], v[136:139], v[168:171], v[104:107]
	v_mfma_f32_16x16x32_bf16 v[92:95], v[124:127], v[176:179], v[92:95]
	v_mfma_f32_16x16x32_bf16 v[88:91], v[136:139], v[176:179], v[88:91]
	v_mfma_f32_16x16x32_bf16 v[76:79], v[124:127], v[198:201], v[76:79]
	v_mfma_f32_16x16x32_bf16 v[72:75], v[136:139], v[198:201], v[72:75]
	v_mfma_f32_16x16x32_bf16 v[128:131], v[132:135], v[164:167], v[128:131]
	v_mfma_f32_16x16x32_bf16 v[120:123], v[140:143], v[164:167], v[120:123]
	v_mfma_f32_16x16x32_bf16 v[108:111], v[132:135], v[172:175], v[108:111]
	v_mfma_f32_16x16x32_bf16 v[104:107], v[140:143], v[172:175], v[104:107]
	v_mfma_f32_16x16x32_bf16 v[92:95], v[132:135], v[180:183], v[92:95]
	v_mfma_f32_16x16x32_bf16 v[88:91], v[140:143], v[180:183], v[88:91]
	v_mfma_f32_16x16x32_bf16 v[76:79], v[132:135], v[202:205], v[76:79]
	v_mfma_f32_16x16x32_bf16 v[72:75], v[140:143], v[202:205], v[72:75]
	s_setprio 0
	s_setprio 1
	v_mfma_f32_16x16x32_bf16 v[116:119], v[144:147], v[160:163], v[116:119]
	v_mfma_f32_16x16x32_bf16 v[112:115], v[152:155], v[160:163], v[112:115]
	v_mfma_f32_16x16x32_bf16 v[100:103], v[144:147], v[168:171], v[100:103]
	v_mfma_f32_16x16x32_bf16 v[96:99], v[152:155], v[168:171], v[96:99]
	v_mfma_f32_16x16x32_bf16 v[84:87], v[144:147], v[176:179], v[84:87]
	v_mfma_f32_16x16x32_bf16 v[80:83], v[152:155], v[176:179], v[80:83]
	v_mfma_f32_16x16x32_bf16 v[68:71], v[144:147], v[198:201], v[68:71]
	v_mfma_f32_16x16x32_bf16 v[64:67], v[152:155], v[198:201], v[64:67]
	v_mfma_f32_16x16x32_bf16 v[116:119], v[148:151], v[164:167], v[116:119]
	v_mfma_f32_16x16x32_bf16 v[112:115], v[156:159], v[164:167], v[112:115]
	v_mfma_f32_16x16x32_bf16 v[100:103], v[148:151], v[172:175], v[100:103]
	v_mfma_f32_16x16x32_bf16 v[96:99], v[156:159], v[172:175], v[96:99]
	v_mfma_f32_16x16x32_bf16 v[84:87], v[148:151], v[180:183], v[84:87]
	v_mfma_f32_16x16x32_bf16 v[80:83], v[156:159], v[180:183], v[80:83]
	v_mfma_f32_16x16x32_bf16 v[68:71], v[148:151], v[202:205], v[68:71]
	v_mfma_f32_16x16x32_bf16 v[64:67], v[156:159], v[202:205], v[64:67]
	s_setprio 0
	s_barrier
; #define PG8_STAGE(bufoff, gbase, voff) do { _Pragma("unroll") for (int _i = 0; _i < 2; ++_i) \
;         __builtin_amdgcn_global_load_lds((const unsigned*)((const char*)(gbase) + (voff)[_i]), (PG8_LAS unsigned*)(lds + (bufoff) + ldsw + _i * 8192), 16, 0, 0); } while (0)
; #define PG8_LDA(dst, b, h) do { _Pragma("unroll") for (int m = 0; m < 4; ++m) _Pragma("unroll") for (int k = 0; k < 2; ++k) dst[m][k] = *(const PG8_LAS bf16x8*)(lds + PG8_SA(b, h) + aoff + m * 2048 + k * 1024); } while (0)
; #define PG8_LDB(dst, b, h) do { _Pragma("unroll") for (int n = 0; n < 2; ++n) _Pragma("unroll") for (int k = 0; k < 2; ++k) dst[n][k] = *(const PG8_LAS bf16x8*)(lds + PG8_SB(b, h) + boff + n * 2048 + k * 1024); } while (0)
; #define PG8_MMA(ai, bj, At, Bt) do { __builtin_amdgcn_s_setprio(1); _Pragma("unroll") for (int m = 0; m < 4; ++m) _Pragma("unroll") for (int n = 0; n < 2; ++n) _Pragma("unroll") for (int k = 0; k < 2; ++k) \
;         acc[ai][bj][m][n] = __builtin_amdgcn_mfma_f32_16x16x32_bf16(Bt[n][k], At[m][k], acc[ai][bj][m][n], 0, 0, 0); __builtin_amdgcn_s_setprio(0); } while (0)
; #define PG8_WAIT_V(n) asm volatile("s_waitcnt vmcnt(" #n ")" ::: "memory")
; template <class Epi, class Sched, bool ALIGN_EPI = false, bool SP2 = false>
; __device__ __forceinline__ void gemm_phase(PG8_LAS unsigned char* lds, const Gemm g, const Sched& S, const Epi& E) {
;     ...
;             PG8_LDB(B0, 0, 0); PG8_LDB(B1, 0, 1); PG8_SCHED; PG8_LDA(At, 0, 0); PG8_STAGE(PG8_SA(1, 1), a1 + hstep, voffA);
;             PG8_WAIT_V(8); PG8_WAIT_L(0); PG8_BAR; PG8_MMA(0, 0, At, B0); PG8_MMA(0, 1, At, B1); PG8_BAR; PG8_SCHED;
;             PG8_LDA(At, 0, 1); PG8_STAGE(PG8_SB(0, 0), b2, voffB); PG8_STAGE(PG8_SB(0, 1), b2 + hstep, voffB); PG8_STAGE(PG8_SA(0, 0), a2, voffA);
;             PG8_WAIT_V(8); PG8_WAIT_L(0); PG8_BAR; PG8_MMA(1, 0, At, B0); PG8_MMA(1, 1, At, B1); PG8_BAR; PG8_SCHED;
;             PG8_LDB(B0, 1, 0); PG8_LDB(B1, 1, 1); PG8_SCHED; PG8_LDA(At, 1, 0); PG8_STAGE(PG8_SA(0, 1), a2 + hstep, voffA);
;             PG8_WAIT_V(8); PG8_WAIT_L(0); PG8_BAR; PG8_MMA(0, 0, At, B0); PG8_MMA(0, 1, At, B1); PG8_BAR; PG8_SCHED;
;             PG8_LDA(At, 1, 1); PG8_STAGE(PG8_SB(1, 0), b3, voffB); PG8_STAGE(PG8_SB(1, 1), b3 + hstep, voffB); PG8_STAGE(PG8_SA(1, 0), a3, voffA);
;             PG8_WAIT_V(8); PG8_WAIT_L(0); PG8_BAR; PG8_MMA(1, 0, At, B0); PG8_MMA(1, 1, At, B1); PG8_BAR; PG8_SCHED;
	s_add_i32 s40, s62, s44
	v_lshl_add_u64 v[206:207], v[206:207], 0, s[16:17]
	s_mov_b32 m0, s40
	ds_read_b128 v[160:163], v236 offset:49152
	ds_read_b128 v[164:167], v236 offset:50176
	ds_read_b128 v[168:171], v236 offset:51200
	ds_read_b128 v[172:175], v236 offset:52224
	ds_read_b128 v[176:179], v236 offset:53248
	ds_read_b128 v[180:183], v236 offset:54272
	ds_read_b128 v[198:201], v236 offset:55296
	ds_read_b128 v[202:205], v236 offset:56320
	global_load_lds_dwordx4 v[206:207], off
	s_add_i32 m0, s40, 0x2000
	s_add_u32 s38, s38, 0x40080
	v_lshl_add_u64 v[206:207], v[208:209], 0, s[16:17]
	s_addc_u32 s39, s39, 0
	s_add_i32 s40, s63, s44
	global_load_lds_dwordx4 v[206:207], off
	s_mov_b32 m0, s40
	s_nop 0
	global_load_lds_dwordx4 v186, s[38:39]
	s_add_i32 m0, s40, 0x2000
	s_nop 0
	global_load_lds_dwordx4 v190, s[38:39]
	v_lshl_add_u64 v[206:207], v[210:211], 0, s[16:17]
	s_mov_b32 m0, s50
	s_nop 0
	global_load_lds_dwordx4 v[206:207], off
	v_lshl_add_u64 v[206:207], v[212:213], 0, s[16:17]
	s_mov_b32 m0, s51
	s_nop 0
	global_load_lds_dwordx4 v[206:207], off
	s_waitcnt vmcnt(8)
	s_waitcnt lgkmcnt(0)
	s_barrier
	s_setprio 1
	s_waitcnt lgkmcnt(0)
	v_mfma_f32_16x16x32_bf16 v[60:63], v[124:127], v[160:163], v[60:63]
	v_mfma_f32_16x16x32_bf16 v[56:59], v[136:139], v[160:163], v[56:59]
	v_mfma_f32_16x16x32_bf16 v[44:47], v[124:127], v[168:171], v[44:47]
	v_mfma_f32_16x16x32_bf16 v[40:43], v[136:139], v[168:171], v[40:43]
	v_mfma_f32_16x16x32_bf16 v[28:31], v[124:127], v[176:179], v[28:31]
	v_mfma_f32_16x16x32_bf16 v[24:27], v[136:139], v[176:179], v[24:27]
	v_mfma_f32_16x16x32_bf16 v[12:15], v[124:127], v[198:201], v[12:15]
	v_mfma_f32_16x16x32_bf16 v[8:11], v[136:139], v[198:201], v[8:11]
	v_mfma_f32_16x16x32_bf16 v[60:63], v[132:135], v[164:167], v[60:63]
	v_mfma_f32_16x16x32_bf16 v[56:59], v[140:143], v[164:167], v[56:59]
	v_mfma_f32_16x16x32_bf16 v[44:47], v[132:135], v[172:175], v[44:47]
	v_mfma_f32_16x16x32_bf16 v[40:43], v[140:143], v[172:175], v[40:43]
	v_mfma_f32_16x16x32_bf16 v[28:31], v[132:135], v[180:183], v[28:31]
	v_mfma_f32_16x16x32_bf16 v[24:27], v[140:143], v[180:183], v[24:27]
	v_mfma_f32_16x16x32_bf16 v[12:15], v[132:135], v[202:205], v[12:15]
	v_mfma_f32_16x16x32_bf16 v[8:11], v[140:143], v[202:205], v[8:11]
	s_setprio 0
	s_setprio 1
	v_mfma_f32_16x16x32_bf16 v[52:55], v[144:147], v[160:163], v[52:55]
	v_mfma_f32_16x16x32_bf16 v[48:51], v[152:155], v[160:163], v[48:51]
	v_mfma_f32_16x16x32_bf16 v[36:39], v[144:147], v[168:171], v[36:39]
	v_mfma_f32_16x16x32_bf16 v[32:35], v[152:155], v[168:171], v[32:35]
	v_mfma_f32_16x16x32_bf16 v[20:23], v[144:147], v[176:179], v[20:23]
	v_mfma_f32_16x16x32_bf16 v[16:19], v[152:155], v[176:179], v[16:19]
	v_mfma_f32_16x16x32_bf16 v[4:7], v[144:147], v[198:201], v[4:7]
	v_mfma_f32_16x16x32_bf16 v[0:3], v[152:155], v[198:201], v[0:3]
	v_mfma_f32_16x16x32_bf16 v[52:55], v[148:151], v[164:167], v[52:55]
	v_mfma_f32_16x16x32_bf16 v[48:51], v[156:159], v[164:167], v[48:51]
	v_mfma_f32_16x16x32_bf16 v[36:39], v[148:151], v[172:175], v[36:39]
	v_mfma_f32_16x16x32_bf16 v[32:35], v[156:159], v[172:175], v[32:35]
	v_mfma_f32_16x16x32_bf16 v[20:23], v[148:151], v[180:183], v[20:23]
	v_mfma_f32_16x16x32_bf16 v[16:19], v[156:159], v[180:183], v[16:19]
	v_mfma_f32_16x16x32_bf16 v[4:7], v[148:151], v[202:205], v[4:7]
	v_mfma_f32_16x16x32_bf16 v[0:3], v[156:159], v[202:205], v[0:3]
	s_setprio 0
	s_add_i32 s61, s61, 2
	s_add_u32 s36, s36, 0x100
	s_addc_u32 s37, s37, 0
	s_add_u32 s59, s59, 0x100
	s_addc_u32 s60, s60, 0
	s_cmp_gt_u32 s61, 13
	s_barrier
.LBB0_888:
	ds_read_b128 v[124:127], v234
	ds_read_b128 v[132:135], v234 offset:1024
	ds_read_b128 v[136:139], v234 offset:2048
	ds_read_b128 v[140:143], v234 offset:3072
	ds_read_b128 v[144:147], v235
	ds_read_b128 v[148:151], v235 offset:1024
	ds_read_b128 v[152:155], v235 offset:2048
	ds_read_b128 v[156:159], v235 offset:3072
	s_add_u32 s38, s36, 0xfffc0080
	s_addc_u32 s39, s37, -1
	s_cmp_eq_u32 s61, 12
	s_cselect_b32 s41, s23, s39
	s_cselect_b32 s40, s31, s38
	s_cselect_b32 s39, s21, s60
	s_cselect_b32 s38, s58, s59
	s_add_i32 m0, s45, 0xc000
	ds_read_b128 v[160:163], v236
	ds_read_b128 v[164:167], v236 offset:1024
	ds_read_b128 v[168:171], v236 offset:2048
	ds_read_b128 v[172:175], v236 offset:3072
	ds_read_b128 v[176:179], v236 offset:4096
	ds_read_b128 v[180:183], v236 offset:5120
	ds_read_b128 v[198:201], v236 offset:6144
	ds_read_b128 v[202:205], v236 offset:7168
	global_load_lds_dwordx4 v192, s[36:37]
	s_add_i32 m0, s45, 0xe000
	s_nop 0
	global_load_lds_dwordx4 v194, s[36:37]
	s_waitcnt vmcnt(8)
	s_waitcnt lgkmcnt(0)
	s_barrier
; #define PG8_STAGE(bufoff, gbase, voff) do { _Pragma("unroll") for (int _i = 0; _i < 2; ++_i) \
;         __builtin_amdgcn_global_load_lds((const unsigned*)((const char*)(gbase) + (voff)[_i]), (PG8_LAS unsigned*)(lds + (bufoff) + ldsw + _i * 8192), 16, 0, 0); } while (0)
; #define PG8_LDA(dst, b, h) do { _Pragma("unroll") for (int m = 0; m < 4; ++m) _Pragma("unroll") for (int k = 0; k < 2; ++k) dst[m][k] = *(const PG8_LAS bf16x8*)(lds + PG8_SA(b, h) + aoff + m * 2048 + k * 1024); } while (0)
; #define PG8_MMA(ai, bj, At, Bt) do { __builtin_amdgcn_s_setprio(1); _Pragma("unroll") for (int m = 0; m < 4; ++m) _Pragma("unroll") for (int n = 0; n < 2; ++n) _Pragma("unroll") for (int k = 0; k < 2; ++k) \
;         acc[ai][bj][m][n] = __builtin_amdgcn_mfma_f32_16x16x32_bf16(Bt[n][k], At[m][k], acc[ai][bj][m][n], 0, 0, 0); __builtin_amdgcn_s_setprio(0); } while (0)
; #define PG8_WAIT_V(n) asm volatile("s_waitcnt vmcnt(" #n ")" ::: "memory")
; #define PG8_WAIT_L(n) asm volatile("s_waitcnt lgkmcnt(" #n ")" ::: "memory")
; #define PG8_BAR __builtin_amdgcn_s_barrier()
; #define PG8_SCHED __builtin_amdgcn_sched_barrier(0)
; template <class Epi, class Sched, bool ALIGN_EPI = false, bool SP2 = false>
; __device__ __forceinline__ void gemm_phase(PG8_LAS unsigned char* lds, const Gemm g, const Sched& S, const Epi& E) {
;     ...
;             PG8_WAIT_V(8); PG8_WAIT_L(0); PG8_BAR; PG8_MMA(0, 0, At, B0); PG8_MMA(0, 1, At, B1); PG8_BAR; PG8_SCHED;
;             PG8_LDA(At, 0, 1); PG8_STAGE(PG8_SB(0, 0), b2, voffB); PG8_STAGE(PG8_SB(0, 1), b2 + hstep, voffB); PG8_STAGE(PG8_SA(0, 0), a2, voffA);
;             PG8_WAIT_V(8); PG8_WAIT_L(0); PG8_BAR; PG8_MMA(1, 0, At, B0); PG8_MMA(1, 1, At, B1); PG8_BAR; PG8_SCHED;
	s_setprio 1
	s_waitcnt lgkmcnt(0)
	v_mfma_f32_16x16x32_bf16 v[128:131], v[124:127], v[160:163], v[128:131]
	v_mfma_f32_16x16x32_bf16 v[120:123], v[136:139], v[160:163], v[120:123]
	v_mfma_f32_16x16x32_bf16 v[108:111], v[124:127], v[168:171], v[108:111]
	v_mfma_f32_16x16x32_bf16 v[104:107], v[136:139], v[168:171], v[104:107]
	v_mfma_f32_16x16x32_bf16 v[92:95], v[124:127], v[176:179], v[92:95]
	v_mfma_f32_16x16x32_bf16 v[88:91], v[136:139], v[176:179], v[88:91]
	v_mfma_f32_16x16x32_bf16 v[76:79], v[124:127], v[198:201], v[76:79]
	v_mfma_f32_16x16x32_bf16 v[72:75], v[136:139], v[198:201], v[72:75]
	v_mfma_f32_16x16x32_bf16 v[128:131], v[132:135], v[164:167], v[128:131]
	v_mfma_f32_16x16x32_bf16 v[120:123], v[140:143], v[164:167], v[120:123]
	v_mfma_f32_16x16x32_bf16 v[108:111], v[132:135], v[172:175], v[108:111]
	v_mfma_f32_16x16x32_bf16 v[104:107], v[140:143], v[172:175], v[104:107]
	v_mfma_f32_16x16x32_bf16 v[92:95], v[132:135], v[180:183], v[92:95]
	v_mfma_f32_16x16x32_bf16 v[88:91], v[140:143], v[180:183], v[88:91]
	v_mfma_f32_16x16x32_bf16 v[76:79], v[132:135], v[202:205], v[76:79]
	v_mfma_f32_16x16x32_bf16 v[72:75], v[140:143], v[202:205], v[72:75]
	s_setprio 0
	s_setprio 1
	v_mfma_f32_16x16x32_bf16 v[116:119], v[144:147], v[160:163], v[116:119]
	v_mfma_f32_16x16x32_bf16 v[112:115], v[152:155], v[160:163], v[112:115]
	v_mfma_f32_16x16x32_bf16 v[100:103], v[144:147], v[168:171], v[100:103]
	v_mfma_f32_16x16x32_bf16 v[96:99], v[152:155], v[168:171], v[96:99]
	v_mfma_f32_16x16x32_bf16 v[84:87], v[144:147], v[176:179], v[84:87]
	v_mfma_f32_16x16x32_bf16 v[80:83], v[152:155], v[176:179], v[80:83]
	v_mfma_f32_16x16x32_bf16 v[68:71], v[144:147], v[198:201], v[68:71]
	v_mfma_f32_16x16x32_bf16 v[64:67], v[152:155], v[198:201], v[64:67]
	v_mfma_f32_16x16x32_bf16 v[116:119], v[148:151], v[164:167], v[116:119]
	v_mfma_f32_16x16x32_bf16 v[112:115], v[156:159], v[164:167], v[112:115]
	v_mfma_f32_16x16x32_bf16 v[100:103], v[148:151], v[172:175], v[100:103]
	v_mfma_f32_16x16x32_bf16 v[96:99], v[156:159], v[172:175], v[96:99]
	v_mfma_f32_16x16x32_bf16 v[84:87], v[148:151], v[180:183], v[84:87]
	v_mfma_f32_16x16x32_bf16 v[80:83], v[156:159], v[180:183], v[80:83]
	v_mfma_f32_16x16x32_bf16 v[68:71], v[148:151], v[202:205], v[68:71]
	v_mfma_f32_16x16x32_bf16 v[64:67], v[156:159], v[202:205], v[64:67]
	s_setprio 0
	s_barrier
	s_add_i32 s62, s55, s44
	v_lshl_add_u64 v[206:207], s[38:39], 0, v[186:187]
	s_mov_b32 m0, s62
	ds_read_b128 v[160:163], v236 offset:16384
	ds_read_b128 v[164:167], v236 offset:17408
	ds_read_b128 v[168:171], v236 offset:18432
	ds_read_b128 v[172:175], v236 offset:19456
	ds_read_b128 v[176:179], v236 offset:20480
	ds_read_b128 v[180:183], v236 offset:21504
	ds_read_b128 v[198:201], v236 offset:22528
	ds_read_b128 v[202:205], v236 offset:23552
	global_load_lds_dwordx4 v[206:207], off
	s_add_i32 m0, s62, 0x2000
	s_add_u32 s62, s38, 0x40000
	v_lshl_add_u64 v[208:209], s[38:39], 0, v[190:191]
	s_addc_u32 s63, s39, 0
	s_add_i32 s64, s56, s44
	global_load_lds_dwordx4 v[208:209], off
	s_mov_b32 m0, s64
	v_lshl_add_u64 v[212:213], s[40:41], 0, v[188:189]
	global_load_lds_dwordx4 v186, s[62:63]
	s_add_i32 m0, s64, 0x2000
	s_nop 0
	global_load_lds_dwordx4 v190, s[62:63]
	v_lshl_add_u64 v[210:211], s[40:41], 0, v[184:185]
	s_mov_b32 m0, s45
	s_nop 0
	global_load_lds_dwordx4 v[210:211], off
	s_mov_b32 m0, s46
	s_nop 0
	global_load_lds_dwordx4 v[212:213], off
	s_waitcnt vmcnt(8)
	s_waitcnt lgkmcnt(0)
	s_barrier
	s_setprio 1
	s_waitcnt lgkmcnt(0)
	v_mfma_f32_16x16x32_bf16 v[60:63], v[124:127], v[160:163], v[60:63]
	v_mfma_f32_16x16x32_bf16 v[56:59], v[136:139], v[160:163], v[56:59]
	v_mfma_f32_16x16x32_bf16 v[44:47], v[124:127], v[168:171], v[44:47]
	v_mfma_f32_16x16x32_bf16 v[40:43], v[136:139], v[168:171], v[40:43]
	v_mfma_f32_16x16x32_bf16 v[28:31], v[124:127], v[176:179], v[28:31]
	v_mfma_f32_16x16x32_bf16 v[24:27], v[136:139], v[176:179], v[24:27]
	v_mfma_f32_16x16x32_bf16 v[12:15], v[124:127], v[198:201], v[12:15]
	v_mfma_f32_16x16x32_bf16 v[8:11], v[136:139], v[198:201], v[8:11]
	v_mfma_f32_16x16x32_bf16 v[60:63], v[132:135], v[164:167], v[60:63]
	v_mfma_f32_16x16x32_bf16 v[56:59], v[140:143], v[164:167], v[56:59]
	v_mfma_f32_16x16x32_bf16 v[44:47], v[132:135], v[172:175], v[44:47]
	v_mfma_f32_16x16x32_bf16 v[40:43], v[140:143], v[172:175], v[40:43]
	v_mfma_f32_16x16x32_bf16 v[28:31], v[132:135], v[180:183], v[28:31]
	v_mfma_f32_16x16x32_bf16 v[24:27], v[140:143], v[180:183], v[24:27]
	v_mfma_f32_16x16x32_bf16 v[12:15], v[132:135], v[202:205], v[12:15]
	v_mfma_f32_16x16x32_bf16 v[8:11], v[140:143], v[202:205], v[8:11]
	s_setprio 0
	s_setprio 1
	v_mfma_f32_16x16x32_bf16 v[52:55], v[144:147], v[160:163], v[52:55]
	v_mfma_f32_16x16x32_bf16 v[48:51], v[152:155], v[160:163], v[48:51]
	v_mfma_f32_16x16x32_bf16 v[36:39], v[144:147], v[168:171], v[36:39]
	v_mfma_f32_16x16x32_bf16 v[32:35], v[152:155], v[168:171], v[32:35]
	v_mfma_f32_16x16x32_bf16 v[20:23], v[144:147], v[176:179], v[20:23]
	v_mfma_f32_16x16x32_bf16 v[16:19], v[152:155], v[176:179], v[16:19]
	v_mfma_f32_16x16x32_bf16 v[4:7], v[144:147], v[198:201], v[4:7]
	v_mfma_f32_16x16x32_bf16 v[0:3], v[152:155], v[198:201], v[0:3]
	v_mfma_f32_16x16x32_bf16 v[52:55], v[148:151], v[164:167], v[52:55]
	v_mfma_f32_16x16x32_bf16 v[48:51], v[156:159], v[164:167], v[48:51]
	v_mfma_f32_16x16x32_bf16 v[36:39], v[148:151], v[172:175], v[36:39]
	v_mfma_f32_16x16x32_bf16 v[32:35], v[156:159], v[172:175], v[32:35]
	v_mfma_f32_16x16x32_bf16 v[20:23], v[148:151], v[180:183], v[20:23]
	v_mfma_f32_16x16x32_bf16 v[16:19], v[156:159], v[180:183], v[16:19]
	v_mfma_f32_16x16x32_bf16 v[4:7], v[148:151], v[202:205], v[4:7]
	v_mfma_f32_16x16x32_bf16 v[0:3], v[156:159], v[202:205], v[0:3]
	s_setprio 0
	s_barrier
; #define PG8_STAGE(bufoff, gbase, voff) do { _Pragma("unroll") for (int _i = 0; _i < 2; ++_i) \
;         __builtin_amdgcn_global_load_lds((const unsigned*)((const char*)(gbase) + (voff)[_i]), (PG8_LAS unsigned*)(lds + (bufoff) + ldsw + _i * 8192), 16, 0, 0); } while (0)
; #define PG8_LDA(dst, b, h) do { _Pragma("unroll") for (int m = 0; m < 4; ++m) _Pragma("unroll") for (int k = 0; k < 2; ++k) dst[m][k] = *(const PG8_LAS bf16x8*)(lds + PG8_SA(b, h) + aoff + m * 2048 + k * 1024); } while (0)
; #define PG8_LDB(dst, b, h) do { _Pragma("unroll") for (int n = 0; n < 2; ++n) _Pragma("unroll") for (int k = 0; k < 2; ++k) dst[n][k] = *(const PG8_LAS bf16x8*)(lds + PG8_SB(b, h) + boff + n * 2048 + k * 1024); } while (0)
; #define PG8_MMA(ai, bj, At, Bt) do { __builtin_amdgcn_s_setprio(1); _Pragma("unroll") for (int m = 0; m < 4; ++m) _Pragma("unroll") for (int n = 0; n < 2; ++n) _Pragma("unroll") for (int k = 0; k < 2; ++k) \
;         acc[ai][bj][m][n] = __builtin_amdgcn_mfma_f32_16x16x32_bf16(Bt[n][k], At[m][k], acc[ai][bj][m][n], 0, 0, 0); __builtin_amdgcn_s_setprio(0); } while (0)
; #define PG8_WAIT_V(n) asm volatile("s_waitcnt vmcnt(" #n ")" ::: "memory")
; #define PG8_WAIT_L(n) asm volatile("s_waitcnt lgkmcnt(" #n ")" ::: "memory")
; #define PG8_BAR __builtin_amdgcn_s_barrier()
; #define PG8_SCHED __builtin_amdgcn_sched_barrier(0)
; template <class Epi, class Sched, bool ALIGN_EPI = false, bool SP2 = false>
; __device__ __forceinline__ void gemm_phase(PG8_LAS unsigned char* lds, const Gemm g, const Sched& S, const Epi& E) {
;     ...
;             PG8_LDB(B0, 1, 0); PG8_LDB(B1, 1, 1); PG8_SCHED; PG8_LDA(At, 1, 0); PG8_STAGE(PG8_SA(0, 1), a2 + hstep, voffA);
;             PG8_WAIT_V(8); PG8_WAIT_L(0); PG8_BAR; PG8_MMA(0, 0, At, B0); PG8_MMA(0, 1, At, B1); PG8_BAR; PG8_SCHED;
	s_add_i32 s62, 0, 0x18000
	s_add_i32 s63, 0, 0x1c000
	v_add_u32_e32 v140, s62, v232
	v_add_u32_e32 v156, s63, v232
	ds_read_b128 v[124:127], v140
	ds_read_b128 v[132:135], v140 offset:1024
	ds_read_b128 v[136:139], v140 offset:2048
	ds_read_b128 v[140:143], v140 offset:3072
	ds_read_b128 v[144:147], v156
	ds_read_b128 v[148:151], v156 offset:1024
	ds_read_b128 v[152:155], v156 offset:2048
	ds_read_b128 v[156:159], v156 offset:3072
	s_add_u32 s40, s40, 0x40000
	s_addc_u32 s41, s41, 0
	s_mov_b32 m0, s47
	ds_read_b128 v[160:163], v236 offset:32768
	ds_read_b128 v[164:167], v236 offset:33792
	ds_read_b128 v[168:171], v236 offset:34816
	ds_read_b128 v[172:175], v236 offset:35840
	ds_read_b128 v[176:179], v236 offset:36864
	ds_read_b128 v[180:183], v236 offset:37888
	ds_read_b128 v[198:201], v236 offset:38912
	ds_read_b128 v[202:205], v236 offset:39936
	global_load_lds_dwordx4 v184, s[40:41]
	v_lshl_add_u64 v[214:215], s[40:41], 0, v[188:189]
	s_mov_b32 m0, s48
	s_nop 0
	global_load_lds_dwordx4 v[214:215], off
	s_waitcnt vmcnt(8)
	s_waitcnt lgkmcnt(0)
	s_barrier
	s_setprio 1
	s_waitcnt lgkmcnt(0)
	v_mfma_f32_16x16x32_bf16 v[128:131], v[124:127], v[160:163], v[128:131]
	v_mfma_f32_16x16x32_bf16 v[120:123], v[136:139], v[160:163], v[120:123]
	v_mfma_f32_16x16x32_bf16 v[108:111], v[124:127], v[168:171], v[108:111]
	v_mfma_f32_16x16x32_bf16 v[104:107], v[136:139], v[168:171], v[104:107]
	v_mfma_f32_16x16x32_bf16 v[92:95], v[124:127], v[176:179], v[92:95]
	v_mfma_f32_16x16x32_bf16 v[88:91], v[136:139], v[176:179], v[88:91]
	v_mfma_f32_16x16x32_bf16 v[76:79], v[124:127], v[198:201], v[76:79]
	v_mfma_f32_16x16x32_bf16 v[72:75], v[136:139], v[198:201], v[72:75]
	v_mfma_f32_16x16x32_bf16 v[128:131], v[132:135], v[164:167], v[128:131]
	v_mfma_f32_16x16x32_bf16 v[120:123], v[140:143], v[164:167], v[120:123]
	v_mfma_f32_16x16x32_bf16 v[108:111], v[132:135], v[172:175], v[108:111]
	v_mfma_f32_16x16x32_bf16 v[104:107], v[140:143], v[172:175], v[104:107]
	v_mfma_f32_16x16x32_bf16 v[92:95], v[132:135], v[180:183], v[92:95]
	v_mfma_f32_16x16x32_bf16 v[88:91], v[140:143], v[180:183], v[88:91]
	v_mfma_f32_16x16x32_bf16 v[76:79], v[132:135], v[202:205], v[76:79]
	v_mfma_f32_16x16x32_bf16 v[72:75], v[140:143], v[202:205], v[72:75]
	s_setprio 0
	s_setprio 1
	v_mfma_f32_16x16x32_bf16 v[116:119], v[144:147], v[160:163], v[116:119]
	v_mfma_f32_16x16x32_bf16 v[112:115], v[152:155], v[160:163], v[112:115]
	v_mfma_f32_16x16x32_bf16 v[100:103], v[144:147], v[168:171], v[100:103]
	v_mfma_f32_16x16x32_bf16 v[96:99], v[152:155], v[168:171], v[96:99]
	v_mfma_f32_16x16x32_bf16 v[84:87], v[144:147], v[176:179], v[84:87]
	v_mfma_f32_16x16x32_bf16 v[80:83], v[152:155], v[176:179], v[80:83]
	v_mfma_f32_16x16x32_bf16 v[68:71], v[144:147], v[198:201], v[68:71]
	v_mfma_f32_16x16x32_bf16 v[64:67], v[152:155], v[198:201], v[64:67]
	v_mfma_f32_16x16x32_bf16 v[116:119], v[148:151], v[164:167], v[116:119]
	v_mfma_f32_16x16x32_bf16 v[112:115], v[156:159], v[164:167], v[112:115]
	v_mfma_f32_16x16x32_bf16 v[100:103], v[148:151], v[172:175], v[100:103]
	v_mfma_f32_16x16x32_bf16 v[96:99], v[156:159], v[172:175], v[96:99]
	v_mfma_f32_16x16x32_bf16 v[84:87], v[148:151], v[180:183], v[84:87]
	v_mfma_f32_16x16x32_bf16 v[80:83], v[156:159], v[180:183], v[80:83]
	v_mfma_f32_16x16x32_bf16 v[68:71], v[148:151], v[202:205], v[68:71]
	v_mfma_f32_16x16x32_bf16 v[64:67], v[156:159], v[202:205], v[64:67]
	s_setprio 0
	s_barrier
; #define PG8_STAGE(bufoff, gbase, voff) do { _Pragma("unroll") for (int _i = 0; _i < 2; ++_i) \
;         __builtin_amdgcn_global_load_lds((const unsigned*)((const char*)(gbase) + (voff)[_i]), (PG8_LAS unsigned*)(lds + (bufoff) + ldsw + _i * 8192), 16, 0, 0); } while (0)
; #define PG8_LDA(dst, b, h) do { _Pragma("unroll") for (int m = 0; m < 4; ++m) _Pragma("unroll") for (int k = 0; k < 2; ++k) dst[m][k] = *(const PG8_LAS bf16x8*)(lds + PG8_SA(b, h) + aoff + m * 2048 + k * 1024); } while (0)
; #define PG8_MMA(ai, bj, At, Bt) do { __builtin_amdgcn_s_setprio(1); _Pragma("unroll") for (int m = 0; m < 4; ++m) _Pragma("unroll") for (int n = 0; n < 2; ++n) _Pragma("unroll") for (int k = 0; k < 2; ++k) \
;         acc[ai][bj][m][n] = __builtin_amdgcn_mfma_f32_16x16x32_bf16(Bt[n][k], At[m][k], acc[ai][bj][m][n], 0, 0, 0); __builtin_amdgcn_s_setprio(0); } while (0)
; #define PG8_WAIT_V(n) asm volatile("s_waitcnt vmcnt(" #n ")" ::: "memory")
; #define PG8_WAIT_L(n) asm volatile("s_waitcnt lgkmcnt(" #n ")" ::: "memory")
; #define PG8_BAR __builtin_amdgcn_s_barrier()
; #define PG8_SCHED __builtin_amdgcn_sched_barrier(0)
; template <class Epi, class Sched, bool ALIGN_EPI = false, bool SP2 = false>
; __device__ __forceinline__ void gemm_phase(PG8_LAS unsigned char* lds, const Gemm g, const Sched& S, const Epi& E) {
;     ...
;         for (int t = 0; t < nt; t += 2) {
;     ...
;             PG8_LDA(At, 1, 1); PG8_STAGE(PG8_SB(1, 0), b3, voffB); PG8_STAGE(PG8_SB(1, 1), b3 + hstep, voffB); PG8_STAGE(PG8_SA(1, 0), a3, voffA);
;             PG8_WAIT_V(8); PG8_WAIT_L(0); PG8_BAR; PG8_MMA(1, 0, At, B0); PG8_MMA(1, 1, At, B1); PG8_BAR; PG8_SCHED;
	s_add_i32 s40, s62, s44
	v_lshl_add_u64 v[206:207], v[206:207], 0, s[16:17]
	s_mov_b32 m0, s40
	ds_read_b128 v[160:163], v236 offset:49152
	ds_read_b128 v[164:167], v236 offset:50176
	ds_read_b128 v[168:171], v236 offset:51200
	ds_read_b128 v[172:175], v236 offset:52224
	ds_read_b128 v[176:179], v236 offset:53248
	ds_read_b128 v[180:183], v236 offset:54272
	ds_read_b128 v[198:201], v236 offset:55296
	ds_read_b128 v[202:205], v236 offset:56320
	global_load_lds_dwordx4 v[206:207], off
	s_add_i32 m0, s40, 0x2000
	s_add_u32 s38, s38, 0x40080
	v_lshl_add_u64 v[206:207], v[208:209], 0, s[16:17]
	s_addc_u32 s39, s39, 0
	s_add_i32 s40, s63, s44
	global_load_lds_dwordx4 v[206:207], off
	s_mov_b32 m0, s40
	s_nop 0
	global_load_lds_dwordx4 v186, s[38:39]
	s_add_i32 m0, s40, 0x2000
	s_nop 0
	global_load_lds_dwordx4 v190, s[38:39]
	v_lshl_add_u64 v[206:207], v[210:211], 0, s[16:17]
	s_mov_b32 m0, s50
	s_nop 0
	global_load_lds_dwordx4 v[206:207], off
	v_lshl_add_u64 v[206:207], v[212:213], 0, s[16:17]
	s_mov_b32 m0, s51
	s_nop 0
	global_load_lds_dwordx4 v[206:207], off
	s_waitcnt vmcnt(8)
	s_waitcnt lgkmcnt(0)
	s_barrier
	s_setprio 1
	s_waitcnt lgkmcnt(0)
	v_mfma_f32_16x16x32_bf16 v[60:63], v[124:127], v[160:163], v[60:63]
	v_mfma_f32_16x16x32_bf16 v[56:59], v[136:139], v[160:163], v[56:59]
	v_mfma_f32_16x16x32_bf16 v[44:47], v[124:127], v[168:171], v[44:47]
	v_mfma_f32_16x16x32_bf16 v[40:43], v[136:139], v[168:171], v[40:43]
	v_mfma_f32_16x16x32_bf16 v[28:31], v[124:127], v[176:179], v[28:31]
	v_mfma_f32_16x16x32_bf16 v[24:27], v[136:139], v[176:179], v[24:27]
	v_mfma_f32_16x16x32_bf16 v[12:15], v[124:127], v[198:201], v[12:15]
	v_mfma_f32_16x16x32_bf16 v[8:11], v[136:139], v[198:201], v[8:11]
	v_mfma_f32_16x16x32_bf16 v[60:63], v[132:135], v[164:167], v[60:63]
	v_mfma_f32_16x16x32_bf16 v[56:59], v[140:143], v[164:167], v[56:59]
	v_mfma_f32_16x16x32_bf16 v[44:47], v[132:135], v[172:175], v[44:47]
	v_mfma_f32_16x16x32_bf16 v[40:43], v[140:143], v[172:175], v[40:43]
	v_mfma_f32_16x16x32_bf16 v[28:31], v[132:135], v[180:183], v[28:31]
	v_mfma_f32_16x16x32_bf16 v[24:27], v[140:143], v[180:183], v[24:27]
	v_mfma_f32_16x16x32_bf16 v[12:15], v[132:135], v[202:205], v[12:15]
	v_mfma_f32_16x16x32_bf16 v[8:11], v[140:143], v[202:205], v[8:11]
	s_setprio 0
	s_setprio 1
	v_mfma_f32_16x16x32_bf16 v[52:55], v[144:147], v[160:163], v[52:55]
	v_mfma_f32_16x16x32_bf16 v[48:51], v[152:155], v[160:163], v[48:51]
	v_mfma_f32_16x16x32_bf16 v[36:39], v[144:147], v[168:171], v[36:39]
	v_mfma_f32_16x16x32_bf16 v[32:35], v[152:155], v[168:171], v[32:35]
	v_mfma_f32_16x16x32_bf16 v[20:23], v[144:147], v[176:179], v[20:23]
	v_mfma_f32_16x16x32_bf16 v[16:19], v[152:155], v[176:179], v[16:19]
	v_mfma_f32_16x16x32_bf16 v[4:7], v[144:147], v[198:201], v[4:7]
	v_mfma_f32_16x16x32_bf16 v[0:3], v[152:155], v[198:201], v[0:3]
	v_mfma_f32_16x16x32_bf16 v[52:55], v[148:151], v[164:167], v[52:55]
	v_mfma_f32_16x16x32_bf16 v[48:51], v[156:159], v[164:167], v[48:51]
	v_mfma_f32_16x16x32_bf16 v[36:39], v[148:151], v[172:175], v[36:39]
	v_mfma_f32_16x16x32_bf16 v[32:35], v[156:159], v[172:175], v[32:35]
	v_mfma_f32_16x16x32_bf16 v[20:23], v[148:151], v[180:183], v[20:23]
	v_mfma_f32_16x16x32_bf16 v[16:19], v[156:159], v[180:183], v[16:19]
	v_mfma_f32_16x16x32_bf16 v[4:7], v[148:151], v[202:205], v[4:7]
	v_mfma_f32_16x16x32_bf16 v[0:3], v[156:159], v[202:205], v[0:3]
	s_setprio 0
	s_add_i32 s61, s61, 2
	s_add_u32 s36, s36, 0x100
	s_addc_u32 s37, s37, 0
	s_add_u32 s59, s59, 0x100
	s_addc_u32 s60, s60, 0
	s_cmp_gt_u32 s61, 13
	s_barrier
	s_cbranch_scc0 .LBB0_888
	s_and_b64 vcc, exec, s[18:19]
	s_cbranch_vccz .LBB0_891
	s_barrier

; #define PG8_STAGE(bufoff, gbase, voff) do { _Pragma("unroll") for (int _i = 0; _i < 2; ++_i) \
;         __builtin_amdgcn_global_load_lds((const unsigned*)((const char*)(gbase) + (voff)[_i]), (PG8_LAS unsigned*)(lds + (bufoff) + ldsw + _i * 8192), 16, 0, 0); } while (0)
; #define PG8_LDA(dst, b, h) do { _Pragma("unroll") for (int m = 0; m < 4; ++m) _Pragma("unroll") for (int k = 0; k < 2; ++k) dst[m][k] = *(const PG8_LAS bf16x8*)(lds + PG8_SA(b, h) + aoff + m * 2048 + k * 1024); } while (0)
; #define PG8_LDB(dst, b, h) do { _Pragma("unroll") for (int n = 0; n < 2; ++n) _Pragma("unroll") for (int k = 0; k < 2; ++k) dst[n][k] = *(const PG8_LAS bf16x8*)(lds + PG8_SB(b, h) + boff + n * 2048 + k * 1024); } while (0)
; #define PG8_MMA(ai, bj, At, Bt) do { __builtin_amdgcn_s_setprio(1); _Pragma("unroll") for (int m = 0; m < 4; ++m) _Pragma("unroll") for (int n = 0; n < 2; ++n) _Pragma("unroll") for (int k = 0; k < 2; ++k) \
;         acc[ai][bj][m][n] = __builtin_amdgcn_mfma_f32_16x16x32_bf16(Bt[n][k], At[m][k], acc[ai][bj][m][n], 0, 0, 0); __builtin_amdgcn_s_setprio(0); } while (0)
; #define PG8_WAIT_V(n) asm volatile("s_waitcnt vmcnt(" #n ")" ::: "memory")
; template <class Epi, class Sched, bool ALIGN_EPI = false, bool SP2 = false>
; __device__ __forceinline__ void gemm_phase(PG8_LAS unsigned char* lds, const Gemm g, const Sched& S, const Epi& E) {
;     ...
;             PG8_LDB(B0, 0, 0); PG8_LDB(B1, 0, 1); PG8_SCHED; PG8_LDA(At, 0, 0); PG8_STAGE(PG8_SA(1, 1), a1 + hstep, voffA);
;             PG8_WAIT_V(8); PG8_WAIT_L(0); PG8_BAR; PG8_MMA(0, 0, At, B0); PG8_MMA(0, 1, At, B1); PG8_BAR; PG8_SCHED;
;             PG8_LDA(At, 0, 1); PG8_STAGE(PG8_SB(0, 0), b2, voffB); PG8_STAGE(PG8_SB(0, 1), b2 + hstep, voffB); PG8_STAGE(PG8_SA(0, 0), a2, voffA);
;             PG8_WAIT_V(8); PG8_WAIT_L(0); PG8_BAR; PG8_MMA(1, 0, At, B0); PG8_MMA(1, 1, At, B1); PG8_BAR; PG8_SCHED;
;             PG8_LDB(B0, 1, 0); PG8_LDB(B1, 1, 1); PG8_SCHED; PG8_LDA(At, 1, 0); PG8_STAGE(PG8_SA(0, 1), a2 + hstep, voffA);
;             PG8_WAIT_V(8); PG8_WAIT_L(0); PG8_BAR; PG8_MMA(0, 0, At, B0); PG8_MMA(0, 1, At, B1); PG8_BAR; PG8_SCHED;
;             PG8_LDA(At, 1, 1); PG8_STAGE(PG8_SB(1, 0), b3, voffB); PG8_STAGE(PG8_SB(1, 1), b3 + hstep, voffB); PG8_STAGE(PG8_SA(1, 0), a3, voffA);
;             PG8_WAIT_V(8); PG8_WAIT_L(0); PG8_BAR; PG8_MMA(1, 0, At, B0); PG8_MMA(1, 1, At, B1); PG8_BAR; PG8_SCHED;
.Lrsb_d_pl:
	s_waitcnt lgkmcnt(0)
	s_barrier
	s_setprio 1
	s_waitcnt lgkmcnt(0)
	v_mfma_f32_16x16x32_bf16 v[124:127], v[144:147], v[202:205], v[124:127]
	v_mfma_f32_16x16x32_bf16 v[116:119], v[178:181], v[202:205], v[116:119]
	v_mfma_f32_16x16x32_bf16 v[108:111], v[144:147], v[210:213], v[108:111]
	v_mfma_f32_16x16x32_bf16 v[100:103], v[178:181], v[210:213], v[100:103]
	v_mfma_f32_16x16x32_bf16 v[92:95], v[144:147], v[218:221], v[92:95]
	v_mfma_f32_16x16x32_bf16 v[84:87], v[178:181], v[218:221], v[84:87]
	v_mfma_f32_16x16x32_bf16 v[76:79], v[144:147], v[226:229], v[76:79]
	v_mfma_f32_16x16x32_bf16 v[68:71], v[178:181], v[226:229], v[68:71]
	v_mfma_f32_16x16x32_bf16 v[124:127], v[170:173], v[206:209], v[124:127]
	v_mfma_f32_16x16x32_bf16 v[116:119], v[182:185], v[206:209], v[116:119]
	v_mfma_f32_16x16x32_bf16 v[108:111], v[170:173], v[214:217], v[108:111]
	v_mfma_f32_16x16x32_bf16 v[100:103], v[182:185], v[214:217], v[100:103]
	v_mfma_f32_16x16x32_bf16 v[92:95], v[170:173], v[222:225], v[92:95]
	v_mfma_f32_16x16x32_bf16 v[84:87], v[182:185], v[222:225], v[84:87]
	v_mfma_f32_16x16x32_bf16 v[76:79], v[170:173], v[232:235], v[76:79]
	v_mfma_f32_16x16x32_bf16 v[68:71], v[182:185], v[232:235], v[68:71]
	s_setprio 0
	s_setprio 1
	v_mfma_f32_16x16x32_bf16 v[120:123], v[186:189], v[202:205], v[120:123]
	v_mfma_f32_16x16x32_bf16 v[112:115], v[194:197], v[202:205], v[112:115]
	v_mfma_f32_16x16x32_bf16 v[104:107], v[186:189], v[210:213], v[104:107]
	v_mfma_f32_16x16x32_bf16 v[96:99], v[194:197], v[210:213], v[96:99]
	v_mfma_f32_16x16x32_bf16 v[88:91], v[186:189], v[218:221], v[88:91]
	v_mfma_f32_16x16x32_bf16 v[80:83], v[194:197], v[218:221], v[80:83]
	v_mfma_f32_16x16x32_bf16 v[72:75], v[186:189], v[226:229], v[72:75]
	v_mfma_f32_16x16x32_bf16 v[64:67], v[194:197], v[226:229], v[64:67]
	v_mfma_f32_16x16x32_bf16 v[120:123], v[190:193], v[206:209], v[120:123]
	v_mfma_f32_16x16x32_bf16 v[112:115], v[198:201], v[206:209], v[112:115]
	v_mfma_f32_16x16x32_bf16 v[104:107], v[190:193], v[214:217], v[104:107]
	v_mfma_f32_16x16x32_bf16 v[96:99], v[198:201], v[214:217], v[96:99]
	v_mfma_f32_16x16x32_bf16 v[88:91], v[190:193], v[222:225], v[88:91]
	v_mfma_f32_16x16x32_bf16 v[80:83], v[198:201], v[222:225], v[80:83]
	v_mfma_f32_16x16x32_bf16 v[72:75], v[190:193], v[232:235], v[72:75]
	v_mfma_f32_16x16x32_bf16 v[64:67], v[198:201], v[232:235], v[64:67]
	s_setprio 0
	s_barrier
	s_add_i32 s38, s59, s43
	v_lshl_add_u64 v[150:151], v[150:151], 0, s[12:13]
	s_mov_b32 m0, s38
	ds_read_b128 v[202:205], v169 offset:49152
	ds_read_b128 v[206:209], v169 offset:50176
	ds_read_b128 v[210:213], v169 offset:51200
	ds_read_b128 v[214:217], v169 offset:52224
	ds_read_b128 v[218:221], v169 offset:53248
	ds_read_b128 v[222:225], v169 offset:54272
	ds_read_b128 v[226:229], v169 offset:55296
	ds_read_b128 v[232:235], v169 offset:56320
	global_load_lds_dwordx4 v[150:151], off
	s_add_i32 m0, s38, 0x2000
	s_add_u32 s36, s36, 0x40080
	v_lshl_add_u64 v[150:151], v[154:155], 0, s[12:13]
	s_addc_u32 s37, s37, 0
	s_add_i32 s38, s60, s43
	global_load_lds_dwordx4 v[150:151], off
	s_mov_b32 m0, s38
	s_nop 0
	global_load_lds_dwordx4 v130, s[36:37]
	s_add_i32 m0, s38, 0x2000
	s_nop 0
	global_load_lds_dwordx4 v134, s[36:37]
	v_lshl_add_u64 v[150:151], v[158:159], 0, s[12:13]
	s_mov_b32 m0, s47
	s_nop 0
	global_load_lds_dwordx4 v[150:151], off
	v_lshl_add_u64 v[150:151], v[162:163], 0, s[12:13]
	s_mov_b32 m0, s48
	s_nop 0
	global_load_lds_dwordx4 v[150:151], off
	s_waitcnt vmcnt(8)
	s_waitcnt lgkmcnt(0)
	s_barrier
	s_setprio 1
	s_waitcnt lgkmcnt(0)
	v_mfma_f32_16x16x32_bf16 v[60:63], v[144:147], v[202:205], v[60:63]
	v_mfma_f32_16x16x32_bf16 v[52:55], v[178:181], v[202:205], v[52:55]
	v_mfma_f32_16x16x32_bf16 v[44:47], v[144:147], v[210:213], v[44:47]
	v_mfma_f32_16x16x32_bf16 v[36:39], v[178:181], v[210:213], v[36:39]
	v_mfma_f32_16x16x32_bf16 v[28:31], v[144:147], v[218:221], v[28:31]
	v_mfma_f32_16x16x32_bf16 v[20:23], v[178:181], v[218:221], v[20:23]
	v_mfma_f32_16x16x32_bf16 v[12:15], v[144:147], v[226:229], v[12:15]
	v_mfma_f32_16x16x32_bf16 v[4:7], v[178:181], v[226:229], v[4:7]
	v_mfma_f32_16x16x32_bf16 v[60:63], v[170:173], v[206:209], v[60:63]
	v_mfma_f32_16x16x32_bf16 v[52:55], v[182:185], v[206:209], v[52:55]
	v_mfma_f32_16x16x32_bf16 v[44:47], v[170:173], v[214:217], v[44:47]
	v_mfma_f32_16x16x32_bf16 v[36:39], v[182:185], v[214:217], v[36:39]
	v_mfma_f32_16x16x32_bf16 v[28:31], v[170:173], v[222:225], v[28:31]
	v_mfma_f32_16x16x32_bf16 v[20:23], v[182:185], v[222:225], v[20:23]
	v_mfma_f32_16x16x32_bf16 v[12:15], v[170:173], v[232:235], v[12:15]
	v_mfma_f32_16x16x32_bf16 v[4:7], v[182:185], v[232:235], v[4:7]
	s_setprio 0
	s_setprio 1
	v_mfma_f32_16x16x32_bf16 v[56:59], v[186:189], v[202:205], v[56:59]
	v_mfma_f32_16x16x32_bf16 v[48:51], v[194:197], v[202:205], v[48:51]
	v_mfma_f32_16x16x32_bf16 v[40:43], v[186:189], v[210:213], v[40:43]
	v_mfma_f32_16x16x32_bf16 v[32:35], v[194:197], v[210:213], v[32:35]
	v_mfma_f32_16x16x32_bf16 v[24:27], v[186:189], v[218:221], v[24:27]
	v_mfma_f32_16x16x32_bf16 v[16:19], v[194:197], v[218:221], v[16:19]
	v_mfma_f32_16x16x32_bf16 v[8:11], v[186:189], v[226:229], v[8:11]
	v_mfma_f32_16x16x32_bf16 v[0:3], v[194:197], v[226:229], v[0:3]
	v_mfma_f32_16x16x32_bf16 v[56:59], v[190:193], v[206:209], v[56:59]
	v_mfma_f32_16x16x32_bf16 v[48:51], v[198:201], v[206:209], v[48:51]
	v_mfma_f32_16x16x32_bf16 v[40:43], v[190:193], v[214:217], v[40:43]
	v_mfma_f32_16x16x32_bf16 v[32:35], v[198:201], v[214:217], v[32:35]
	v_mfma_f32_16x16x32_bf16 v[24:27], v[190:193], v[222:225], v[24:27]
	v_mfma_f32_16x16x32_bf16 v[16:19], v[198:201], v[222:225], v[16:19]
	v_mfma_f32_16x16x32_bf16 v[8:11], v[190:193], v[232:235], v[8:11]
	v_mfma_f32_16x16x32_bf16 v[0:3], v[198:201], v[232:235], v[0:3]
	s_setprio 0
	s_add_i32 s58, s58, 2
	s_add_u32 s34, s34, 0x100
	s_addc_u32 s35, s35, 0
	s_add_u32 s56, s56, 0x100
	s_addc_u32 s57, s57, 0
	s_cmp_gt_u32 s58, 13
	s_barrier

; #define PG8_STAGE(bufoff, gbase, voff) do { _Pragma("unroll") for (int _i = 0; _i < 2; ++_i) \
;         __builtin_amdgcn_global_load_lds((const unsigned*)((const char*)(gbase) + (voff)[_i]), (PG8_LAS unsigned*)(lds + (bufoff) + ldsw + _i * 8192), 16, 0, 0); } while (0)
; #define PG8_LDA(dst, b, h) do { _Pragma("unroll") for (int m = 0; m < 4; ++m) _Pragma("unroll") for (int k = 0; k < 2; ++k) dst[m][k] = *(const PG8_LAS bf16x8*)(lds + PG8_SA(b, h) + aoff + m * 2048 + k * 1024); } while (0)
; #define PG8_LDB(dst, b, h) do { _Pragma("unroll") for (int n = 0; n < 2; ++n) _Pragma("unroll") for (int k = 0; k < 2; ++k) dst[n][k] = *(const PG8_LAS bf16x8*)(lds + PG8_SB(b, h) + boff + n * 2048 + k * 1024); } while (0)
; #define PG8_MMA(ai, bj, At, Bt) do { __builtin_amdgcn_s_setprio(1); _Pragma("unroll") for (int m = 0; m < 4; ++m) _Pragma("unroll") for (int n = 0; n < 2; ++n) _Pragma("unroll") for (int k = 0; k < 2; ++k) \
;         acc[ai][bj][m][n] = __builtin_amdgcn_mfma_f32_16x16x32_bf16(Bt[n][k], At[m][k], acc[ai][bj][m][n], 0, 0, 0); __builtin_amdgcn_s_setprio(0); } while (0)
; #define PG8_WAIT_V(n) asm volatile("s_waitcnt vmcnt(" #n ")" ::: "memory")
; template <class Epi, class Sched, bool ALIGN_EPI = false, bool SP2 = false>
; __device__ __forceinline__ void gemm_phase(PG8_LAS unsigned char* lds, const Gemm g, const Sched& S, const Epi& E) {
;     ...
;             PG8_LDB(B0, 0, 0); PG8_LDB(B1, 0, 1); PG8_SCHED; PG8_LDA(At, 0, 0); PG8_STAGE(PG8_SA(1, 1), a1 + hstep, voffA);
;             PG8_WAIT_V(8); PG8_WAIT_L(0); PG8_BAR; PG8_MMA(0, 0, At, B0); PG8_MMA(0, 1, At, B1); PG8_BAR; PG8_SCHED;
;             PG8_LDA(At, 0, 1); PG8_STAGE(PG8_SB(0, 0), b2, voffB); PG8_STAGE(PG8_SB(0, 1), b2 + hstep, voffB); PG8_STAGE(PG8_SA(0, 0), a2, voffA);
;             PG8_WAIT_V(8); PG8_WAIT_L(0); PG8_BAR; PG8_MMA(1, 0, At, B0); PG8_MMA(1, 1, At, B1); PG8_BAR; PG8_SCHED;
;             PG8_LDB(B0, 1, 0); PG8_LDB(B1, 1, 1); PG8_SCHED; PG8_LDA(At, 1, 0); PG8_STAGE(PG8_SA(0, 1), a2 + hstep, voffA);
;             PG8_WAIT_V(8); PG8_WAIT_L(0); PG8_BAR; PG8_MMA(0, 0, At, B0); PG8_MMA(0, 1, At, B1); PG8_BAR; PG8_SCHED;
;             PG8_LDA(At, 1, 1); PG8_STAGE(PG8_SB(1, 0), b3, voffB); PG8_STAGE(PG8_SB(1, 1), b3 + hstep, voffB); PG8_STAGE(PG8_SA(1, 0), a3, voffA);
;             PG8_WAIT_V(8); PG8_WAIT_L(0); PG8_BAR; PG8_MMA(1, 0, At, B0); PG8_MMA(1, 1, At, B1); PG8_BAR; PG8_SCHED;
.Lrsb_d:
	s_waitcnt lgkmcnt(0)
	s_barrier
	s_setprio 1
	s_waitcnt lgkmcnt(0)
	v_mfma_f32_16x16x32_bf16 v[124:127], v[144:147], v[202:205], v[124:127]
	v_mfma_f32_16x16x32_bf16 v[116:119], v[178:181], v[202:205], v[116:119]
	v_mfma_f32_16x16x32_bf16 v[108:111], v[144:147], v[210:213], v[108:111]
	v_mfma_f32_16x16x32_bf16 v[100:103], v[178:181], v[210:213], v[100:103]
	v_mfma_f32_16x16x32_bf16 v[92:95], v[144:147], v[218:221], v[92:95]
	v_mfma_f32_16x16x32_bf16 v[84:87], v[178:181], v[218:221], v[84:87]
	v_mfma_f32_16x16x32_bf16 v[76:79], v[144:147], v[226:229], v[76:79]
	v_mfma_f32_16x16x32_bf16 v[68:71], v[178:181], v[226:229], v[68:71]
	v_mfma_f32_16x16x32_bf16 v[124:127], v[170:173], v[206:209], v[124:127]
	v_mfma_f32_16x16x32_bf16 v[116:119], v[182:185], v[206:209], v[116:119]
	v_mfma_f32_16x16x32_bf16 v[108:111], v[170:173], v[214:217], v[108:111]
	v_mfma_f32_16x16x32_bf16 v[100:103], v[182:185], v[214:217], v[100:103]
	v_mfma_f32_16x16x32_bf16 v[92:95], v[170:173], v[222:225], v[92:95]
	v_mfma_f32_16x16x32_bf16 v[84:87], v[182:185], v[222:225], v[84:87]
	v_mfma_f32_16x16x32_bf16 v[76:79], v[170:173], v[232:235], v[76:79]
	v_mfma_f32_16x16x32_bf16 v[68:71], v[182:185], v[232:235], v[68:71]
	s_setprio 0
	s_setprio 1
	v_mfma_f32_16x16x32_bf16 v[120:123], v[186:189], v[202:205], v[120:123]
	v_mfma_f32_16x16x32_bf16 v[112:115], v[194:197], v[202:205], v[112:115]
	v_mfma_f32_16x16x32_bf16 v[104:107], v[186:189], v[210:213], v[104:107]
	v_mfma_f32_16x16x32_bf16 v[96:99], v[194:197], v[210:213], v[96:99]
	v_mfma_f32_16x16x32_bf16 v[88:91], v[186:189], v[218:221], v[88:91]
	v_mfma_f32_16x16x32_bf16 v[80:83], v[194:197], v[218:221], v[80:83]
	v_mfma_f32_16x16x32_bf16 v[72:75], v[186:189], v[226:229], v[72:75]
	v_mfma_f32_16x16x32_bf16 v[64:67], v[194:197], v[226:229], v[64:67]
	v_mfma_f32_16x16x32_bf16 v[120:123], v[190:193], v[206:209], v[120:123]
	v_mfma_f32_16x16x32_bf16 v[112:115], v[198:201], v[206:209], v[112:115]
	v_mfma_f32_16x16x32_bf16 v[104:107], v[190:193], v[214:217], v[104:107]
	v_mfma_f32_16x16x32_bf16 v[96:99], v[198:201], v[214:217], v[96:99]
	v_mfma_f32_16x16x32_bf16 v[88:91], v[190:193], v[222:225], v[88:91]
	v_mfma_f32_16x16x32_bf16 v[80:83], v[198:201], v[222:225], v[80:83]
	v_mfma_f32_16x16x32_bf16 v[72:75], v[190:193], v[232:235], v[72:75]
	v_mfma_f32_16x16x32_bf16 v[64:67], v[198:201], v[232:235], v[64:67]
	s_setprio 0
	s_barrier
	s_add_i32 s38, s59, s43
	v_lshl_add_u64 v[150:151], v[150:151], 0, s[12:13]
	s_mov_b32 m0, s38
	ds_read_b128 v[202:205], v169 offset:49152
	ds_read_b128 v[206:209], v169 offset:50176
	ds_read_b128 v[210:213], v169 offset:51200
	ds_read_b128 v[214:217], v169 offset:52224
	ds_read_b128 v[218:221], v169 offset:53248
	ds_read_b128 v[222:225], v169 offset:54272
	ds_read_b128 v[226:229], v169 offset:55296
	ds_read_b128 v[232:235], v169 offset:56320
	global_load_lds_dwordx4 v[150:151], off
	s_add_i32 m0, s38, 0x2000
	s_add_u32 s36, s36, 0x40080
	v_lshl_add_u64 v[150:151], v[154:155], 0, s[12:13]
	s_addc_u32 s37, s37, 0
	s_add_i32 s38, s60, s43
	global_load_lds_dwordx4 v[150:151], off
	s_mov_b32 m0, s38
	s_nop 0
	global_load_lds_dwordx4 v130, s[36:37]
	s_add_i32 m0, s38, 0x2000
	s_nop 0
	global_load_lds_dwordx4 v134, s[36:37]
	v_lshl_add_u64 v[150:151], v[158:159], 0, s[12:13]
	s_mov_b32 m0, s47
	s_nop 0
	global_load_lds_dwordx4 v[150:151], off
	v_lshl_add_u64 v[150:151], v[162:163], 0, s[12:13]
	s_mov_b32 m0, s48
	s_nop 0
	global_load_lds_dwordx4 v[150:151], off
	s_waitcnt vmcnt(8)
	s_waitcnt lgkmcnt(0)
	s_barrier
	s_setprio 1
	s_waitcnt lgkmcnt(0)
	v_mfma_f32_16x16x32_bf16 v[60:63], v[144:147], v[202:205], v[60:63]
	v_mfma_f32_16x16x32_bf16 v[52:55], v[178:181], v[202:205], v[52:55]
	v_mfma_f32_16x16x32_bf16 v[44:47], v[144:147], v[210:213], v[44:47]
	v_mfma_f32_16x16x32_bf16 v[36:39], v[178:181], v[210:213], v[36:39]
	v_mfma_f32_16x16x32_bf16 v[28:31], v[144:147], v[218:221], v[28:31]
	v_mfma_f32_16x16x32_bf16 v[20:23], v[178:181], v[218:221], v[20:23]
	v_mfma_f32_16x16x32_bf16 v[12:15], v[144:147], v[226:229], v[12:15]
	v_mfma_f32_16x16x32_bf16 v[4:7], v[178:181], v[226:229], v[4:7]
	v_mfma_f32_16x16x32_bf16 v[60:63], v[170:173], v[206:209], v[60:63]
	v_mfma_f32_16x16x32_bf16 v[52:55], v[182:185], v[206:209], v[52:55]
	v_mfma_f32_16x16x32_bf16 v[44:47], v[170:173], v[214:217], v[44:47]
	v_mfma_f32_16x16x32_bf16 v[36:39], v[182:185], v[214:217], v[36:39]
	v_mfma_f32_16x16x32_bf16 v[28:31], v[170:173], v[222:225], v[28:31]
	v_mfma_f32_16x16x32_bf16 v[20:23], v[182:185], v[222:225], v[20:23]
	v_mfma_f32_16x16x32_bf16 v[12:15], v[170:173], v[232:235], v[12:15]
	v_mfma_f32_16x16x32_bf16 v[4:7], v[182:185], v[232:235], v[4:7]
	s_setprio 0
	s_setprio 1
	v_mfma_f32_16x16x32_bf16 v[56:59], v[186:189], v[202:205], v[56:59]
	v_mfma_f32_16x16x32_bf16 v[48:51], v[194:197], v[202:205], v[48:51]
	v_mfma_f32_16x16x32_bf16 v[40:43], v[186:189], v[210:213], v[40:43]
	v_mfma_f32_16x16x32_bf16 v[32:35], v[194:197], v[210:213], v[32:35]
	v_mfma_f32_16x16x32_bf16 v[24:27], v[186:189], v[218:221], v[24:27]
	v_mfma_f32_16x16x32_bf16 v[16:19], v[194:197], v[218:221], v[16:19]
	v_mfma_f32_16x16x32_bf16 v[8:11], v[186:189], v[226:229], v[8:11]
	v_mfma_f32_16x16x32_bf16 v[0:3], v[194:197], v[226:229], v[0:3]
	v_mfma_f32_16x16x32_bf16 v[56:59], v[190:193], v[206:209], v[56:59]
	v_mfma_f32_16x16x32_bf16 v[48:51], v[198:201], v[206:209], v[48:51]
	v_mfma_f32_16x16x32_bf16 v[40:43], v[190:193], v[214:217], v[40:43]
	v_mfma_f32_16x16x32_bf16 v[32:35], v[198:201], v[214:217], v[32:35]
	v_mfma_f32_16x16x32_bf16 v[24:27], v[190:193], v[222:225], v[24:27]
	v_mfma_f32_16x16x32_bf16 v[16:19], v[198:201], v[222:225], v[16:19]
	v_mfma_f32_16x16x32_bf16 v[8:11], v[190:193], v[232:235], v[8:11]
	v_mfma_f32_16x16x32_bf16 v[0:3], v[198:201], v[232:235], v[0:3]
	s_setprio 0
	s_add_i32 s58, s58, 2
	s_add_u32 s34, s34, 0x100
	s_addc_u32 s35, s35, 0
	s_add_u32 s56, s56, 0x100
	s_addc_u32 s57, s57, 0
	s_cmp_gt_u32 s58, 13
	s_barrier
	s_cbranch_scc0 .LBB0_977
	s_and_b64 vcc, exec, s[16:17]
	s_cbranch_vccz .LBB0_980
	s_barrier

; #define PG8_STAGE(bufoff, gbase, voff) do { _Pragma("unroll") for (int _i = 0; _i < 2; ++_i) \
;         __builtin_amdgcn_global_load_lds((const unsigned*)((const char*)(gbase) + (voff)[_i]), (PG8_LAS unsigned*)(lds + (bufoff) + ldsw + _i * 8192), 16, 0, 0); } while (0)
; #define PG8_LDA(dst, b, h) do { _Pragma("unroll") for (int m = 0; m < 4; ++m) _Pragma("unroll") for (int k = 0; k < 2; ++k) dst[m][k] = *(const PG8_LAS bf16x8*)(lds + PG8_SA(b, h) + aoff + m * 2048 + k * 1024); } while (0)
; #define PG8_LDB(dst, b, h) do { _Pragma("unroll") for (int n = 0; n < 2; ++n) _Pragma("unroll") for (int k = 0; k < 2; ++k) dst[n][k] = *(const PG8_LAS bf16x8*)(lds + PG8_SB(b, h) + boff + n * 2048 + k * 1024); } while (0)
; #define PG8_WAIT_V(n) asm volatile("s_waitcnt vmcnt(" #n ")" ::: "memory")
; #define PG8_WAIT_L(n) asm volatile("s_waitcnt lgkmcnt(" #n ")" ::: "memory")
; #define PG8_BAR __builtin_amdgcn_s_barrier()
; #define PG8_SCHED __builtin_amdgcn_sched_barrier(0)
; template <class Epi, class Sched, bool ALIGN_EPI = false, bool SP2 = false>
; __device__ __forceinline__ void gemm_phase(PG8_LAS unsigned char* lds, const Gemm g, const Sched& S, const Epi& E) {
;     ...
;         const bool has_next = S.next(ui + 1, nxt);
;         const char* nA = has_next ? (const char*)g.A + (size_t)nxt.pm * tstep : cA; const char* nB = has_next ? (const char*)g.Bt + (size_t)nxt.pn * tstep : cB;
;         for (int t = 0; t < nt; t += 2) {
;             const bool last = (t == nt - 2);
;             const char* a1 = cA + (size_t)(t + 1) * kstep;
;             const char* a2 = last ? nA : cA + (size_t)(t + 2) * kstep; const char* b2 = last ? nB : cB + (size_t)(t + 2) * kstep;
;             const char* a3 = a2 + kstep; const char* b3 = b2 + kstep;
;             if (last && has_next) S.a_ready(nxt);
;             if constexpr (SP2) {
;             PG8_LDB(B0, 0, 0); PG8_LDB(B1, 0, 1); PG8_SCHED; PG8_LDA(At, 0, 0); PG8_STAGE(PG8_SA(1, 1), a1 + hstep, voffA);
;             PG8_WAIT_V(8); PG8_WAIT_L(0); PG8_BAR; PG8_MMA(0, 0, At, B0); PG8_MMA(0, 1, At, B1); PG8_BAR; PG8_SCHED;
;             PG8_LDA(At, 0, 1); PG8_STAGE(PG8_SB(0, 0), b2, voffB); PG8_STAGE(PG8_SB(0, 1), b2 + hstep, voffB); PG8_STAGE(PG8_SA(0, 0), a2, voffA);
;             PG8_WAIT_V(8); PG8_WAIT_L(0); PG8_BAR; PG8_MMA(1, 0, At, B0); PG8_MMA(1, 1, At, B1); PG8_BAR; PG8_SCHED;
.LBB0_1061:
	s_add_u32 s16, s16, 0xb0080
	s_addc_u32 s17, s17, 0
	s_add_u32 s41, s18, 0x100
	s_addc_u32 s42, s19, 0
	s_mov_b32 s43, -2
	ds_read_b128 v[128:131], v189
	ds_read_b128 v[132:135], v189 offset:1024
	ds_read_b128 v[136:139], v189 offset:2048
	ds_read_b128 v[140:143], v189 offset:3072
	ds_read_b128 v[144:147], v190
	ds_read_b128 v[148:151], v190 offset:1024
	ds_read_b128 v[152:155], v190 offset:2048
	ds_read_b128 v[156:159], v190 offset:3072
	s_add_u32 s18, s16, 0xfff50080
	s_addc_u32 s19, s17, -1
	s_cmp_eq_u32 s43, 40
	s_cselect_b32 s21, s13, s19
	s_cselect_b32 s20, s12, s18
	s_cselect_b32 s19, s15, s42
	s_cselect_b32 s18, s14, s41
	s_add_i32 m0, s26, 0xc000
	ds_read_b128 v[174:177], v191
	ds_read_b128 v[178:181], v191 offset:1024
	ds_read_b128 v[182:185], v191 offset:2048
	ds_read_b128 v[192:195], v191 offset:3072
	ds_read_b128 v[196:199], v191 offset:4096
	ds_read_b128 v[200:203], v191 offset:5120
	ds_read_b128 v[204:207], v191 offset:6144
	ds_read_b128 v[208:211], v191 offset:7168
	global_load_lds_dwordx4 v168, s[16:17]
	s_add_i32 m0, s26, 0xe000
	s_nop 0
	global_load_lds_dwordx4 v170, s[16:17]
	s_waitcnt vmcnt(8)
	s_waitcnt lgkmcnt(0)
	s_barrier
	s_setprio 1
	s_waitcnt lgkmcnt(0)
	v_mfma_f32_16x16x32_bf16 v[124:127], v[128:131], v[174:177], 0
	v_mfma_f32_16x16x32_bf16 v[120:123], v[136:139], v[174:177], 0
	v_mfma_f32_16x16x32_bf16 v[116:119], v[128:131], v[182:185], 0
	v_mfma_f32_16x16x32_bf16 v[104:107], v[136:139], v[182:185], 0
	v_mfma_f32_16x16x32_bf16 v[96:99], v[128:131], v[196:199], 0
	v_mfma_f32_16x16x32_bf16 v[88:91], v[136:139], v[196:199], 0
	v_mfma_f32_16x16x32_bf16 v[80:83], v[128:131], v[204:207], 0
	v_mfma_f32_16x16x32_bf16 v[72:75], v[136:139], v[204:207], 0
	v_mfma_f32_16x16x32_bf16 v[124:127], v[132:135], v[178:181], v[124:127]
	v_mfma_f32_16x16x32_bf16 v[120:123], v[140:143], v[178:181], v[120:123]
	v_mfma_f32_16x16x32_bf16 v[116:119], v[132:135], v[192:195], v[116:119]
	v_mfma_f32_16x16x32_bf16 v[104:107], v[140:143], v[192:195], v[104:107]
	v_mfma_f32_16x16x32_bf16 v[96:99], v[132:135], v[200:203], v[96:99]
	v_mfma_f32_16x16x32_bf16 v[88:91], v[140:143], v[200:203], v[88:91]
	v_mfma_f32_16x16x32_bf16 v[80:83], v[132:135], v[208:211], v[80:83]
	v_mfma_f32_16x16x32_bf16 v[72:75], v[140:143], v[208:211], v[72:75]
	s_setprio 0
	s_setprio 1
	v_mfma_f32_16x16x32_bf16 v[112:115], v[144:147], v[174:177], 0
	v_mfma_f32_16x16x32_bf16 v[108:111], v[152:155], v[174:177], 0
	v_mfma_f32_16x16x32_bf16 v[100:103], v[144:147], v[182:185], 0
	v_mfma_f32_16x16x32_bf16 v[92:95], v[152:155], v[182:185], 0
	v_mfma_f32_16x16x32_bf16 v[84:87], v[144:147], v[196:199], 0
	v_mfma_f32_16x16x32_bf16 v[76:79], v[152:155], v[196:199], 0
	v_mfma_f32_16x16x32_bf16 v[68:71], v[144:147], v[204:207], 0
	v_mfma_f32_16x16x32_bf16 v[64:67], v[152:155], v[204:207], 0
	v_mfma_f32_16x16x32_bf16 v[112:115], v[148:151], v[178:181], v[112:115]
	v_mfma_f32_16x16x32_bf16 v[108:111], v[156:159], v[178:181], v[108:111]
	v_mfma_f32_16x16x32_bf16 v[100:103], v[148:151], v[192:195], v[100:103]
	v_mfma_f32_16x16x32_bf16 v[92:95], v[156:159], v[192:195], v[92:95]
	v_mfma_f32_16x16x32_bf16 v[84:87], v[148:151], v[200:203], v[84:87]
	v_mfma_f32_16x16x32_bf16 v[76:79], v[156:159], v[200:203], v[76:79]
	v_mfma_f32_16x16x32_bf16 v[68:71], v[148:151], v[208:211], v[68:71]
	v_mfma_f32_16x16x32_bf16 v[64:67], v[156:159], v[208:211], v[64:67]
	s_setprio 0
	s_barrier
	s_add_i32 s44, s35, s25
	v_lshl_add_u64 v[212:213], s[18:19], 0, v[162:163]
	s_mov_b32 m0, s44
	ds_read_b128 v[174:177], v191 offset:16384
	ds_read_b128 v[178:181], v191 offset:17408
	ds_read_b128 v[182:185], v191 offset:18432
	ds_read_b128 v[192:195], v191 offset:19456
	ds_read_b128 v[196:199], v191 offset:20480
	ds_read_b128 v[200:203], v191 offset:21504
	ds_read_b128 v[204:207], v191 offset:22528
	ds_read_b128 v[208:211], v191 offset:23552
	global_load_lds_dwordx4 v[212:213], off
	s_add_i32 m0, s44, 0x2000
	s_add_u32 s44, s18, 0xb0000
	v_lshl_add_u64 v[214:215], s[18:19], 0, v[166:167]
	s_addc_u32 s45, s19, 0
	s_add_i32 s46, s36, s25
	global_load_lds_dwordx4 v[214:215], off
	s_mov_b32 m0, s46
	v_lshl_add_u64 v[218:219], s[20:21], 0, v[164:165]
	global_load_lds_dwordx4 v162, s[44:45]
	s_add_i32 m0, s46, 0x2000
	s_nop 0
	global_load_lds_dwordx4 v166, s[44:45]
	v_lshl_add_u64 v[216:217], s[20:21], 0, v[160:161]
	s_mov_b32 m0, s26
	s_nop 0
	global_load_lds_dwordx4 v[216:217], off
	s_mov_b32 m0, s27
	s_nop 0
	global_load_lds_dwordx4 v[218:219], off
	s_waitcnt vmcnt(8)
	s_waitcnt lgkmcnt(0)
	s_barrier
	s_setprio 1
	s_waitcnt lgkmcnt(0)
	v_mfma_f32_16x16x32_bf16 v[60:63], v[128:131], v[174:177], 0
	v_mfma_f32_16x16x32_bf16 v[56:59], v[136:139], v[174:177], 0
	v_mfma_f32_16x16x32_bf16 v[48:51], v[128:131], v[182:185], 0
	v_mfma_f32_16x16x32_bf16 v[40:43], v[136:139], v[182:185], 0
	v_mfma_f32_16x16x32_bf16 v[32:35], v[128:131], v[196:199], 0
	v_mfma_f32_16x16x32_bf16 v[24:27], v[136:139], v[196:199], 0
	v_mfma_f32_16x16x32_bf16 v[16:19], v[128:131], v[204:207], 0
	v_mfma_f32_16x16x32_bf16 v[8:11], v[136:139], v[204:207], 0
	v_mfma_f32_16x16x32_bf16 v[60:63], v[132:135], v[178:181], v[60:63]
	v_mfma_f32_16x16x32_bf16 v[56:59], v[140:143], v[178:181], v[56:59]
	v_mfma_f32_16x16x32_bf16 v[48:51], v[132:135], v[192:195], v[48:51]
	v_mfma_f32_16x16x32_bf16 v[40:43], v[140:143], v[192:195], v[40:43]
	v_mfma_f32_16x16x32_bf16 v[32:35], v[132:135], v[200:203], v[32:35]
	v_mfma_f32_16x16x32_bf16 v[24:27], v[140:143], v[200:203], v[24:27]
	v_mfma_f32_16x16x32_bf16 v[16:19], v[132:135], v[208:211], v[16:19]
	v_mfma_f32_16x16x32_bf16 v[8:11], v[140:143], v[208:211], v[8:11]
	s_setprio 0
	s_setprio 1
	v_mfma_f32_16x16x32_bf16 v[52:55], v[144:147], v[174:177], 0
	v_mfma_f32_16x16x32_bf16 v[44:47], v[152:155], v[174:177], 0
	v_mfma_f32_16x16x32_bf16 v[36:39], v[144:147], v[182:185], 0
	v_mfma_f32_16x16x32_bf16 v[28:31], v[152:155], v[182:185], 0
	v_mfma_f32_16x16x32_bf16 v[20:23], v[144:147], v[196:199], 0
	v_mfma_f32_16x16x32_bf16 v[12:15], v[152:155], v[196:199], 0
	v_mfma_f32_16x16x32_bf16 v[4:7], v[144:147], v[204:207], 0
	v_mfma_f32_16x16x32_bf16 v[0:3], v[152:155], v[204:207], 0
	v_mfma_f32_16x16x32_bf16 v[52:55], v[148:151], v[178:181], v[52:55]
	v_mfma_f32_16x16x32_bf16 v[44:47], v[156:159], v[178:181], v[44:47]
	v_mfma_f32_16x16x32_bf16 v[36:39], v[148:151], v[192:195], v[36:39]
	v_mfma_f32_16x16x32_bf16 v[28:31], v[156:159], v[192:195], v[28:31]
	v_mfma_f32_16x16x32_bf16 v[20:23], v[148:151], v[200:203], v[20:23]
	v_mfma_f32_16x16x32_bf16 v[12:15], v[156:159], v[200:203], v[12:15]
	v_mfma_f32_16x16x32_bf16 v[4:7], v[148:151], v[208:211], v[4:7]
	v_mfma_f32_16x16x32_bf16 v[0:3], v[156:159], v[208:211], v[0:3]
	s_setprio 0
	s_barrier
; #define PG8_STAGE(bufoff, gbase, voff) do { _Pragma("unroll") for (int _i = 0; _i < 2; ++_i) \
;         __builtin_amdgcn_global_load_lds((const unsigned*)((const char*)(gbase) + (voff)[_i]), (PG8_LAS unsigned*)(lds + (bufoff) + ldsw + _i * 8192), 16, 0, 0); } while (0)
; #define PG8_LDA(dst, b, h) do { _Pragma("unroll") for (int m = 0; m < 4; ++m) _Pragma("unroll") for (int k = 0; k < 2; ++k) dst[m][k] = *(const PG8_LAS bf16x8*)(lds + PG8_SA(b, h) + aoff + m * 2048 + k * 1024); } while (0)
; #define PG8_LDB(dst, b, h) do { _Pragma("unroll") for (int n = 0; n < 2; ++n) _Pragma("unroll") for (int k = 0; k < 2; ++k) dst[n][k] = *(const PG8_LAS bf16x8*)(lds + PG8_SB(b, h) + boff + n * 2048 + k * 1024); } while (0)
; #define PG8_MMA(ai, bj, At, Bt) do { __builtin_amdgcn_s_setprio(1); _Pragma("unroll") for (int m = 0; m < 4; ++m) _Pragma("unroll") for (int n = 0; n < 2; ++n) _Pragma("unroll") for (int k = 0; k < 2; ++k) \
;         acc[ai][bj][m][n] = __builtin_amdgcn_mfma_f32_16x16x32_bf16(Bt[n][k], At[m][k], acc[ai][bj][m][n], 0, 0, 0); __builtin_amdgcn_s_setprio(0); } while (0)
; #define PG8_WAIT_V(n) asm volatile("s_waitcnt vmcnt(" #n ")" ::: "memory")
; #define PG8_WAIT_L(n) asm volatile("s_waitcnt lgkmcnt(" #n ")" ::: "memory")
; #define PG8_BAR __builtin_amdgcn_s_barrier()
; #define PG8_SCHED __builtin_amdgcn_sched_barrier(0)
; template <class Epi, class Sched, bool ALIGN_EPI = false, bool SP2 = false>
; __device__ __forceinline__ void gemm_phase(PG8_LAS unsigned char* lds, const Gemm g, const Sched& S, const Epi& E) {
;     ...
;             PG8_LDB(B0, 1, 0); PG8_LDB(B1, 1, 1); PG8_SCHED; PG8_LDA(At, 1, 0); PG8_STAGE(PG8_SA(0, 1), a2 + hstep, voffA);
;             PG8_WAIT_V(8); PG8_WAIT_L(0); PG8_BAR; PG8_MMA(0, 0, At, B0); PG8_MMA(0, 1, At, B1); PG8_BAR; PG8_SCHED;
;             PG8_LDA(At, 1, 1); PG8_STAGE(PG8_SB(1, 0), b3, voffB); PG8_STAGE(PG8_SB(1, 1), b3 + hstep, voffB); PG8_STAGE(PG8_SA(1, 0), a3, voffA);
;             PG8_WAIT_V(8); PG8_WAIT_L(0); PG8_BAR; PG8_MMA(1, 0, At, B0); PG8_MMA(1, 1, At, B1); PG8_BAR; PG8_SCHED;
	s_add_i32 s44, 0, 0x18000
	s_add_i32 s45, 0, 0x1c000
	v_add_u32_e32 v140, s44, v187
	v_add_u32_e32 v156, s45, v187
	ds_read_b128 v[128:131], v140
	ds_read_b128 v[132:135], v140 offset:1024
	ds_read_b128 v[136:139], v140 offset:2048
	ds_read_b128 v[140:143], v140 offset:3072
	ds_read_b128 v[144:147], v156
	ds_read_b128 v[148:151], v156 offset:1024
	ds_read_b128 v[152:155], v156 offset:2048
	ds_read_b128 v[156:159], v156 offset:3072
	s_add_u32 s20, s20, 0xb0000
	s_addc_u32 s21, s21, 0
	s_mov_b32 m0, s28
	ds_read_b128 v[174:177], v191 offset:32768
	ds_read_b128 v[178:181], v191 offset:33792
	ds_read_b128 v[182:185], v191 offset:34816
	ds_read_b128 v[192:195], v191 offset:35840
	ds_read_b128 v[196:199], v191 offset:36864
	ds_read_b128 v[200:203], v191 offset:37888
	ds_read_b128 v[204:207], v191 offset:38912
	ds_read_b128 v[208:211], v191 offset:39936
	global_load_lds_dwordx4 v160, s[20:21]
	v_lshl_add_u64 v[220:221], s[20:21], 0, v[164:165]
	s_mov_b32 m0, s29
	s_nop 0
	global_load_lds_dwordx4 v[220:221], off
	s_waitcnt vmcnt(8)
	s_waitcnt lgkmcnt(0)
	s_barrier
	s_setprio 1
	s_waitcnt lgkmcnt(0)
	v_mfma_f32_16x16x32_bf16 v[124:127], v[128:131], v[174:177], v[124:127]
	v_mfma_f32_16x16x32_bf16 v[120:123], v[136:139], v[174:177], v[120:123]
	v_mfma_f32_16x16x32_bf16 v[116:119], v[128:131], v[182:185], v[116:119]
	v_mfma_f32_16x16x32_bf16 v[104:107], v[136:139], v[182:185], v[104:107]
	v_mfma_f32_16x16x32_bf16 v[96:99], v[128:131], v[196:199], v[96:99]
	v_mfma_f32_16x16x32_bf16 v[88:91], v[136:139], v[196:199], v[88:91]
	v_mfma_f32_16x16x32_bf16 v[80:83], v[128:131], v[204:207], v[80:83]
	v_mfma_f32_16x16x32_bf16 v[72:75], v[136:139], v[204:207], v[72:75]
	v_mfma_f32_16x16x32_bf16 v[124:127], v[132:135], v[178:181], v[124:127]
	v_mfma_f32_16x16x32_bf16 v[120:123], v[140:143], v[178:181], v[120:123]
	v_mfma_f32_16x16x32_bf16 v[116:119], v[132:135], v[192:195], v[116:119]
	v_mfma_f32_16x16x32_bf16 v[104:107], v[140:143], v[192:195], v[104:107]
	v_mfma_f32_16x16x32_bf16 v[96:99], v[132:135], v[200:203], v[96:99]
	v_mfma_f32_16x16x32_bf16 v[88:91], v[140:143], v[200:203], v[88:91]
	v_mfma_f32_16x16x32_bf16 v[80:83], v[132:135], v[208:211], v[80:83]
	v_mfma_f32_16x16x32_bf16 v[72:75], v[140:143], v[208:211], v[72:75]
	s_setprio 0
	s_setprio 1
	v_mfma_f32_16x16x32_bf16 v[112:115], v[144:147], v[174:177], v[112:115]
	v_mfma_f32_16x16x32_bf16 v[108:111], v[152:155], v[174:177], v[108:111]
	v_mfma_f32_16x16x32_bf16 v[100:103], v[144:147], v[182:185], v[100:103]
	v_mfma_f32_16x16x32_bf16 v[92:95], v[152:155], v[182:185], v[92:95]
	v_mfma_f32_16x16x32_bf16 v[84:87], v[144:147], v[196:199], v[84:87]
	v_mfma_f32_16x16x32_bf16 v[76:79], v[152:155], v[196:199], v[76:79]
	v_mfma_f32_16x16x32_bf16 v[68:71], v[144:147], v[204:207], v[68:71]
	v_mfma_f32_16x16x32_bf16 v[64:67], v[152:155], v[204:207], v[64:67]
	v_mfma_f32_16x16x32_bf16 v[112:115], v[148:151], v[178:181], v[112:115]
	v_mfma_f32_16x16x32_bf16 v[108:111], v[156:159], v[178:181], v[108:111]
	v_mfma_f32_16x16x32_bf16 v[100:103], v[148:151], v[192:195], v[100:103]
	v_mfma_f32_16x16x32_bf16 v[92:95], v[156:159], v[192:195], v[92:95]
	v_mfma_f32_16x16x32_bf16 v[84:87], v[148:151], v[200:203], v[84:87]
	v_mfma_f32_16x16x32_bf16 v[76:79], v[156:159], v[200:203], v[76:79]
	v_mfma_f32_16x16x32_bf16 v[68:71], v[148:151], v[208:211], v[68:71]
	v_mfma_f32_16x16x32_bf16 v[64:67], v[156:159], v[208:211], v[64:67]
	s_setprio 0
	s_barrier
	s_add_i32 s20, s44, s25
	v_lshl_add_u64 v[212:213], v[212:213], 0, s[8:9]
	s_mov_b32 m0, s20
	ds_read_b128 v[174:177], v191 offset:49152
	ds_read_b128 v[178:181], v191 offset:50176
	ds_read_b128 v[182:185], v191 offset:51200
	ds_read_b128 v[192:195], v191 offset:52224
	ds_read_b128 v[196:199], v191 offset:53248
	ds_read_b128 v[200:203], v191 offset:54272
	ds_read_b128 v[204:207], v191 offset:55296
	ds_read_b128 v[208:211], v191 offset:56320
	global_load_lds_dwordx4 v[212:213], off
	s_add_i32 m0, s20, 0x2000
	s_add_u32 s18, s18, 0xb0080
	v_lshl_add_u64 v[212:213], v[214:215], 0, s[8:9]
	s_addc_u32 s19, s19, 0
	s_add_i32 s20, s45, s25
	global_load_lds_dwordx4 v[212:213], off
	s_mov_b32 m0, s20
	s_nop 0
	global_load_lds_dwordx4 v162, s[18:19]
	s_add_i32 m0, s20, 0x2000
	s_nop 0
	global_load_lds_dwordx4 v166, s[18:19]
	v_lshl_add_u64 v[212:213], v[216:217], 0, s[8:9]
	s_mov_b32 m0, s33
	s_nop 0
	global_load_lds_dwordx4 v[212:213], off
	v_lshl_add_u64 v[212:213], v[218:219], 0, s[8:9]
	s_mov_b32 m0, s34
	s_nop 0
	global_load_lds_dwordx4 v[212:213], off
	s_waitcnt vmcnt(8)
	s_waitcnt lgkmcnt(0)
	s_barrier
	s_setprio 1
	s_waitcnt lgkmcnt(0)
	v_mfma_f32_16x16x32_bf16 v[60:63], v[128:131], v[174:177], v[60:63]
	v_mfma_f32_16x16x32_bf16 v[56:59], v[136:139], v[174:177], v[56:59]
	v_mfma_f32_16x16x32_bf16 v[48:51], v[128:131], v[182:185], v[48:51]
	v_mfma_f32_16x16x32_bf16 v[40:43], v[136:139], v[182:185], v[40:43]
	v_mfma_f32_16x16x32_bf16 v[32:35], v[128:131], v[196:199], v[32:35]
	v_mfma_f32_16x16x32_bf16 v[24:27], v[136:139], v[196:199], v[24:27]
	v_mfma_f32_16x16x32_bf16 v[16:19], v[128:131], v[204:207], v[16:19]
	v_mfma_f32_16x16x32_bf16 v[8:11], v[136:139], v[204:207], v[8:11]
	v_mfma_f32_16x16x32_bf16 v[60:63], v[132:135], v[178:181], v[60:63]
	v_mfma_f32_16x16x32_bf16 v[56:59], v[140:143], v[178:181], v[56:59]
	v_mfma_f32_16x16x32_bf16 v[48:51], v[132:135], v[192:195], v[48:51]
	v_mfma_f32_16x16x32_bf16 v[40:43], v[140:143], v[192:195], v[40:43]
	v_mfma_f32_16x16x32_bf16 v[32:35], v[132:135], v[200:203], v[32:35]
	v_mfma_f32_16x16x32_bf16 v[24:27], v[140:143], v[200:203], v[24:27]
	v_mfma_f32_16x16x32_bf16 v[16:19], v[132:135], v[208:211], v[16:19]
	v_mfma_f32_16x16x32_bf16 v[8:11], v[140:143], v[208:211], v[8:11]
	s_setprio 0
	s_setprio 1
	v_mfma_f32_16x16x32_bf16 v[52:55], v[144:147], v[174:177], v[52:55]
	v_mfma_f32_16x16x32_bf16 v[44:47], v[152:155], v[174:177], v[44:47]
	v_mfma_f32_16x16x32_bf16 v[36:39], v[144:147], v[182:185], v[36:39]
	v_mfma_f32_16x16x32_bf16 v[28:31], v[152:155], v[182:185], v[28:31]
	v_mfma_f32_16x16x32_bf16 v[20:23], v[144:147], v[196:199], v[20:23]
	v_mfma_f32_16x16x32_bf16 v[12:15], v[152:155], v[196:199], v[12:15]
	v_mfma_f32_16x16x32_bf16 v[4:7], v[144:147], v[204:207], v[4:7]
	v_mfma_f32_16x16x32_bf16 v[0:3], v[152:155], v[204:207], v[0:3]
	v_mfma_f32_16x16x32_bf16 v[52:55], v[148:151], v[178:181], v[52:55]
	v_mfma_f32_16x16x32_bf16 v[44:47], v[156:159], v[178:181], v[44:47]
	v_mfma_f32_16x16x32_bf16 v[36:39], v[148:151], v[192:195], v[36:39]
	v_mfma_f32_16x16x32_bf16 v[28:31], v[156:159], v[192:195], v[28:31]
	v_mfma_f32_16x16x32_bf16 v[20:23], v[148:151], v[200:203], v[20:23]
	v_mfma_f32_16x16x32_bf16 v[12:15], v[156:159], v[200:203], v[12:15]
	v_mfma_f32_16x16x32_bf16 v[4:7], v[148:151], v[208:211], v[4:7]
	v_mfma_f32_16x16x32_bf16 v[0:3], v[156:159], v[208:211], v[0:3]
	s_setprio 0
	s_add_i32 s43, s43, 2
	s_add_u32 s16, s16, 0x100
	s_addc_u32 s17, s17, 0
	s_add_u32 s41, s41, 0x100
	s_addc_u32 s42, s42, 0
	s_cmp_gt_u32 s43, 41
	s_barrier
; #define PG8_STAGE(bufoff, gbase, voff) do { _Pragma("unroll") for (int _i = 0; _i < 2; ++_i) \
;         __builtin_amdgcn_global_load_lds((const unsigned*)((const char*)(gbase) + (voff)[_i]), (PG8_LAS unsigned*)(lds + (bufoff) + ldsw + _i * 8192), 16, 0, 0); } while (0)
; #define PG8_LDA(dst, b, h) do { _Pragma("unroll") for (int m = 0; m < 4; ++m) _Pragma("unroll") for (int k = 0; k < 2; ++k) dst[m][k] = *(const PG8_LAS bf16x8*)(lds + PG8_SA(b, h) + aoff + m * 2048 + k * 1024); } while (0)
; #define PG8_LDB(dst, b, h) do { _Pragma("unroll") for (int n = 0; n < 2; ++n) _Pragma("unroll") for (int k = 0; k < 2; ++k) dst[n][k] = *(const PG8_LAS bf16x8*)(lds + PG8_SB(b, h) + boff + n * 2048 + k * 1024); } while (0)
; #define PG8_MMA(ai, bj, At, Bt) do { __builtin_amdgcn_s_setprio(1); _Pragma("unroll") for (int m = 0; m < 4; ++m) _Pragma("unroll") for (int n = 0; n < 2; ++n) _Pragma("unroll") for (int k = 0; k < 2; ++k) \
;         acc[ai][bj][m][n] = __builtin_amdgcn_mfma_f32_16x16x32_bf16(Bt[n][k], At[m][k], acc[ai][bj][m][n], 0, 0, 0); __builtin_amdgcn_s_setprio(0); } while (0)
; #define PG8_WAIT_V(n) asm volatile("s_waitcnt vmcnt(" #n ")" ::: "memory")
; #define PG8_WAIT_L(n) asm volatile("s_waitcnt lgkmcnt(" #n ")" ::: "memory")
; #define PG8_BAR __builtin_amdgcn_s_barrier()
; #define PG8_SCHED __builtin_amdgcn_sched_barrier(0)
; template <class Epi, class Sched, bool ALIGN_EPI = false, bool SP2 = false>
; __device__ __forceinline__ void gemm_phase(PG8_LAS unsigned char* lds, const Gemm g, const Sched& S, const Epi& E) {
;     ...
;             PG8_LDB(B0, 0, 0); PG8_LDB(B1, 0, 1); PG8_SCHED; PG8_LDA(At, 0, 0); PG8_STAGE(PG8_SA(1, 1), a1 + hstep, voffA);
;             PG8_WAIT_V(8); PG8_WAIT_L(0); PG8_BAR; PG8_MMA(0, 0, At, B0); PG8_MMA(0, 1, At, B1); PG8_BAR; PG8_SCHED;
;             PG8_LDA(At, 0, 1); PG8_STAGE(PG8_SB(0, 0), b2, voffB); PG8_STAGE(PG8_SB(0, 1), b2 + hstep, voffB); PG8_STAGE(PG8_SA(0, 0), a2, voffA);
;             PG8_WAIT_V(8); PG8_WAIT_L(0); PG8_BAR; PG8_MMA(1, 0, At, B0); PG8_MMA(1, 1, At, B1); PG8_BAR; PG8_SCHED;
.LBB0_1062:
	ds_read_b128 v[128:131], v189
	ds_read_b128 v[132:135], v189 offset:1024
	ds_read_b128 v[136:139], v189 offset:2048
	ds_read_b128 v[140:143], v189 offset:3072
	ds_read_b128 v[144:147], v190
	ds_read_b128 v[148:151], v190 offset:1024
	ds_read_b128 v[152:155], v190 offset:2048
	ds_read_b128 v[156:159], v190 offset:3072
	s_add_u32 s18, s16, 0xfff50080
	s_addc_u32 s19, s17, -1
	s_cmp_eq_u32 s43, 40
	s_cselect_b32 s21, s13, s19
	s_cselect_b32 s20, s12, s18
	s_cselect_b32 s19, s15, s42
	s_cselect_b32 s18, s14, s41
	s_add_i32 m0, s26, 0xc000
	ds_read_b128 v[174:177], v191
	ds_read_b128 v[178:181], v191 offset:1024
	ds_read_b128 v[182:185], v191 offset:2048
	ds_read_b128 v[192:195], v191 offset:3072
	ds_read_b128 v[196:199], v191 offset:4096
	ds_read_b128 v[200:203], v191 offset:5120
	ds_read_b128 v[204:207], v191 offset:6144
	ds_read_b128 v[208:211], v191 offset:7168
	global_load_lds_dwordx4 v168, s[16:17]
	s_add_i32 m0, s26, 0xe000
	s_nop 0
	global_load_lds_dwordx4 v170, s[16:17]
	s_waitcnt vmcnt(8)
	s_waitcnt lgkmcnt(0)
	s_barrier
	s_setprio 1
	s_waitcnt lgkmcnt(0)
	v_mfma_f32_16x16x32_bf16 v[124:127], v[128:131], v[174:177], v[124:127]
	v_mfma_f32_16x16x32_bf16 v[120:123], v[136:139], v[174:177], v[120:123]
	v_mfma_f32_16x16x32_bf16 v[116:119], v[128:131], v[182:185], v[116:119]
	v_mfma_f32_16x16x32_bf16 v[104:107], v[136:139], v[182:185], v[104:107]
	v_mfma_f32_16x16x32_bf16 v[96:99], v[128:131], v[196:199], v[96:99]
	v_mfma_f32_16x16x32_bf16 v[88:91], v[136:139], v[196:199], v[88:91]
	v_mfma_f32_16x16x32_bf16 v[80:83], v[128:131], v[204:207], v[80:83]
	v_mfma_f32_16x16x32_bf16 v[72:75], v[136:139], v[204:207], v[72:75]
	v_mfma_f32_16x16x32_bf16 v[124:127], v[132:135], v[178:181], v[124:127]
	v_mfma_f32_16x16x32_bf16 v[120:123], v[140:143], v[178:181], v[120:123]
	v_mfma_f32_16x16x32_bf16 v[116:119], v[132:135], v[192:195], v[116:119]
	v_mfma_f32_16x16x32_bf16 v[104:107], v[140:143], v[192:195], v[104:107]
	v_mfma_f32_16x16x32_bf16 v[96:99], v[132:135], v[200:203], v[96:99]
	v_mfma_f32_16x16x32_bf16 v[88:91], v[140:143], v[200:203], v[88:91]
	v_mfma_f32_16x16x32_bf16 v[80:83], v[132:135], v[208:211], v[80:83]
	v_mfma_f32_16x16x32_bf16 v[72:75], v[140:143], v[208:211], v[72:75]
	s_setprio 0
	s_setprio 1
	v_mfma_f32_16x16x32_bf16 v[112:115], v[144:147], v[174:177], v[112:115]
	v_mfma_f32_16x16x32_bf16 v[108:111], v[152:155], v[174:177], v[108:111]
	v_mfma_f32_16x16x32_bf16 v[100:103], v[144:147], v[182:185], v[100:103]
	v_mfma_f32_16x16x32_bf16 v[92:95], v[152:155], v[182:185], v[92:95]
	v_mfma_f32_16x16x32_bf16 v[84:87], v[144:147], v[196:199], v[84:87]
	v_mfma_f32_16x16x32_bf16 v[76:79], v[152:155], v[196:199], v[76:79]
	v_mfma_f32_16x16x32_bf16 v[68:71], v[144:147], v[204:207], v[68:71]
	v_mfma_f32_16x16x32_bf16 v[64:67], v[152:155], v[204:207], v[64:67]
	v_mfma_f32_16x16x32_bf16 v[112:115], v[148:151], v[178:181], v[112:115]
	v_mfma_f32_16x16x32_bf16 v[108:111], v[156:159], v[178:181], v[108:111]
	v_mfma_f32_16x16x32_bf16 v[100:103], v[148:151], v[192:195], v[100:103]
	v_mfma_f32_16x16x32_bf16 v[92:95], v[156:159], v[192:195], v[92:95]
	v_mfma_f32_16x16x32_bf16 v[84:87], v[148:151], v[200:203], v[84:87]
	v_mfma_f32_16x16x32_bf16 v[76:79], v[156:159], v[200:203], v[76:79]
	v_mfma_f32_16x16x32_bf16 v[68:71], v[148:151], v[208:211], v[68:71]
	v_mfma_f32_16x16x32_bf16 v[64:67], v[156:159], v[208:211], v[64:67]
	s_setprio 0
	s_barrier
	s_add_i32 s44, s35, s25
	v_lshl_add_u64 v[212:213], s[18:19], 0, v[162:163]
	s_mov_b32 m0, s44
	ds_read_b128 v[174:177], v191 offset:16384
	ds_read_b128 v[178:181], v191 offset:17408
	ds_read_b128 v[182:185], v191 offset:18432
	ds_read_b128 v[192:195], v191 offset:19456
	ds_read_b128 v[196:199], v191 offset:20480
	ds_read_b128 v[200:203], v191 offset:21504
	ds_read_b128 v[204:207], v191 offset:22528
	ds_read_b128 v[208:211], v191 offset:23552
	global_load_lds_dwordx4 v[212:213], off
	s_add_i32 m0, s44, 0x2000
	s_add_u32 s44, s18, 0xb0000
	v_lshl_add_u64 v[214:215], s[18:19], 0, v[166:167]
	s_addc_u32 s45, s19, 0
	s_add_i32 s46, s36, s25
	global_load_lds_dwordx4 v[214:215], off
	s_mov_b32 m0, s46
	v_lshl_add_u64 v[218:219], s[20:21], 0, v[164:165]
	global_load_lds_dwordx4 v162, s[44:45]
	s_add_i32 m0, s46, 0x2000
	s_nop 0
	global_load_lds_dwordx4 v166, s[44:45]
	v_lshl_add_u64 v[216:217], s[20:21], 0, v[160:161]
	s_mov_b32 m0, s26
	s_nop 0
	global_load_lds_dwordx4 v[216:217], off
	s_mov_b32 m0, s27
	s_nop 0
	global_load_lds_dwordx4 v[218:219], off
	s_waitcnt vmcnt(8)
	s_waitcnt lgkmcnt(0)
	s_barrier
; #define PG8_STAGE(bufoff, gbase, voff) do { _Pragma("unroll") for (int _i = 0; _i < 2; ++_i) \
;         __builtin_amdgcn_global_load_lds((const unsigned*)((const char*)(gbase) + (voff)[_i]), (PG8_LAS unsigned*)(lds + (bufoff) + ldsw + _i * 8192), 16, 0, 0); } while (0)
; #define PG8_LDA(dst, b, h) do { _Pragma("unroll") for (int m = 0; m < 4; ++m) _Pragma("unroll") for (int k = 0; k < 2; ++k) dst[m][k] = *(const PG8_LAS bf16x8*)(lds + PG8_SA(b, h) + aoff + m * 2048 + k * 1024); } while (0)
; #define PG8_LDB(dst, b, h) do { _Pragma("unroll") for (int n = 0; n < 2; ++n) _Pragma("unroll") for (int k = 0; k < 2; ++k) dst[n][k] = *(const PG8_LAS bf16x8*)(lds + PG8_SB(b, h) + boff + n * 2048 + k * 1024); } while (0)
; #define PG8_MMA(ai, bj, At, Bt) do { __builtin_amdgcn_s_setprio(1); _Pragma("unroll") for (int m = 0; m < 4; ++m) _Pragma("unroll") for (int n = 0; n < 2; ++n) _Pragma("unroll") for (int k = 0; k < 2; ++k) \
;         acc[ai][bj][m][n] = __builtin_amdgcn_mfma_f32_16x16x32_bf16(Bt[n][k], At[m][k], acc[ai][bj][m][n], 0, 0, 0); __builtin_amdgcn_s_setprio(0); } while (0)
; #define PG8_WAIT_V(n) asm volatile("s_waitcnt vmcnt(" #n ")" ::: "memory")
; #define PG8_WAIT_L(n) asm volatile("s_waitcnt lgkmcnt(" #n ")" ::: "memory")
; #define PG8_BAR __builtin_amdgcn_s_barrier()
; #define PG8_SCHED __builtin_amdgcn_sched_barrier(0)
; template <class Epi, class Sched, bool ALIGN_EPI = false, bool SP2 = false>
; __device__ __forceinline__ void gemm_phase(PG8_LAS unsigned char* lds, const Gemm g, const Sched& S, const Epi& E) {
;     ...
;             PG8_WAIT_V(8); PG8_WAIT_L(0); PG8_BAR; PG8_MMA(1, 0, At, B0); PG8_MMA(1, 1, At, B1); PG8_BAR; PG8_SCHED;
;             PG8_LDB(B0, 1, 0); PG8_LDB(B1, 1, 1); PG8_SCHED; PG8_LDA(At, 1, 0); PG8_STAGE(PG8_SA(0, 1), a2 + hstep, voffA);
;             PG8_WAIT_V(8); PG8_WAIT_L(0); PG8_BAR; PG8_MMA(0, 0, At, B0); PG8_MMA(0, 1, At, B1); PG8_BAR; PG8_SCHED;
	s_setprio 1
	s_waitcnt lgkmcnt(0)
	v_mfma_f32_16x16x32_bf16 v[60:63], v[128:131], v[174:177], v[60:63]
	v_mfma_f32_16x16x32_bf16 v[56:59], v[136:139], v[174:177], v[56:59]
	v_mfma_f32_16x16x32_bf16 v[48:51], v[128:131], v[182:185], v[48:51]
	v_mfma_f32_16x16x32_bf16 v[40:43], v[136:139], v[182:185], v[40:43]
	v_mfma_f32_16x16x32_bf16 v[32:35], v[128:131], v[196:199], v[32:35]
	v_mfma_f32_16x16x32_bf16 v[24:27], v[136:139], v[196:199], v[24:27]
	v_mfma_f32_16x16x32_bf16 v[16:19], v[128:131], v[204:207], v[16:19]
	v_mfma_f32_16x16x32_bf16 v[8:11], v[136:139], v[204:207], v[8:11]
	v_mfma_f32_16x16x32_bf16 v[60:63], v[132:135], v[178:181], v[60:63]
	v_mfma_f32_16x16x32_bf16 v[56:59], v[140:143], v[178:181], v[56:59]
	v_mfma_f32_16x16x32_bf16 v[48:51], v[132:135], v[192:195], v[48:51]
	v_mfma_f32_16x16x32_bf16 v[40:43], v[140:143], v[192:195], v[40:43]
	v_mfma_f32_16x16x32_bf16 v[32:35], v[132:135], v[200:203], v[32:35]
	v_mfma_f32_16x16x32_bf16 v[24:27], v[140:143], v[200:203], v[24:27]
	v_mfma_f32_16x16x32_bf16 v[16:19], v[132:135], v[208:211], v[16:19]
	v_mfma_f32_16x16x32_bf16 v[8:11], v[140:143], v[208:211], v[8:11]
	s_setprio 0
	s_setprio 1
	v_mfma_f32_16x16x32_bf16 v[52:55], v[144:147], v[174:177], v[52:55]
	v_mfma_f32_16x16x32_bf16 v[44:47], v[152:155], v[174:177], v[44:47]
	v_mfma_f32_16x16x32_bf16 v[36:39], v[144:147], v[182:185], v[36:39]
	v_mfma_f32_16x16x32_bf16 v[28:31], v[152:155], v[182:185], v[28:31]
	v_mfma_f32_16x16x32_bf16 v[20:23], v[144:147], v[196:199], v[20:23]
	v_mfma_f32_16x16x32_bf16 v[12:15], v[152:155], v[196:199], v[12:15]
	v_mfma_f32_16x16x32_bf16 v[4:7], v[144:147], v[204:207], v[4:7]
	v_mfma_f32_16x16x32_bf16 v[0:3], v[152:155], v[204:207], v[0:3]
	v_mfma_f32_16x16x32_bf16 v[52:55], v[148:151], v[178:181], v[52:55]
	v_mfma_f32_16x16x32_bf16 v[44:47], v[156:159], v[178:181], v[44:47]
	v_mfma_f32_16x16x32_bf16 v[36:39], v[148:151], v[192:195], v[36:39]
	v_mfma_f32_16x16x32_bf16 v[28:31], v[156:159], v[192:195], v[28:31]
	v_mfma_f32_16x16x32_bf16 v[20:23], v[148:151], v[200:203], v[20:23]
	v_mfma_f32_16x16x32_bf16 v[12:15], v[156:159], v[200:203], v[12:15]
	v_mfma_f32_16x16x32_bf16 v[4:7], v[148:151], v[208:211], v[4:7]
	v_mfma_f32_16x16x32_bf16 v[0:3], v[156:159], v[208:211], v[0:3]
	s_setprio 0
	s_barrier
	s_add_i32 s44, 0, 0x18000
	s_add_i32 s45, 0, 0x1c000
	v_add_u32_e32 v140, s44, v187
	v_add_u32_e32 v156, s45, v187
	ds_read_b128 v[128:131], v140
	ds_read_b128 v[132:135], v140 offset:1024
	ds_read_b128 v[136:139], v140 offset:2048
	ds_read_b128 v[140:143], v140 offset:3072
	ds_read_b128 v[144:147], v156
	ds_read_b128 v[148:151], v156 offset:1024
	ds_read_b128 v[152:155], v156 offset:2048
	ds_read_b128 v[156:159], v156 offset:3072
	s_add_u32 s20, s20, 0xb0000
	s_addc_u32 s21, s21, 0
	s_mov_b32 m0, s28
	ds_read_b128 v[174:177], v191 offset:32768
	ds_read_b128 v[178:181], v191 offset:33792
	ds_read_b128 v[182:185], v191 offset:34816
	ds_read_b128 v[192:195], v191 offset:35840
	ds_read_b128 v[196:199], v191 offset:36864
	ds_read_b128 v[200:203], v191 offset:37888
	ds_read_b128 v[204:207], v191 offset:38912
	ds_read_b128 v[208:211], v191 offset:39936
	global_load_lds_dwordx4 v160, s[20:21]
	v_lshl_add_u64 v[220:221], s[20:21], 0, v[164:165]
	s_mov_b32 m0, s29
	s_nop 0
	global_load_lds_dwordx4 v[220:221], off
	s_waitcnt vmcnt(8)
	s_waitcnt lgkmcnt(0)
	s_barrier
	s_setprio 1
	s_waitcnt lgkmcnt(0)
	v_mfma_f32_16x16x32_bf16 v[124:127], v[128:131], v[174:177], v[124:127]
	v_mfma_f32_16x16x32_bf16 v[120:123], v[136:139], v[174:177], v[120:123]
	v_mfma_f32_16x16x32_bf16 v[116:119], v[128:131], v[182:185], v[116:119]
	v_mfma_f32_16x16x32_bf16 v[104:107], v[136:139], v[182:185], v[104:107]
	v_mfma_f32_16x16x32_bf16 v[96:99], v[128:131], v[196:199], v[96:99]
	v_mfma_f32_16x16x32_bf16 v[88:91], v[136:139], v[196:199], v[88:91]
	v_mfma_f32_16x16x32_bf16 v[80:83], v[128:131], v[204:207], v[80:83]
	v_mfma_f32_16x16x32_bf16 v[72:75], v[136:139], v[204:207], v[72:75]
	v_mfma_f32_16x16x32_bf16 v[124:127], v[132:135], v[178:181], v[124:127]
	v_mfma_f32_16x16x32_bf16 v[120:123], v[140:143], v[178:181], v[120:123]
	v_mfma_f32_16x16x32_bf16 v[116:119], v[132:135], v[192:195], v[116:119]
	v_mfma_f32_16x16x32_bf16 v[104:107], v[140:143], v[192:195], v[104:107]
	v_mfma_f32_16x16x32_bf16 v[96:99], v[132:135], v[200:203], v[96:99]
	v_mfma_f32_16x16x32_bf16 v[88:91], v[140:143], v[200:203], v[88:91]
	v_mfma_f32_16x16x32_bf16 v[80:83], v[132:135], v[208:211], v[80:83]
	v_mfma_f32_16x16x32_bf16 v[72:75], v[140:143], v[208:211], v[72:75]
	s_setprio 0
	s_setprio 1
	v_mfma_f32_16x16x32_bf16 v[112:115], v[144:147], v[174:177], v[112:115]
	v_mfma_f32_16x16x32_bf16 v[108:111], v[152:155], v[174:177], v[108:111]
	v_mfma_f32_16x16x32_bf16 v[100:103], v[144:147], v[182:185], v[100:103]
	v_mfma_f32_16x16x32_bf16 v[92:95], v[152:155], v[182:185], v[92:95]
	v_mfma_f32_16x16x32_bf16 v[84:87], v[144:147], v[196:199], v[84:87]
	v_mfma_f32_16x16x32_bf16 v[76:79], v[152:155], v[196:199], v[76:79]
	v_mfma_f32_16x16x32_bf16 v[68:71], v[144:147], v[204:207], v[68:71]
	v_mfma_f32_16x16x32_bf16 v[64:67], v[152:155], v[204:207], v[64:67]
	v_mfma_f32_16x16x32_bf16 v[112:115], v[148:151], v[178:181], v[112:115]
	v_mfma_f32_16x16x32_bf16 v[108:111], v[156:159], v[178:181], v[108:111]
	v_mfma_f32_16x16x32_bf16 v[100:103], v[148:151], v[192:195], v[100:103]
	v_mfma_f32_16x16x32_bf16 v[92:95], v[156:159], v[192:195], v[92:95]
	v_mfma_f32_16x16x32_bf16 v[84:87], v[148:151], v[200:203], v[84:87]
	v_mfma_f32_16x16x32_bf16 v[76:79], v[156:159], v[200:203], v[76:79]
	v_mfma_f32_16x16x32_bf16 v[68:71], v[148:151], v[208:211], v[68:71]
	v_mfma_f32_16x16x32_bf16 v[64:67], v[156:159], v[208:211], v[64:67]
	s_setprio 0
	s_barrier
; #define PG8_STAGE(bufoff, gbase, voff) do { _Pragma("unroll") for (int _i = 0; _i < 2; ++_i) \
;         __builtin_amdgcn_global_load_lds((const unsigned*)((const char*)(gbase) + (voff)[_i]), (PG8_LAS unsigned*)(lds + (bufoff) + ldsw + _i * 8192), 16, 0, 0); } while (0)
; #define PG8_LDA(dst, b, h) do { _Pragma("unroll") for (int m = 0; m < 4; ++m) _Pragma("unroll") for (int k = 0; k < 2; ++k) dst[m][k] = *(const PG8_LAS bf16x8*)(lds + PG8_SA(b, h) + aoff + m * 2048 + k * 1024); } while (0)
; #define PG8_MMA(ai, bj, At, Bt) do { __builtin_amdgcn_s_setprio(1); _Pragma("unroll") for (int m = 0; m < 4; ++m) _Pragma("unroll") for (int n = 0; n < 2; ++n) _Pragma("unroll") for (int k = 0; k < 2; ++k) \
;         acc[ai][bj][m][n] = __builtin_amdgcn_mfma_f32_16x16x32_bf16(Bt[n][k], At[m][k], acc[ai][bj][m][n], 0, 0, 0); __builtin_amdgcn_s_setprio(0); } while (0)
; #define PG8_WAIT_V(n) asm volatile("s_waitcnt vmcnt(" #n ")" ::: "memory")
; #define PG8_WAIT_L(n) asm volatile("s_waitcnt lgkmcnt(" #n ")" ::: "memory")
; #define PG8_BAR __builtin_amdgcn_s_barrier()
; #define PG8_SCHED __builtin_amdgcn_sched_barrier(0)
; template <class Epi, class Sched, bool ALIGN_EPI = false, bool SP2 = false>
; __device__ __forceinline__ void gemm_phase(PG8_LAS unsigned char* lds, const Gemm g, const Sched& S, const Epi& E) {
;     ...
;         for (int t = 0; t < nt; t += 2) {
;     ...
;             PG8_LDA(At, 1, 1); PG8_STAGE(PG8_SB(1, 0), b3, voffB); PG8_STAGE(PG8_SB(1, 1), b3 + hstep, voffB); PG8_STAGE(PG8_SA(1, 0), a3, voffA);
;             PG8_WAIT_V(8); PG8_WAIT_L(0); PG8_BAR; PG8_MMA(1, 0, At, B0); PG8_MMA(1, 1, At, B1); PG8_BAR; PG8_SCHED;
	s_add_i32 s20, s44, s25
	v_lshl_add_u64 v[212:213], v[212:213], 0, s[8:9]
	s_mov_b32 m0, s20
	ds_read_b128 v[174:177], v191 offset:49152
	ds_read_b128 v[178:181], v191 offset:50176
	ds_read_b128 v[182:185], v191 offset:51200
	ds_read_b128 v[192:195], v191 offset:52224
	ds_read_b128 v[196:199], v191 offset:53248
	ds_read_b128 v[200:203], v191 offset:54272
	ds_read_b128 v[204:207], v191 offset:55296
	ds_read_b128 v[208:211], v191 offset:56320
	global_load_lds_dwordx4 v[212:213], off
	s_add_i32 m0, s20, 0x2000
	s_add_u32 s18, s18, 0xb0080
	v_lshl_add_u64 v[212:213], v[214:215], 0, s[8:9]
	s_addc_u32 s19, s19, 0
	s_add_i32 s20, s45, s25
	global_load_lds_dwordx4 v[212:213], off
	s_mov_b32 m0, s20
	s_nop 0
	global_load_lds_dwordx4 v162, s[18:19]
	s_add_i32 m0, s20, 0x2000
	s_nop 0
	global_load_lds_dwordx4 v166, s[18:19]
	v_lshl_add_u64 v[212:213], v[216:217], 0, s[8:9]
	s_mov_b32 m0, s33
	s_nop 0
	global_load_lds_dwordx4 v[212:213], off
	v_lshl_add_u64 v[212:213], v[218:219], 0, s[8:9]
	s_mov_b32 m0, s34
	s_nop 0
	global_load_lds_dwordx4 v[212:213], off
	s_waitcnt vmcnt(8)
	s_waitcnt lgkmcnt(0)
	s_barrier
	s_setprio 1
	s_waitcnt lgkmcnt(0)
	v_mfma_f32_16x16x32_bf16 v[60:63], v[128:131], v[174:177], v[60:63]
	v_mfma_f32_16x16x32_bf16 v[56:59], v[136:139], v[174:177], v[56:59]
	v_mfma_f32_16x16x32_bf16 v[48:51], v[128:131], v[182:185], v[48:51]
	v_mfma_f32_16x16x32_bf16 v[40:43], v[136:139], v[182:185], v[40:43]
	v_mfma_f32_16x16x32_bf16 v[32:35], v[128:131], v[196:199], v[32:35]
	v_mfma_f32_16x16x32_bf16 v[24:27], v[136:139], v[196:199], v[24:27]
	v_mfma_f32_16x16x32_bf16 v[16:19], v[128:131], v[204:207], v[16:19]
	v_mfma_f32_16x16x32_bf16 v[8:11], v[136:139], v[204:207], v[8:11]
	v_mfma_f32_16x16x32_bf16 v[60:63], v[132:135], v[178:181], v[60:63]
	v_mfma_f32_16x16x32_bf16 v[56:59], v[140:143], v[178:181], v[56:59]
	v_mfma_f32_16x16x32_bf16 v[48:51], v[132:135], v[192:195], v[48:51]
	v_mfma_f32_16x16x32_bf16 v[40:43], v[140:143], v[192:195], v[40:43]
	v_mfma_f32_16x16x32_bf16 v[32:35], v[132:135], v[200:203], v[32:35]
	v_mfma_f32_16x16x32_bf16 v[24:27], v[140:143], v[200:203], v[24:27]
	v_mfma_f32_16x16x32_bf16 v[16:19], v[132:135], v[208:211], v[16:19]
	v_mfma_f32_16x16x32_bf16 v[8:11], v[140:143], v[208:211], v[8:11]
	s_setprio 0
	s_setprio 1
	v_mfma_f32_16x16x32_bf16 v[52:55], v[144:147], v[174:177], v[52:55]
	v_mfma_f32_16x16x32_bf16 v[44:47], v[152:155], v[174:177], v[44:47]
	v_mfma_f32_16x16x32_bf16 v[36:39], v[144:147], v[182:185], v[36:39]
	v_mfma_f32_16x16x32_bf16 v[28:31], v[152:155], v[182:185], v[28:31]
	v_mfma_f32_16x16x32_bf16 v[20:23], v[144:147], v[196:199], v[20:23]
	v_mfma_f32_16x16x32_bf16 v[12:15], v[152:155], v[196:199], v[12:15]
	v_mfma_f32_16x16x32_bf16 v[4:7], v[144:147], v[204:207], v[4:7]
	v_mfma_f32_16x16x32_bf16 v[0:3], v[152:155], v[204:207], v[0:3]
	v_mfma_f32_16x16x32_bf16 v[52:55], v[148:151], v[178:181], v[52:55]
	v_mfma_f32_16x16x32_bf16 v[44:47], v[156:159], v[178:181], v[44:47]
	v_mfma_f32_16x16x32_bf16 v[36:39], v[148:151], v[192:195], v[36:39]
	v_mfma_f32_16x16x32_bf16 v[28:31], v[156:159], v[192:195], v[28:31]
	v_mfma_f32_16x16x32_bf16 v[20:23], v[148:151], v[200:203], v[20:23]
	v_mfma_f32_16x16x32_bf16 v[12:15], v[156:159], v[200:203], v[12:15]
	v_mfma_f32_16x16x32_bf16 v[4:7], v[148:151], v[208:211], v[4:7]
	v_mfma_f32_16x16x32_bf16 v[0:3], v[156:159], v[208:211], v[0:3]
	s_setprio 0
	s_add_i32 s43, s43, 2
	s_add_u32 s16, s16, 0x100
	s_addc_u32 s17, s17, 0
	s_add_u32 s41, s41, 0x100
	s_addc_u32 s42, s42, 0
	s_cmp_gt_u32 s43, 41
	s_barrier
	s_cbranch_scc0 .LBB0_1062
	s_and_b64 vcc, exec, s[10:11]
	s_cbranch_vccz .LBB0_1065
	s_barrier
